# balanced K-loops, deferred LDS-DMA pieces issued after the segment's ds_reads (in front of the segment's own first piece)
# baseline (speedup 1.0000x reference)
; #define PG8_STAGE(bufoff, gbase, voff) do { _Pragma("unroll") for (int _i = 0; _i < 2; ++_i) \
;         __builtin_amdgcn_global_load_lds((const unsigned*)((const char*)(gbase) + (voff)[_i]), (PG8_LAS unsigned*)(lds + (bufoff) + ldsw + _i * 8192), 16, 0, 0); } while (0)
; #define PG8_LDA(dst, b, h) do { _Pragma("unroll") for (int m = 0; m < 4; ++m) _Pragma("unroll") for (int k = 0; k < 2; ++k) dst[m][k] = *(const PG8_LAS bf16x8*)(lds + PG8_SA(b, h) + aoff + m * 2048 + k * 1024); } while (0)
; #define PG8_LDB(dst, b, h) do { _Pragma("unroll") for (int n = 0; n < 2; ++n) _Pragma("unroll") for (int k = 0; k < 2; ++k) dst[n][k] = *(const PG8_LAS bf16x8*)(lds + PG8_SB(b, h) + boff + n * 2048 + k * 1024); } while (0)
; #define PG8_WAIT_V(n) asm volatile("s_waitcnt vmcnt(" #n ")" ::: "memory")
; #define PG8_WAIT_L(n) asm volatile("s_waitcnt lgkmcnt(" #n ")" ::: "memory")
; #define PG8_BAR __builtin_amdgcn_s_barrier()
; #define PG8_SCHED __builtin_amdgcn_sched_barrier(0)
; template <class Epi, class Sched, bool ALIGN_EPI = false, bool SP2 = false, bool I8 = false>
; __device__ __forceinline__ void gemm_phase(PG8_LAS unsigned char* lds, const Gemm g, const Sched& S, const Epi& E) {
;     ...
;         const bool has_next = S.next(ui + 1, nxt);
;         const char* nA = has_next ? (const char*)g.A + (size_t)nxt.pm * tstep : cA; const char* nB = has_next ? (const char*)g.Bt + (size_t)nxt.pn * tstep : cB;
;         for (int t = 0; t < nt; t += 2) {
;             const bool last = (t == nt - 2);
;             const char* a1 = cA + (size_t)(t + 1) * kstep;
;             const char* a2 = last ? nA : cA + (size_t)(t + 2) * kstep; const char* b2 = last ? nB : cB + (size_t)(t + 2) * kstep;
;             const char* a3 = a2 + kstep; const char* b3 = b2 + kstep;
;             if (last && has_next) S.a_ready(nxt);
;             if constexpr (SP2) {
;             PG8_LDB(B0, 0, 0); PG8_LDB(B1, 0, 1); PG8_SCHED; PG8_LDA(At, 0, 0); PG8_STAGE(PG8_SA(1, 1), a1 + hstep, voffA);
;             PG8_WAIT_V(8); PG8_WAIT_L(0); PG8_BAR; PG8_MMA(0, 0, At, B0); PG8_MMA(0, 1, At, B1); PG8_BAR; PG8_SCHED;
;             PG8_LDA(At, 0, 1); PG8_STAGE(PG8_SB(0, 0), b2, voffB); PG8_STAGE(PG8_SB(0, 1), b2 + hstep, voffB); PG8_STAGE(PG8_SA(0, 0), a2, voffA);
;             PG8_WAIT_V(8); PG8_WAIT_L(0); PG8_BAR; PG8_MMA(1, 0, At, B0); PG8_MMA(1, 1, At, B1); PG8_BAR; PG8_SCHED;
.LBB0_207:
	s_ashr_i32 s19, s18, 31
	s_lshl_b64 s[22:23], s[18:19], 20
	s_add_u32 s22, s28, s22
	s_addc_u32 s23, s34, s23
	s_and_b64 s[24:25], s[6:7], exec
	s_cselect_b32 s19, s23, s27
	s_cselect_b32 s64, s22, s26
	s_ashr_i32 s17, s16, 31
	s_lshl_b64 s[24:25], s[16:17], 20
	s_add_u32 s24, s35, s24
	s_addc_u32 s25, s42, s25
	s_and_b64 s[40:41], s[6:7], exec
	s_cselect_b32 s17, s25, s37
	s_cselect_b32 s65, s24, s36
	s_add_u32 s26, s26, 0x80080
	s_addc_u32 s27, s27, 0
	s_add_u32 s72, s36, 0x100
	s_addc_u32 s73, s37, 0
	s_mov_b32 s76, -2
	s_add_u32 s36, s26, 0xfff80080
	s_addc_u32 s37, s27, -1
	s_add_i32 s50, 0, 0x10000
	s_cmp_eq_u32 s76, 28
	s_cselect_b32 s41, s19, s37
	s_cselect_b32 s40, s64, s36
	s_cselect_b32 s37, s17, s73
	s_cselect_b32 s36, s65, s72
	s_add_i32 s56, 0, 0x14000
	v_add_u32_e32 v136, s50, v175
	v_add_u32_e32 v172, s56, v175
	ds_read_b128 v[116:119], v136
	ds_read_b128 v[124:127], v136 offset:1024
	ds_read_b128 v[132:135], v136 offset:2048
	ds_read_b128 v[136:139], v136 offset:3072
	ds_read_b128 v[160:163], v172
	ds_read_b128 v[164:167], v172 offset:1024
	ds_read_b128 v[168:171], v172 offset:2048
	ds_read_b128 v[178:181], v172 offset:3072
	v_lshl_add_u64 v[172:173], s[26:27], 0, v[156:157]
	s_add_i32 m0, s44, 0xc000
	ds_read_b128 v[182:185], v177
	ds_read_b128 v[186:189], v177 offset:1024
	ds_read_b128 v[204:207], v177 offset:2048
	ds_read_b128 v[208:211], v177 offset:3072
	ds_read_b128 v[212:215], v177 offset:4096
	ds_read_b128 v[216:219], v177 offset:5120
	ds_read_b128 v[220:223], v177 offset:6144
	ds_read_b128 v[224:227], v177 offset:7168
	global_load_lds_dwordx4 v[172:173], off
	v_lshl_add_u64 v[172:173], s[26:27], 0, v[158:159]
	s_add_i32 m0, s44, 0xe000
	s_nop 0
	global_load_lds_dwordx4 v[172:173], off
	s_waitcnt vmcnt(8)
	s_waitcnt lgkmcnt(0)
	s_barrier
	s_setprio 1
	s_waitcnt lgkmcnt(0)
	v_mfma_i32_16x16x64_i8 v[144:147], v[116:119], v[182:185], 0
	v_mfma_i32_16x16x64_i8 v[144:147], v[124:127], v[186:189], v[144:147]
	v_mfma_i32_16x16x64_i8 v[112:115], v[124:127], v[208:211], 0
	v_mfma_i32_16x16x64_i8 v[112:115], v[116:119], v[204:207], v[112:115]
	v_mfma_i32_16x16x64_i8 v[96:99], v[116:119], v[212:215], 0
	v_mfma_i32_16x16x64_i8 v[96:99], v[124:127], v[216:219], v[96:99]
	v_mfma_i32_16x16x64_i8 v[80:83], v[124:127], v[224:227], 0
	v_mfma_i32_16x16x64_i8 v[80:83], v[116:119], v[220:223], v[80:83]
	v_mfma_i32_16x16x64_i8 v[76:79], v[132:135], v[220:223], 0
	v_mfma_i32_16x16x64_i8 v[76:79], v[136:139], v[224:227], v[76:79]
	v_mfma_i32_16x16x64_i8 v[92:95], v[136:139], v[216:219], 0
	v_mfma_i32_16x16x64_i8 v[92:95], v[132:135], v[212:215], v[92:95]
	v_mfma_i32_16x16x64_i8 v[108:111], v[132:135], v[204:207], 0
	v_mfma_i32_16x16x64_i8 v[108:111], v[136:139], v[208:211], v[108:111]
	v_mfma_i32_16x16x64_i8 v[140:143], v[136:139], v[186:189], 0
	v_mfma_i32_16x16x64_i8 v[140:143], v[132:135], v[182:185], v[140:143]
	v_mfma_i32_16x16x64_i8 v[128:131], v[160:163], v[182:185], 0
	v_mfma_i32_16x16x64_i8 v[128:131], v[164:167], v[186:189], v[128:131]
	v_mfma_i32_16x16x64_i8 v[104:107], v[164:167], v[208:211], 0
	v_mfma_i32_16x16x64_i8 v[104:107], v[160:163], v[204:207], v[104:107]
	v_mfma_i32_16x16x64_i8 v[88:91], v[160:163], v[212:215], 0
	v_mfma_i32_16x16x64_i8 v[88:91], v[164:167], v[216:219], v[88:91]
	v_mfma_i32_16x16x64_i8 v[72:75], v[164:167], v[224:227], 0
	v_mfma_i32_16x16x64_i8 v[72:75], v[160:163], v[220:223], v[72:75]
	v_mfma_i32_16x16x64_i8 v[68:71], v[168:171], v[220:223], 0
	v_mfma_i32_16x16x64_i8 v[68:71], v[178:181], v[224:227], v[68:71]
	v_mfma_i32_16x16x64_i8 v[84:87], v[178:181], v[216:219], 0
	v_mfma_i32_16x16x64_i8 v[84:87], v[168:171], v[212:215], v[84:87]
	v_mfma_i32_16x16x64_i8 v[100:103], v[168:171], v[204:207], 0
	v_mfma_i32_16x16x64_i8 v[100:103], v[178:181], v[208:211], v[100:103]
	v_mfma_i32_16x16x64_i8 v[120:123], v[178:181], v[186:189], 0
	v_mfma_i32_16x16x64_i8 v[120:123], v[168:171], v[182:185], v[120:123]
	s_setprio 0
	s_barrier
	s_add_i32 s50, s50, s43
	v_lshl_add_u64 v[172:173], s[36:37], 0, v[2:3]
	s_mov_b32 m0, s50
	ds_read_b128 v[182:185], v177 offset:16384
	ds_read_b128 v[186:189], v177 offset:17408
	ds_read_b128 v[204:207], v177 offset:18432
	ds_read_b128 v[208:211], v177 offset:19456
	ds_read_b128 v[212:215], v177 offset:20480
	ds_read_b128 v[216:219], v177 offset:21504
	ds_read_b128 v[220:223], v177 offset:22528
	ds_read_b128 v[224:227], v177 offset:23552
	global_load_lds_dwordx4 v[172:173], off
	s_add_i32 m0, s50, 0x2000
	s_add_u32 s50, s36, 0x80000
	v_lshl_add_u64 v[190:191], s[36:37], 0, v[148:149]
	s_addc_u32 s51, s37, 0
	s_add_i32 s56, s56, s43
	global_load_lds_dwordx4 v[190:191], off
	v_lshl_add_u64 v[228:229], s[50:51], 0, v[2:3]
	s_mov_b32 m0, s56
	v_lshl_add_u64 v[240:241], s[40:41], 0, v[150:151]
	global_load_lds_dwordx4 v[228:229], off
	v_lshl_add_u64 v[228:229], s[50:51], 0, v[148:149]
	s_add_i32 m0, s56, 0x2000
	s_nop 0
	global_load_lds_dwordx4 v[228:229], off
	v_lshl_add_u64 v[228:229], s[40:41], 0, v[152:153]
	s_waitcnt vmcnt(6)
	s_waitcnt lgkmcnt(0)
	s_barrier
; #define PG8_STAGE(bufoff, gbase, voff) do { _Pragma("unroll") for (int _i = 0; _i < 2; ++_i) \
;         __builtin_amdgcn_global_load_lds((const unsigned*)((const char*)(gbase) + (voff)[_i]), (PG8_LAS unsigned*)(lds + (bufoff) + ldsw + _i * 8192), 16, 0, 0); } while (0)
; #define PG8_LDA(dst, b, h) do { _Pragma("unroll") for (int m = 0; m < 4; ++m) _Pragma("unroll") for (int k = 0; k < 2; ++k) dst[m][k] = *(const PG8_LAS bf16x8*)(lds + PG8_SA(b, h) + aoff + m * 2048 + k * 1024); } while (0)
; #define PG8_LDB(dst, b, h) do { _Pragma("unroll") for (int n = 0; n < 2; ++n) _Pragma("unroll") for (int k = 0; k < 2; ++k) dst[n][k] = *(const PG8_LAS bf16x8*)(lds + PG8_SB(b, h) + boff + n * 2048 + k * 1024); } while (0)
; #define PG8_WAIT_V(n) asm volatile("s_waitcnt vmcnt(" #n ")" ::: "memory")
; #define PG8_WAIT_L(n) asm volatile("s_waitcnt lgkmcnt(" #n ")" ::: "memory")
; #define PG8_BAR __builtin_amdgcn_s_barrier()
; #define PG8_SCHED __builtin_amdgcn_sched_barrier(0)
; template <class Epi, class Sched, bool ALIGN_EPI = false, bool SP2 = false, bool I8 = false>
; __device__ __forceinline__ void gemm_phase(PG8_LAS unsigned char* lds, const Gemm g, const Sched& S, const Epi& E) {
;     ...
;             PG8_WAIT_V(8); PG8_WAIT_L(0); PG8_BAR; PG8_MMA(0, 0, At, B0); PG8_MMA(0, 1, At, B1); PG8_BAR; PG8_SCHED;
;             PG8_LDA(At, 0, 1); PG8_STAGE(PG8_SB(0, 0), b2, voffB); PG8_STAGE(PG8_SB(0, 1), b2 + hstep, voffB); PG8_STAGE(PG8_SA(0, 0), a2, voffA);
;             PG8_WAIT_V(8); PG8_WAIT_L(0); PG8_BAR; PG8_MMA(1, 0, At, B0); PG8_MMA(1, 1, At, B1); PG8_BAR; PG8_SCHED;
;             PG8_LDB(B0, 1, 0); PG8_LDB(B1, 1, 1); PG8_SCHED; PG8_LDA(At, 1, 0); PG8_STAGE(PG8_SA(0, 1), a2 + hstep, voffA);
;             PG8_WAIT_V(8); PG8_WAIT_L(0); PG8_BAR; PG8_MMA(0, 0, At, B0); PG8_MMA(0, 1, At, B1); PG8_BAR; PG8_SCHED;
;             PG8_LDA(At, 1, 1); PG8_STAGE(PG8_SB(1, 0), b3, voffB); PG8_STAGE(PG8_SB(1, 1), b3 + hstep, voffB); PG8_STAGE(PG8_SA(1, 0), a3, voffA);
;             PG8_WAIT_V(8); PG8_WAIT_L(0); PG8_BAR; PG8_MMA(1, 0, At, B0); PG8_MMA(1, 1, At, B1); PG8_BAR; PG8_SCHED;
	s_setprio 1
	s_waitcnt lgkmcnt(0)
	v_mfma_i32_16x16x64_i8 v[64:67], v[116:119], v[182:185], 0
	v_mfma_i32_16x16x64_i8 v[64:67], v[124:127], v[186:189], v[64:67]
	v_mfma_i32_16x16x64_i8 v[48:51], v[124:127], v[208:211], 0
	v_mfma_i32_16x16x64_i8 v[48:51], v[116:119], v[204:207], v[48:51]
	v_mfma_i32_16x16x64_i8 v[32:35], v[116:119], v[212:215], 0
	v_mfma_i32_16x16x64_i8 v[32:35], v[124:127], v[216:219], v[32:35]
	v_mfma_i32_16x16x64_i8 v[16:19], v[124:127], v[224:227], 0
	v_mfma_i32_16x16x64_i8 v[16:19], v[116:119], v[220:223], v[16:19]
	v_mfma_i32_16x16x64_i8 v[12:15], v[132:135], v[220:223], 0
	v_mfma_i32_16x16x64_i8 v[12:15], v[136:139], v[224:227], v[12:15]
	v_mfma_i32_16x16x64_i8 v[28:31], v[136:139], v[216:219], 0
	v_mfma_i32_16x16x64_i8 v[28:31], v[132:135], v[212:215], v[28:31]
	v_mfma_i32_16x16x64_i8 v[44:47], v[132:135], v[204:207], 0
	v_mfma_i32_16x16x64_i8 v[44:47], v[136:139], v[208:211], v[44:47]
	v_mfma_i32_16x16x64_i8 v[60:63], v[136:139], v[186:189], 0
	v_mfma_i32_16x16x64_i8 v[60:63], v[132:135], v[182:185], v[60:63]
	v_mfma_i32_16x16x64_i8 v[56:59], v[160:163], v[182:185], 0
	v_mfma_i32_16x16x64_i8 v[56:59], v[164:167], v[186:189], v[56:59]
	v_mfma_i32_16x16x64_i8 v[40:43], v[164:167], v[208:211], 0
	v_mfma_i32_16x16x64_i8 v[40:43], v[160:163], v[204:207], v[40:43]
	v_mfma_i32_16x16x64_i8 v[24:27], v[160:163], v[212:215], 0
	v_mfma_i32_16x16x64_i8 v[24:27], v[164:167], v[216:219], v[24:27]
	v_mfma_i32_16x16x64_i8 v[8:11], v[164:167], v[224:227], 0
	v_mfma_i32_16x16x64_i8 v[8:11], v[160:163], v[220:223], v[8:11]
	v_mfma_i32_16x16x64_i8 v[4:7], v[168:171], v[220:223], 0
	v_mfma_i32_16x16x64_i8 v[4:7], v[178:181], v[224:227], v[4:7]
	v_mfma_i32_16x16x64_i8 v[20:23], v[178:181], v[216:219], 0
	v_mfma_i32_16x16x64_i8 v[20:23], v[168:171], v[212:215], v[20:23]
	v_mfma_i32_16x16x64_i8 v[36:39], v[168:171], v[204:207], 0
	v_mfma_i32_16x16x64_i8 v[36:39], v[178:181], v[208:211], v[36:39]
	v_mfma_i32_16x16x64_i8 v[52:55], v[178:181], v[186:189], 0
	v_mfma_i32_16x16x64_i8 v[52:55], v[168:171], v[182:185], v[52:55]
	s_setprio 0
	s_barrier
	s_add_i32 s50, 0, 0x18000
	s_add_i32 s51, 0, 0x1c000
	v_add_u32_e32 v136, s50, v175
	v_add_u32_e32 v178, s51, v175
	ds_read_b128 v[116:119], v136
	ds_read_b128 v[124:127], v136 offset:1024
	ds_read_b128 v[132:135], v136 offset:2048
	ds_read_b128 v[136:139], v136 offset:3072
	ds_read_b128 v[160:163], v178
	ds_read_b128 v[164:167], v178 offset:1024
	ds_read_b128 v[168:171], v178 offset:2048
	ds_read_b128 v[178:181], v178 offset:3072
	s_add_u32 s40, s40, 0x80000
	s_addc_u32 s41, s41, 0
	s_mov_b32 m0, s46
	v_lshl_add_u64 v[242:243], s[40:41], 0, v[152:153]
	ds_read_b128 v[182:185], v177 offset:32768
	ds_read_b128 v[186:189], v177 offset:33792
	ds_read_b128 v[204:207], v177 offset:34816
	ds_read_b128 v[208:211], v177 offset:35840
	ds_read_b128 v[212:215], v177 offset:36864
	ds_read_b128 v[216:219], v177 offset:37888
	ds_read_b128 v[220:223], v177 offset:38912
	ds_read_b128 v[224:227], v177 offset:39936
	s_mov_b32 m0, s44
	s_nop 0
	global_load_lds_dwordx4 v[228:229], off
	s_mov_b32 m0, s45
	s_nop 0
	global_load_lds_dwordx4 v[240:241], off
	s_mov_b32 m0, s46
	s_nop 0
	global_load_lds_dwordx4 v[242:243], off
	v_lshl_add_u64 v[242:243], s[40:41], 0, v[150:151]
	s_mov_b32 m0, s47
	s_nop 0
	global_load_lds_dwordx4 v[242:243], off
	s_waitcnt vmcnt(8)
	s_waitcnt lgkmcnt(0)
	s_barrier
	s_setprio 1
	s_waitcnt lgkmcnt(0)
	v_mfma_i32_16x16x64_i8 v[144:147], v[116:119], v[182:185], v[144:147]
	v_mfma_i32_16x16x64_i8 v[144:147], v[124:127], v[186:189], v[144:147]
	v_mfma_i32_16x16x64_i8 v[112:115], v[124:127], v[208:211], v[112:115]
	v_mfma_i32_16x16x64_i8 v[112:115], v[116:119], v[204:207], v[112:115]
	v_mfma_i32_16x16x64_i8 v[96:99], v[116:119], v[212:215], v[96:99]
	v_mfma_i32_16x16x64_i8 v[96:99], v[124:127], v[216:219], v[96:99]
	v_mfma_i32_16x16x64_i8 v[80:83], v[124:127], v[224:227], v[80:83]
	v_mfma_i32_16x16x64_i8 v[80:83], v[116:119], v[220:223], v[80:83]
	v_mfma_i32_16x16x64_i8 v[76:79], v[132:135], v[220:223], v[76:79]
	v_mfma_i32_16x16x64_i8 v[76:79], v[136:139], v[224:227], v[76:79]
	v_mfma_i32_16x16x64_i8 v[92:95], v[136:139], v[216:219], v[92:95]
	v_mfma_i32_16x16x64_i8 v[92:95], v[132:135], v[212:215], v[92:95]
	v_mfma_i32_16x16x64_i8 v[108:111], v[132:135], v[204:207], v[108:111]
	v_mfma_i32_16x16x64_i8 v[108:111], v[136:139], v[208:211], v[108:111]
	v_mfma_i32_16x16x64_i8 v[140:143], v[136:139], v[186:189], v[140:143]
	v_mfma_i32_16x16x64_i8 v[140:143], v[132:135], v[182:185], v[140:143]
	v_mfma_i32_16x16x64_i8 v[128:131], v[160:163], v[182:185], v[128:131]
	v_mfma_i32_16x16x64_i8 v[128:131], v[164:167], v[186:189], v[128:131]
	v_mfma_i32_16x16x64_i8 v[104:107], v[164:167], v[208:211], v[104:107]
	v_mfma_i32_16x16x64_i8 v[104:107], v[160:163], v[204:207], v[104:107]
	v_mfma_i32_16x16x64_i8 v[88:91], v[160:163], v[212:215], v[88:91]
	v_mfma_i32_16x16x64_i8 v[88:91], v[164:167], v[216:219], v[88:91]
	v_mfma_i32_16x16x64_i8 v[72:75], v[164:167], v[224:227], v[72:75]
	v_mfma_i32_16x16x64_i8 v[72:75], v[160:163], v[220:223], v[72:75]
	v_mfma_i32_16x16x64_i8 v[68:71], v[168:171], v[220:223], v[68:71]
	v_mfma_i32_16x16x64_i8 v[68:71], v[178:181], v[224:227], v[68:71]
	v_mfma_i32_16x16x64_i8 v[84:87], v[178:181], v[216:219], v[84:87]
	v_mfma_i32_16x16x64_i8 v[84:87], v[168:171], v[212:215], v[84:87]
	v_mfma_i32_16x16x64_i8 v[100:103], v[168:171], v[204:207], v[100:103]
	v_mfma_i32_16x16x64_i8 v[100:103], v[178:181], v[208:211], v[100:103]
	v_mfma_i32_16x16x64_i8 v[120:123], v[178:181], v[186:189], v[120:123]
	v_mfma_i32_16x16x64_i8 v[120:123], v[168:171], v[182:185], v[120:123]
	s_setprio 0
	s_barrier
	s_add_i32 s40, s50, s43
	v_lshl_add_u64 v[172:173], v[172:173], 0, s[84:85]
	s_mov_b32 m0, s40
	ds_read_b128 v[182:185], v177 offset:49152
	ds_read_b128 v[186:189], v177 offset:50176
	ds_read_b128 v[204:207], v177 offset:51200
	ds_read_b128 v[208:211], v177 offset:52224
	ds_read_b128 v[212:215], v177 offset:53248
	ds_read_b128 v[216:219], v177 offset:54272
	ds_read_b128 v[220:223], v177 offset:55296
	ds_read_b128 v[224:227], v177 offset:56320
	global_load_lds_dwordx4 v[172:173], off
	s_add_i32 m0, s40, 0x2000
	s_add_u32 s36, s36, 0x80080
	v_lshl_add_u64 v[172:173], v[190:191], 0, s[84:85]
	s_addc_u32 s37, s37, 0
	s_add_i32 s40, s51, s43
	global_load_lds_dwordx4 v[172:173], off
	v_lshl_add_u64 v[172:173], s[36:37], 0, v[2:3]
	s_mov_b32 m0, s40
	s_nop 0
	global_load_lds_dwordx4 v[172:173], off
	v_lshl_add_u64 v[172:173], s[36:37], 0, v[148:149]
	s_add_i32 m0, s40, 0x2000
	s_nop 0
	global_load_lds_dwordx4 v[172:173], off
	s_cmp_eq_u32 s76, 28
	s_cbranch_scc0 .Ldefer_208_peel
	v_lshl_add_u64 v[172:173], v[228:229], 0, s[84:85]
	s_mov_b32 m0, s52
	s_nop 0
	global_load_lds_dwordx4 v[172:173], off
	v_lshl_add_u64 v[172:173], v[240:241], 0, s[84:85]
	s_mov_b32 m0, s53
	s_nop 0
	global_load_lds_dwordx4 v[172:173], off

; #define PG8_STAGE(bufoff, gbase, voff) do { _Pragma("unroll") for (int _i = 0; _i < 2; ++_i) \
;         __builtin_amdgcn_global_load_lds((const unsigned*)((const char*)(gbase) + (voff)[_i]), (PG8_LAS unsigned*)(lds + (bufoff) + ldsw + _i * 8192), 16, 0, 0); } while (0)
; #define PG8_LDA(dst, b, h) do { _Pragma("unroll") for (int m = 0; m < 4; ++m) _Pragma("unroll") for (int k = 0; k < 2; ++k) dst[m][k] = *(const PG8_LAS bf16x8*)(lds + PG8_SA(b, h) + aoff + m * 2048 + k * 1024); } while (0)
; #define PG8_LDB(dst, b, h) do { _Pragma("unroll") for (int n = 0; n < 2; ++n) _Pragma("unroll") for (int k = 0; k < 2; ++k) dst[n][k] = *(const PG8_LAS bf16x8*)(lds + PG8_SB(b, h) + boff + n * 2048 + k * 1024); } while (0)
; #define PG8_WAIT_V(n) asm volatile("s_waitcnt vmcnt(" #n ")" ::: "memory")
; #define PG8_WAIT_L(n) asm volatile("s_waitcnt lgkmcnt(" #n ")" ::: "memory")
; #define PG8_BAR __builtin_amdgcn_s_barrier()
; #define PG8_SCHED __builtin_amdgcn_sched_barrier(0)
; template <class Epi, class Sched, bool ALIGN_EPI = false, bool SP2 = false, bool I8 = false>
; __device__ __forceinline__ void gemm_phase(PG8_LAS unsigned char* lds, const Gemm g, const Sched& S, const Epi& E) {
;     ...
;             if constexpr (SP2) {
;             PG8_LDB(B0, 0, 0); PG8_LDB(B1, 0, 1); PG8_SCHED; PG8_LDA(At, 0, 0); PG8_STAGE(PG8_SA(1, 1), a1 + hstep, voffA);
;             PG8_WAIT_V(8); PG8_WAIT_L(0); PG8_BAR; PG8_MMA(0, 0, At, B0); PG8_MMA(0, 1, At, B1); PG8_BAR; PG8_SCHED;
;             PG8_LDA(At, 0, 1); PG8_STAGE(PG8_SB(0, 0), b2, voffB); PG8_STAGE(PG8_SB(0, 1), b2 + hstep, voffB); PG8_STAGE(PG8_SA(0, 0), a2, voffA);
;             PG8_WAIT_V(8); PG8_WAIT_L(0); PG8_BAR; PG8_MMA(1, 0, At, B0); PG8_MMA(1, 1, At, B1); PG8_BAR; PG8_SCHED;
.LBB0_208:
	s_add_u32 s36, s26, 0xfff80080
	s_addc_u32 s37, s27, -1
	s_add_i32 s50, 0, 0x10000
	s_cmp_eq_u32 s76, 28
	s_cselect_b32 s41, s19, s37
	s_cselect_b32 s40, s64, s36
	s_cselect_b32 s37, s17, s73
	s_cselect_b32 s36, s65, s72
	s_add_i32 s56, 0, 0x14000
	v_add_u32_e32 v136, s50, v175
	v_add_u32_e32 v172, s56, v175
	ds_read_b128 v[116:119], v136
	ds_read_b128 v[124:127], v136 offset:1024
	ds_read_b128 v[132:135], v136 offset:2048
	ds_read_b128 v[136:139], v136 offset:3072
	ds_read_b128 v[160:163], v172
	ds_read_b128 v[164:167], v172 offset:1024
	ds_read_b128 v[168:171], v172 offset:2048
	ds_read_b128 v[178:181], v172 offset:3072
	ds_read_b128 v[182:185], v177
	ds_read_b128 v[186:189], v177 offset:1024
	ds_read_b128 v[204:207], v177 offset:2048
	ds_read_b128 v[208:211], v177 offset:3072
	ds_read_b128 v[212:215], v177 offset:4096
	ds_read_b128 v[216:219], v177 offset:5120
	ds_read_b128 v[220:223], v177 offset:6144
	ds_read_b128 v[224:227], v177 offset:7168
	v_lshl_add_u64 v[172:173], v[228:229], 0, s[84:85]
	s_mov_b32 m0, s52
	s_nop 0
	global_load_lds_dwordx4 v[172:173], off
	v_lshl_add_u64 v[172:173], v[240:241], 0, s[84:85]
	s_mov_b32 m0, s53
	s_nop 0
	global_load_lds_dwordx4 v[172:173], off
	v_lshl_add_u64 v[172:173], s[26:27], 0, v[156:157]
	s_add_i32 m0, s44, 0xc000
	s_nop 0
	global_load_lds_dwordx4 v[172:173], off
	v_lshl_add_u64 v[172:173], s[26:27], 0, v[158:159]
	s_add_i32 m0, s44, 0xe000
	s_nop 0
	global_load_lds_dwordx4 v[172:173], off
	s_waitcnt vmcnt(8)
	s_waitcnt lgkmcnt(0)
	s_barrier
	s_setprio 1
	s_waitcnt lgkmcnt(0)
	v_mfma_i32_16x16x64_i8 v[144:147], v[116:119], v[182:185], v[144:147]
	v_mfma_i32_16x16x64_i8 v[144:147], v[124:127], v[186:189], v[144:147]
	v_mfma_i32_16x16x64_i8 v[112:115], v[124:127], v[208:211], v[112:115]
	v_mfma_i32_16x16x64_i8 v[112:115], v[116:119], v[204:207], v[112:115]
	v_mfma_i32_16x16x64_i8 v[96:99], v[116:119], v[212:215], v[96:99]
	v_mfma_i32_16x16x64_i8 v[96:99], v[124:127], v[216:219], v[96:99]
	v_mfma_i32_16x16x64_i8 v[80:83], v[124:127], v[224:227], v[80:83]
	v_mfma_i32_16x16x64_i8 v[80:83], v[116:119], v[220:223], v[80:83]
	v_mfma_i32_16x16x64_i8 v[76:79], v[132:135], v[220:223], v[76:79]
	v_mfma_i32_16x16x64_i8 v[76:79], v[136:139], v[224:227], v[76:79]
	v_mfma_i32_16x16x64_i8 v[92:95], v[136:139], v[216:219], v[92:95]
	v_mfma_i32_16x16x64_i8 v[92:95], v[132:135], v[212:215], v[92:95]
	v_mfma_i32_16x16x64_i8 v[108:111], v[132:135], v[204:207], v[108:111]
	v_mfma_i32_16x16x64_i8 v[108:111], v[136:139], v[208:211], v[108:111]
	v_mfma_i32_16x16x64_i8 v[140:143], v[136:139], v[186:189], v[140:143]
	v_mfma_i32_16x16x64_i8 v[140:143], v[132:135], v[182:185], v[140:143]
	v_mfma_i32_16x16x64_i8 v[128:131], v[160:163], v[182:185], v[128:131]
	v_mfma_i32_16x16x64_i8 v[128:131], v[164:167], v[186:189], v[128:131]
	v_mfma_i32_16x16x64_i8 v[104:107], v[164:167], v[208:211], v[104:107]
	v_mfma_i32_16x16x64_i8 v[104:107], v[160:163], v[204:207], v[104:107]
	v_mfma_i32_16x16x64_i8 v[88:91], v[160:163], v[212:215], v[88:91]
	v_mfma_i32_16x16x64_i8 v[88:91], v[164:167], v[216:219], v[88:91]
	v_mfma_i32_16x16x64_i8 v[72:75], v[164:167], v[224:227], v[72:75]
	v_mfma_i32_16x16x64_i8 v[72:75], v[160:163], v[220:223], v[72:75]
	v_mfma_i32_16x16x64_i8 v[68:71], v[168:171], v[220:223], v[68:71]
	v_mfma_i32_16x16x64_i8 v[68:71], v[178:181], v[224:227], v[68:71]
	v_mfma_i32_16x16x64_i8 v[84:87], v[178:181], v[216:219], v[84:87]
	v_mfma_i32_16x16x64_i8 v[84:87], v[168:171], v[212:215], v[84:87]
	v_mfma_i32_16x16x64_i8 v[100:103], v[168:171], v[204:207], v[100:103]
	v_mfma_i32_16x16x64_i8 v[100:103], v[178:181], v[208:211], v[100:103]
	v_mfma_i32_16x16x64_i8 v[120:123], v[178:181], v[186:189], v[120:123]
	v_mfma_i32_16x16x64_i8 v[120:123], v[168:171], v[182:185], v[120:123]
	s_setprio 0
	s_barrier
	s_add_i32 s50, s50, s43
	v_lshl_add_u64 v[172:173], s[36:37], 0, v[2:3]
	s_mov_b32 m0, s50
	ds_read_b128 v[182:185], v177 offset:16384
	ds_read_b128 v[186:189], v177 offset:17408
	ds_read_b128 v[204:207], v177 offset:18432
	ds_read_b128 v[208:211], v177 offset:19456
	ds_read_b128 v[212:215], v177 offset:20480
	ds_read_b128 v[216:219], v177 offset:21504
	ds_read_b128 v[220:223], v177 offset:22528
	ds_read_b128 v[224:227], v177 offset:23552
	global_load_lds_dwordx4 v[172:173], off
	s_add_i32 m0, s50, 0x2000
	s_add_u32 s50, s36, 0x80000
	v_lshl_add_u64 v[190:191], s[36:37], 0, v[148:149]
	s_addc_u32 s51, s37, 0
	s_add_i32 s56, s56, s43
	global_load_lds_dwordx4 v[190:191], off
	v_lshl_add_u64 v[228:229], s[50:51], 0, v[2:3]
	s_mov_b32 m0, s56
	v_lshl_add_u64 v[240:241], s[40:41], 0, v[150:151]
	global_load_lds_dwordx4 v[228:229], off
	v_lshl_add_u64 v[228:229], s[50:51], 0, v[148:149]
	s_add_i32 m0, s56, 0x2000
	s_nop 0
	global_load_lds_dwordx4 v[228:229], off
	v_lshl_add_u64 v[228:229], s[40:41], 0, v[152:153]
	s_waitcnt vmcnt(6)
	s_waitcnt lgkmcnt(0)
	s_barrier
; #define PG8_STAGE(bufoff, gbase, voff) do { _Pragma("unroll") for (int _i = 0; _i < 2; ++_i) \
;         __builtin_amdgcn_global_load_lds((const unsigned*)((const char*)(gbase) + (voff)[_i]), (PG8_LAS unsigned*)(lds + (bufoff) + ldsw + _i * 8192), 16, 0, 0); } while (0)
; #define PG8_LDA(dst, b, h) do { _Pragma("unroll") for (int m = 0; m < 4; ++m) _Pragma("unroll") for (int k = 0; k < 2; ++k) dst[m][k] = *(const PG8_LAS bf16x8*)(lds + PG8_SA(b, h) + aoff + m * 2048 + k * 1024); } while (0)
; #define PG8_LDB(dst, b, h) do { _Pragma("unroll") for (int n = 0; n < 2; ++n) _Pragma("unroll") for (int k = 0; k < 2; ++k) dst[n][k] = *(const PG8_LAS bf16x8*)(lds + PG8_SB(b, h) + boff + n * 2048 + k * 1024); } while (0)
; #define PG8_WAIT_V(n) asm volatile("s_waitcnt vmcnt(" #n ")" ::: "memory")
; #define PG8_WAIT_L(n) asm volatile("s_waitcnt lgkmcnt(" #n ")" ::: "memory")
; #define PG8_BAR __builtin_amdgcn_s_barrier()
; #define PG8_SCHED __builtin_amdgcn_sched_barrier(0)
; template <class Epi, class Sched, bool ALIGN_EPI = false, bool SP2 = false, bool I8 = false>
; __device__ __forceinline__ void gemm_phase(PG8_LAS unsigned char* lds, const Gemm g, const Sched& S, const Epi& E) {
;     ...
;             PG8_WAIT_V(8); PG8_WAIT_L(0); PG8_BAR; PG8_MMA(0, 0, At, B0); PG8_MMA(0, 1, At, B1); PG8_BAR; PG8_SCHED;
;             PG8_LDA(At, 0, 1); PG8_STAGE(PG8_SB(0, 0), b2, voffB); PG8_STAGE(PG8_SB(0, 1), b2 + hstep, voffB); PG8_STAGE(PG8_SA(0, 0), a2, voffA);
;             PG8_WAIT_V(8); PG8_WAIT_L(0); PG8_BAR; PG8_MMA(1, 0, At, B0); PG8_MMA(1, 1, At, B1); PG8_BAR; PG8_SCHED;
;             PG8_LDB(B0, 1, 0); PG8_LDB(B1, 1, 1); PG8_SCHED; PG8_LDA(At, 1, 0); PG8_STAGE(PG8_SA(0, 1), a2 + hstep, voffA);
;             PG8_WAIT_V(8); PG8_WAIT_L(0); PG8_BAR; PG8_MMA(0, 0, At, B0); PG8_MMA(0, 1, At, B1); PG8_BAR; PG8_SCHED;
;             PG8_LDA(At, 1, 1); PG8_STAGE(PG8_SB(1, 0), b3, voffB); PG8_STAGE(PG8_SB(1, 1), b3 + hstep, voffB); PG8_STAGE(PG8_SA(1, 0), a3, voffA);
;             PG8_WAIT_V(8); PG8_WAIT_L(0); PG8_BAR; PG8_MMA(1, 0, At, B0); PG8_MMA(1, 1, At, B1); PG8_BAR; PG8_SCHED;
	s_setprio 1
	s_waitcnt lgkmcnt(0)
	v_mfma_i32_16x16x64_i8 v[64:67], v[116:119], v[182:185], v[64:67]
	v_mfma_i32_16x16x64_i8 v[64:67], v[124:127], v[186:189], v[64:67]
	v_mfma_i32_16x16x64_i8 v[48:51], v[124:127], v[208:211], v[48:51]
	v_mfma_i32_16x16x64_i8 v[48:51], v[116:119], v[204:207], v[48:51]
	v_mfma_i32_16x16x64_i8 v[32:35], v[116:119], v[212:215], v[32:35]
	v_mfma_i32_16x16x64_i8 v[32:35], v[124:127], v[216:219], v[32:35]
	v_mfma_i32_16x16x64_i8 v[16:19], v[124:127], v[224:227], v[16:19]
	v_mfma_i32_16x16x64_i8 v[16:19], v[116:119], v[220:223], v[16:19]
	v_mfma_i32_16x16x64_i8 v[12:15], v[132:135], v[220:223], v[12:15]
	v_mfma_i32_16x16x64_i8 v[12:15], v[136:139], v[224:227], v[12:15]
	v_mfma_i32_16x16x64_i8 v[28:31], v[136:139], v[216:219], v[28:31]
	v_mfma_i32_16x16x64_i8 v[28:31], v[132:135], v[212:215], v[28:31]
	v_mfma_i32_16x16x64_i8 v[44:47], v[132:135], v[204:207], v[44:47]
	v_mfma_i32_16x16x64_i8 v[44:47], v[136:139], v[208:211], v[44:47]
	v_mfma_i32_16x16x64_i8 v[60:63], v[136:139], v[186:189], v[60:63]
	v_mfma_i32_16x16x64_i8 v[60:63], v[132:135], v[182:185], v[60:63]
	v_mfma_i32_16x16x64_i8 v[56:59], v[160:163], v[182:185], v[56:59]
	v_mfma_i32_16x16x64_i8 v[56:59], v[164:167], v[186:189], v[56:59]
	v_mfma_i32_16x16x64_i8 v[40:43], v[164:167], v[208:211], v[40:43]
	v_mfma_i32_16x16x64_i8 v[40:43], v[160:163], v[204:207], v[40:43]
	v_mfma_i32_16x16x64_i8 v[24:27], v[160:163], v[212:215], v[24:27]
	v_mfma_i32_16x16x64_i8 v[24:27], v[164:167], v[216:219], v[24:27]
	v_mfma_i32_16x16x64_i8 v[8:11], v[164:167], v[224:227], v[8:11]
	v_mfma_i32_16x16x64_i8 v[8:11], v[160:163], v[220:223], v[8:11]
	v_mfma_i32_16x16x64_i8 v[4:7], v[168:171], v[220:223], v[4:7]
	v_mfma_i32_16x16x64_i8 v[4:7], v[178:181], v[224:227], v[4:7]
	v_mfma_i32_16x16x64_i8 v[20:23], v[178:181], v[216:219], v[20:23]
	v_mfma_i32_16x16x64_i8 v[20:23], v[168:171], v[212:215], v[20:23]
	v_mfma_i32_16x16x64_i8 v[36:39], v[168:171], v[204:207], v[36:39]
	v_mfma_i32_16x16x64_i8 v[36:39], v[178:181], v[208:211], v[36:39]
	v_mfma_i32_16x16x64_i8 v[52:55], v[178:181], v[186:189], v[52:55]
	v_mfma_i32_16x16x64_i8 v[52:55], v[168:171], v[182:185], v[52:55]
	s_setprio 0
	s_barrier
	s_add_i32 s50, 0, 0x18000
	s_add_i32 s51, 0, 0x1c000
	v_add_u32_e32 v136, s50, v175
	v_add_u32_e32 v178, s51, v175
	ds_read_b128 v[116:119], v136
	ds_read_b128 v[124:127], v136 offset:1024
	ds_read_b128 v[132:135], v136 offset:2048
	ds_read_b128 v[136:139], v136 offset:3072
	ds_read_b128 v[160:163], v178
	ds_read_b128 v[164:167], v178 offset:1024
	ds_read_b128 v[168:171], v178 offset:2048
	ds_read_b128 v[178:181], v178 offset:3072
	s_add_u32 s40, s40, 0x80000
	s_addc_u32 s41, s41, 0
	s_mov_b32 m0, s46
	v_lshl_add_u64 v[242:243], s[40:41], 0, v[152:153]
	ds_read_b128 v[182:185], v177 offset:32768
	ds_read_b128 v[186:189], v177 offset:33792
	ds_read_b128 v[204:207], v177 offset:34816
	ds_read_b128 v[208:211], v177 offset:35840
	ds_read_b128 v[212:215], v177 offset:36864
	ds_read_b128 v[216:219], v177 offset:37888
	ds_read_b128 v[220:223], v177 offset:38912
	ds_read_b128 v[224:227], v177 offset:39936
	s_mov_b32 m0, s44
	s_nop 0
	global_load_lds_dwordx4 v[228:229], off
	s_mov_b32 m0, s45
	s_nop 0
	global_load_lds_dwordx4 v[240:241], off
	s_mov_b32 m0, s46
	s_nop 0
	global_load_lds_dwordx4 v[242:243], off
	v_lshl_add_u64 v[242:243], s[40:41], 0, v[150:151]
	s_mov_b32 m0, s47
	s_nop 0
	global_load_lds_dwordx4 v[242:243], off
	s_waitcnt vmcnt(8)
	s_waitcnt lgkmcnt(0)
	s_barrier
	s_setprio 1
	s_waitcnt lgkmcnt(0)
	v_mfma_i32_16x16x64_i8 v[144:147], v[116:119], v[182:185], v[144:147]
	v_mfma_i32_16x16x64_i8 v[144:147], v[124:127], v[186:189], v[144:147]
	v_mfma_i32_16x16x64_i8 v[112:115], v[124:127], v[208:211], v[112:115]
	v_mfma_i32_16x16x64_i8 v[112:115], v[116:119], v[204:207], v[112:115]
	v_mfma_i32_16x16x64_i8 v[96:99], v[116:119], v[212:215], v[96:99]
	v_mfma_i32_16x16x64_i8 v[96:99], v[124:127], v[216:219], v[96:99]
	v_mfma_i32_16x16x64_i8 v[80:83], v[124:127], v[224:227], v[80:83]
	v_mfma_i32_16x16x64_i8 v[80:83], v[116:119], v[220:223], v[80:83]
	v_mfma_i32_16x16x64_i8 v[76:79], v[132:135], v[220:223], v[76:79]
	v_mfma_i32_16x16x64_i8 v[76:79], v[136:139], v[224:227], v[76:79]
	v_mfma_i32_16x16x64_i8 v[92:95], v[136:139], v[216:219], v[92:95]
	v_mfma_i32_16x16x64_i8 v[92:95], v[132:135], v[212:215], v[92:95]
	v_mfma_i32_16x16x64_i8 v[108:111], v[132:135], v[204:207], v[108:111]
	v_mfma_i32_16x16x64_i8 v[108:111], v[136:139], v[208:211], v[108:111]
	v_mfma_i32_16x16x64_i8 v[140:143], v[136:139], v[186:189], v[140:143]
	v_mfma_i32_16x16x64_i8 v[140:143], v[132:135], v[182:185], v[140:143]
	v_mfma_i32_16x16x64_i8 v[128:131], v[160:163], v[182:185], v[128:131]
	v_mfma_i32_16x16x64_i8 v[128:131], v[164:167], v[186:189], v[128:131]
	v_mfma_i32_16x16x64_i8 v[104:107], v[164:167], v[208:211], v[104:107]
	v_mfma_i32_16x16x64_i8 v[104:107], v[160:163], v[204:207], v[104:107]
	v_mfma_i32_16x16x64_i8 v[88:91], v[160:163], v[212:215], v[88:91]
	v_mfma_i32_16x16x64_i8 v[88:91], v[164:167], v[216:219], v[88:91]
	v_mfma_i32_16x16x64_i8 v[72:75], v[164:167], v[224:227], v[72:75]
	v_mfma_i32_16x16x64_i8 v[72:75], v[160:163], v[220:223], v[72:75]
	v_mfma_i32_16x16x64_i8 v[68:71], v[168:171], v[220:223], v[68:71]
	v_mfma_i32_16x16x64_i8 v[68:71], v[178:181], v[224:227], v[68:71]
	v_mfma_i32_16x16x64_i8 v[84:87], v[178:181], v[216:219], v[84:87]
	v_mfma_i32_16x16x64_i8 v[84:87], v[168:171], v[212:215], v[84:87]
	v_mfma_i32_16x16x64_i8 v[100:103], v[168:171], v[204:207], v[100:103]
	v_mfma_i32_16x16x64_i8 v[100:103], v[178:181], v[208:211], v[100:103]
	v_mfma_i32_16x16x64_i8 v[120:123], v[178:181], v[186:189], v[120:123]
	v_mfma_i32_16x16x64_i8 v[120:123], v[168:171], v[182:185], v[120:123]
	s_setprio 0
	s_barrier
	s_add_i32 s40, s50, s43
	v_lshl_add_u64 v[172:173], v[172:173], 0, s[84:85]
	s_mov_b32 m0, s40
	ds_read_b128 v[182:185], v177 offset:49152
	ds_read_b128 v[186:189], v177 offset:50176
	ds_read_b128 v[204:207], v177 offset:51200
	ds_read_b128 v[208:211], v177 offset:52224
	ds_read_b128 v[212:215], v177 offset:53248
	ds_read_b128 v[216:219], v177 offset:54272
	ds_read_b128 v[220:223], v177 offset:55296
	ds_read_b128 v[224:227], v177 offset:56320
	global_load_lds_dwordx4 v[172:173], off
	s_add_i32 m0, s40, 0x2000
	s_add_u32 s36, s36, 0x80080
	v_lshl_add_u64 v[172:173], v[190:191], 0, s[84:85]
	s_addc_u32 s37, s37, 0
	s_add_i32 s40, s51, s43
	global_load_lds_dwordx4 v[172:173], off
	v_lshl_add_u64 v[172:173], s[36:37], 0, v[2:3]
	s_mov_b32 m0, s40
	s_nop 0
	global_load_lds_dwordx4 v[172:173], off
	v_lshl_add_u64 v[172:173], s[36:37], 0, v[148:149]
	s_add_i32 m0, s40, 0x2000
	s_nop 0
	global_load_lds_dwordx4 v[172:173], off
	s_cmp_eq_u32 s76, 28
	s_cbranch_scc0 .Ldefer_208_body
	v_lshl_add_u64 v[172:173], v[228:229], 0, s[84:85]
	s_mov_b32 m0, s52
	s_nop 0
	global_load_lds_dwordx4 v[172:173], off
	v_lshl_add_u64 v[172:173], v[240:241], 0, s[84:85]
	s_mov_b32 m0, s53
	s_nop 0
	global_load_lds_dwordx4 v[172:173], off

; #define PG8_STAGE(bufoff, gbase, voff) do { _Pragma("unroll") for (int _i = 0; _i < 2; ++_i) \
;         __builtin_amdgcn_global_load_lds((const unsigned*)((const char*)(gbase) + (voff)[_i]), (PG8_LAS unsigned*)(lds + (bufoff) + ldsw + _i * 8192), 16, 0, 0); } while (0)
; #define PG8_LDA(dst, b, h) do { _Pragma("unroll") for (int m = 0; m < 4; ++m) _Pragma("unroll") for (int k = 0; k < 2; ++k) dst[m][k] = *(const PG8_LAS bf16x8*)(lds + PG8_SA(b, h) + aoff + m * 2048 + k * 1024); } while (0)
; #define PG8_LDB(dst, b, h) do { _Pragma("unroll") for (int n = 0; n < 2; ++n) _Pragma("unroll") for (int k = 0; k < 2; ++k) dst[n][k] = *(const PG8_LAS bf16x8*)(lds + PG8_SB(b, h) + boff + n * 2048 + k * 1024); } while (0)
; #define PG8_WAIT_V(n) asm volatile("s_waitcnt vmcnt(" #n ")" ::: "memory")
; #define PG8_WAIT_L(n) asm volatile("s_waitcnt lgkmcnt(" #n ")" ::: "memory")
; #define PG8_BAR __builtin_amdgcn_s_barrier()
; #define PG8_SCHED __builtin_amdgcn_sched_barrier(0)
; template <class Epi, class Sched, bool ALIGN_EPI = false, bool SP2 = false, bool I8 = false>
; __device__ __forceinline__ void gemm_phase(PG8_LAS unsigned char* lds, const Gemm g, const Sched& S, const Epi& E) {
;     ...
;         const bool has_next = S.next(ui + 1, nxt);
;         const char* nA = has_next ? (const char*)g.A + (size_t)nxt.pm * tstep : cA; const char* nB = has_next ? (const char*)g.Bt + (size_t)nxt.pn * tstep : cB;
;         for (int t = 0; t < nt; t += 2) {
;             const bool last = (t == nt - 2);
;             const char* a1 = cA + (size_t)(t + 1) * kstep;
;             const char* a2 = last ? nA : cA + (size_t)(t + 2) * kstep; const char* b2 = last ? nB : cB + (size_t)(t + 2) * kstep;
;             const char* a3 = a2 + kstep; const char* b3 = b2 + kstep;
;             if (last && has_next) S.a_ready(nxt);
;             if constexpr (SP2) {
;             PG8_LDB(B0, 0, 0); PG8_LDB(B1, 0, 1); PG8_SCHED; PG8_LDA(At, 0, 0); PG8_STAGE(PG8_SA(1, 1), a1 + hstep, voffA);
;             PG8_WAIT_V(8); PG8_WAIT_L(0); PG8_BAR; PG8_MMA(0, 0, At, B0); PG8_MMA(0, 1, At, B1); PG8_BAR; PG8_SCHED;
;             PG8_LDA(At, 0, 1); PG8_STAGE(PG8_SB(0, 0), b2, voffB); PG8_STAGE(PG8_SB(0, 1), b2 + hstep, voffB); PG8_STAGE(PG8_SA(0, 0), a2, voffA);
;             PG8_WAIT_V(8); PG8_WAIT_L(0); PG8_BAR; PG8_MMA(1, 0, At, B0); PG8_MMA(1, 1, At, B1); PG8_BAR; PG8_SCHED;
.LBB0_229:
	s_ashr_i32 s37, s36, 31
	s_lshl_b64 s[34:35], s[36:37], 21
	s_add_u32 s40, s42, s34
	s_addc_u32 s41, s43, s35
	s_and_b64 s[34:35], s[8:9], exec
	s_cselect_b32 s11, s41, s13
	s_cselect_b32 s34, s40, s12
	s_ashr_i32 s27, s26, 31
	s_lshl_b64 s[50:51], s[26:27], 21
	s_add_u32 s54, s44, s50
	s_addc_u32 s55, s45, s51
	s_and_b64 s[50:51], s[8:9], exec
	s_cselect_b32 s27, s55, s73
	s_cselect_b32 s35, s54, s72
	s_add_u32 s12, s12, 0x100080
	s_addc_u32 s13, s13, 0
	s_add_u32 s37, s72, 0x100
	s_addc_u32 s61, s73, 0
	s_mov_b32 s97, -2
	s_add_u32 s50, s12, 0xfff00080
	s_addc_u32 s51, s13, -1
	s_add_i32 s56, 0, 0x10000
	s_cmp_eq_u32 s97, 60
	s_cselect_b32 s77, s11, s51
	s_cselect_b32 s76, s34, s50
	s_cselect_b32 s73, s27, s61
	s_cselect_b32 s72, s35, s37
	s_add_i32 s57, 0, 0x14000
	v_add_u32_e32 v156, s56, v171
	v_add_u32_e32 v168, s57, v171
	s_waitcnt vmcnt(0)
	ds_read_b128 v[112:115], v156
	ds_read_b128 v[120:123], v156 offset:1024
	ds_read_b128 v[152:155], v156 offset:2048
	ds_read_b128 v[156:159], v156 offset:3072
	ds_read_b128 v[160:163], v168
	ds_read_b128 v[164:167], v168 offset:1024
	s_waitcnt lgkmcnt(0)
	ds_read_b128 v[176:179], v168 offset:2048
	ds_read_b128 v[180:183], v168 offset:3072
	v_lshl_add_u64 v[168:169], s[12:13], 0, v[148:149]
	s_add_i32 m0, s47, 0xc000
	ds_read_b128 v[184:187], v173
	ds_read_b128 v[188:191], v173 offset:1024
	ds_read_b128 v[204:207], v173 offset:2048
	ds_read_b128 v[208:211], v173 offset:3072
	ds_read_b128 v[212:215], v173 offset:4096
	ds_read_b128 v[216:219], v173 offset:5120
	ds_read_b128 v[220:223], v173 offset:6144
	ds_read_b128 v[224:227], v173 offset:7168
	global_load_lds_dwordx4 v[168:169], off
	v_lshl_add_u64 v[168:169], s[12:13], 0, v[150:151]
	s_add_i32 m0, s47, 0xe000
	s_nop 0
	global_load_lds_dwordx4 v[168:169], off
	s_waitcnt vmcnt(8)
	s_waitcnt lgkmcnt(0)
	s_barrier
	s_setprio 1
	s_waitcnt lgkmcnt(0)
	v_mfma_f32_16x16x32_bf16 v[136:139], v[112:115], v[184:187], 0
	v_mfma_f32_16x16x32_bf16 v[136:139], v[120:123], v[188:191], v[136:139]
	v_mfma_f32_16x16x32_bf16 v[116:119], v[120:123], v[208:211], 0
	v_mfma_f32_16x16x32_bf16 v[116:119], v[112:115], v[204:207], v[116:119]
	v_mfma_f32_16x16x32_bf16 v[96:99], v[112:115], v[212:215], 0
	v_mfma_f32_16x16x32_bf16 v[96:99], v[120:123], v[216:219], v[96:99]
	v_mfma_f32_16x16x32_bf16 v[80:83], v[120:123], v[224:227], 0
	v_mfma_f32_16x16x32_bf16 v[80:83], v[112:115], v[220:223], v[80:83]
	v_mfma_f32_16x16x32_bf16 v[76:79], v[152:155], v[220:223], 0
	v_mfma_f32_16x16x32_bf16 v[76:79], v[156:159], v[224:227], v[76:79]
	v_mfma_f32_16x16x32_bf16 v[92:95], v[156:159], v[216:219], 0
	v_mfma_f32_16x16x32_bf16 v[92:95], v[152:155], v[212:215], v[92:95]
	v_mfma_f32_16x16x32_bf16 v[108:111], v[152:155], v[204:207], 0
	v_mfma_f32_16x16x32_bf16 v[108:111], v[156:159], v[208:211], v[108:111]
	v_mfma_f32_16x16x32_bf16 v[132:135], v[156:159], v[188:191], 0
	v_mfma_f32_16x16x32_bf16 v[132:135], v[152:155], v[184:187], v[132:135]
	v_mfma_f32_16x16x32_bf16 v[128:131], v[160:163], v[184:187], 0
	v_mfma_f32_16x16x32_bf16 v[128:131], v[164:167], v[188:191], v[128:131]
	v_mfma_f32_16x16x32_bf16 v[104:107], v[164:167], v[208:211], 0
	v_mfma_f32_16x16x32_bf16 v[104:107], v[160:163], v[204:207], v[104:107]
	v_mfma_f32_16x16x32_bf16 v[88:91], v[160:163], v[212:215], 0
	v_mfma_f32_16x16x32_bf16 v[88:91], v[164:167], v[216:219], v[88:91]
	v_mfma_f32_16x16x32_bf16 v[72:75], v[164:167], v[224:227], 0
	v_mfma_f32_16x16x32_bf16 v[72:75], v[160:163], v[220:223], v[72:75]
	v_mfma_f32_16x16x32_bf16 v[68:71], v[176:179], v[220:223], 0
	v_mfma_f32_16x16x32_bf16 v[68:71], v[180:183], v[224:227], v[68:71]
	v_mfma_f32_16x16x32_bf16 v[84:87], v[180:183], v[216:219], 0
	v_mfma_f32_16x16x32_bf16 v[84:87], v[176:179], v[212:215], v[84:87]
	v_mfma_f32_16x16x32_bf16 v[100:103], v[176:179], v[204:207], 0
	v_mfma_f32_16x16x32_bf16 v[100:103], v[180:183], v[208:211], v[100:103]
	v_mfma_f32_16x16x32_bf16 v[124:127], v[180:183], v[188:191], 0
	v_mfma_f32_16x16x32_bf16 v[124:127], v[176:179], v[184:187], v[124:127]
	s_setprio 0
	s_barrier
	s_add_i32 s50, s56, s46
	v_lshl_add_u64 v[168:169], s[72:73], 0, v[2:3]
	s_mov_b32 m0, s50
	ds_read_b128 v[184:187], v173 offset:16384
	ds_read_b128 v[188:191], v173 offset:17408
	ds_read_b128 v[204:207], v173 offset:18432
	ds_read_b128 v[208:211], v173 offset:19456
	ds_read_b128 v[212:215], v173 offset:20480
	ds_read_b128 v[216:219], v173 offset:21504
	ds_read_b128 v[220:223], v173 offset:22528
	ds_read_b128 v[224:227], v173 offset:23552
	global_load_lds_dwordx4 v[168:169], off
	s_add_i32 m0, s50, 0x2000
	s_add_u32 s50, s72, 0x100000
	v_lshl_add_u64 v[228:229], s[72:73], 0, v[144:145]
	s_addc_u32 s51, s73, 0
	s_add_i32 s56, s57, s46
	global_load_lds_dwordx4 v[228:229], off
	v_lshl_add_u64 v[240:241], s[50:51], 0, v[2:3]
	s_mov_b32 m0, s56
	v_lshl_add_u64 v[242:243], s[76:77], 0, v[142:143]
	global_load_lds_dwordx4 v[240:241], off
	v_lshl_add_u64 v[240:241], s[50:51], 0, v[144:145]
	s_add_i32 m0, s56, 0x2000
	s_nop 0
	global_load_lds_dwordx4 v[240:241], off
	v_lshl_add_u64 v[240:241], s[76:77], 0, v[140:141]
	s_waitcnt vmcnt(6)
	s_waitcnt lgkmcnt(0)
	s_barrier
; #define PG8_STAGE(bufoff, gbase, voff) do { _Pragma("unroll") for (int _i = 0; _i < 2; ++_i) \
;         __builtin_amdgcn_global_load_lds((const unsigned*)((const char*)(gbase) + (voff)[_i]), (PG8_LAS unsigned*)(lds + (bufoff) + ldsw + _i * 8192), 16, 0, 0); } while (0)
; #define PG8_LDA(dst, b, h) do { _Pragma("unroll") for (int m = 0; m < 4; ++m) _Pragma("unroll") for (int k = 0; k < 2; ++k) dst[m][k] = *(const PG8_LAS bf16x8*)(lds + PG8_SA(b, h) + aoff + m * 2048 + k * 1024); } while (0)
; #define PG8_LDB(dst, b, h) do { _Pragma("unroll") for (int n = 0; n < 2; ++n) _Pragma("unroll") for (int k = 0; k < 2; ++k) dst[n][k] = *(const PG8_LAS bf16x8*)(lds + PG8_SB(b, h) + boff + n * 2048 + k * 1024); } while (0)
; #define PG8_WAIT_V(n) asm volatile("s_waitcnt vmcnt(" #n ")" ::: "memory")
; #define PG8_WAIT_L(n) asm volatile("s_waitcnt lgkmcnt(" #n ")" ::: "memory")
; #define PG8_BAR __builtin_amdgcn_s_barrier()
; #define PG8_SCHED __builtin_amdgcn_sched_barrier(0)
; template <class Epi, class Sched, bool ALIGN_EPI = false, bool SP2 = false, bool I8 = false>
; __device__ __forceinline__ void gemm_phase(PG8_LAS unsigned char* lds, const Gemm g, const Sched& S, const Epi& E) {
;     ...
;             PG8_WAIT_V(8); PG8_WAIT_L(0); PG8_BAR; PG8_MMA(0, 0, At, B0); PG8_MMA(0, 1, At, B1); PG8_BAR; PG8_SCHED;
;             PG8_LDA(At, 0, 1); PG8_STAGE(PG8_SB(0, 0), b2, voffB); PG8_STAGE(PG8_SB(0, 1), b2 + hstep, voffB); PG8_STAGE(PG8_SA(0, 0), a2, voffA);
;             PG8_WAIT_V(8); PG8_WAIT_L(0); PG8_BAR; PG8_MMA(1, 0, At, B0); PG8_MMA(1, 1, At, B1); PG8_BAR; PG8_SCHED;
;             PG8_LDB(B0, 1, 0); PG8_LDB(B1, 1, 1); PG8_SCHED; PG8_LDA(At, 1, 0); PG8_STAGE(PG8_SA(0, 1), a2 + hstep, voffA);
;             PG8_WAIT_V(8); PG8_WAIT_L(0); PG8_BAR; PG8_MMA(0, 0, At, B0); PG8_MMA(0, 1, At, B1); PG8_BAR; PG8_SCHED;
;             PG8_LDA(At, 1, 1); PG8_STAGE(PG8_SB(1, 0), b3, voffB); PG8_STAGE(PG8_SB(1, 1), b3 + hstep, voffB); PG8_STAGE(PG8_SA(1, 0), a3, voffA);
;             PG8_WAIT_V(8); PG8_WAIT_L(0); PG8_BAR; PG8_MMA(1, 0, At, B0); PG8_MMA(1, 1, At, B1); PG8_BAR; PG8_SCHED;
	s_setprio 1
	s_waitcnt lgkmcnt(0)
	v_mfma_f32_16x16x32_bf16 v[64:67], v[112:115], v[184:187], 0
	v_mfma_f32_16x16x32_bf16 v[64:67], v[120:123], v[188:191], v[64:67]
	v_mfma_f32_16x16x32_bf16 v[48:51], v[120:123], v[208:211], 0
	v_mfma_f32_16x16x32_bf16 v[48:51], v[112:115], v[204:207], v[48:51]
	v_mfma_f32_16x16x32_bf16 v[32:35], v[112:115], v[212:215], 0
	v_mfma_f32_16x16x32_bf16 v[32:35], v[120:123], v[216:219], v[32:35]
	v_mfma_f32_16x16x32_bf16 v[16:19], v[120:123], v[224:227], 0
	v_mfma_f32_16x16x32_bf16 v[16:19], v[112:115], v[220:223], v[16:19]
	v_mfma_f32_16x16x32_bf16 v[12:15], v[152:155], v[220:223], 0
	v_mfma_f32_16x16x32_bf16 v[12:15], v[156:159], v[224:227], v[12:15]
	v_mfma_f32_16x16x32_bf16 v[28:31], v[156:159], v[216:219], 0
	v_mfma_f32_16x16x32_bf16 v[28:31], v[152:155], v[212:215], v[28:31]
	v_mfma_f32_16x16x32_bf16 v[44:47], v[152:155], v[204:207], 0
	v_mfma_f32_16x16x32_bf16 v[44:47], v[156:159], v[208:211], v[44:47]
	v_mfma_f32_16x16x32_bf16 v[60:63], v[156:159], v[188:191], 0
	v_mfma_f32_16x16x32_bf16 v[60:63], v[152:155], v[184:187], v[60:63]
	v_mfma_f32_16x16x32_bf16 v[56:59], v[160:163], v[184:187], 0
	v_mfma_f32_16x16x32_bf16 v[56:59], v[164:167], v[188:191], v[56:59]
	v_mfma_f32_16x16x32_bf16 v[40:43], v[164:167], v[208:211], 0
	v_mfma_f32_16x16x32_bf16 v[40:43], v[160:163], v[204:207], v[40:43]
	v_mfma_f32_16x16x32_bf16 v[24:27], v[160:163], v[212:215], 0
	v_mfma_f32_16x16x32_bf16 v[24:27], v[164:167], v[216:219], v[24:27]
	v_mfma_f32_16x16x32_bf16 v[8:11], v[164:167], v[224:227], 0
	v_mfma_f32_16x16x32_bf16 v[8:11], v[160:163], v[220:223], v[8:11]
	v_mfma_f32_16x16x32_bf16 v[4:7], v[176:179], v[220:223], 0
	v_mfma_f32_16x16x32_bf16 v[4:7], v[180:183], v[224:227], v[4:7]
	v_mfma_f32_16x16x32_bf16 v[20:23], v[180:183], v[216:219], 0
	v_mfma_f32_16x16x32_bf16 v[20:23], v[176:179], v[212:215], v[20:23]
	v_mfma_f32_16x16x32_bf16 v[36:39], v[176:179], v[204:207], 0
	v_mfma_f32_16x16x32_bf16 v[36:39], v[180:183], v[208:211], v[36:39]
	v_mfma_f32_16x16x32_bf16 v[52:55], v[180:183], v[188:191], 0
	v_mfma_f32_16x16x32_bf16 v[52:55], v[176:179], v[184:187], v[52:55]
	s_setprio 0
	s_barrier
	s_add_i32 s56, 0, 0x18000
	s_add_i32 s57, 0, 0x1c000
	v_add_u32_e32 v156, s56, v171
	v_add_u32_e32 v175, s57, v171
	ds_read_b128 v[112:115], v156
	ds_read_b128 v[120:123], v156 offset:1024
	ds_read_b128 v[152:155], v156 offset:2048
	ds_read_b128 v[156:159], v156 offset:3072
	ds_read_b128 v[160:163], v175
	ds_read_b128 v[164:167], v175 offset:1024
	ds_read_b128 v[176:179], v175 offset:2048
	ds_read_b128 v[180:183], v175 offset:3072
	s_add_u32 s50, s76, 0x100000
	s_addc_u32 s51, s77, 0
	s_mov_b32 m0, s53
	v_lshl_add_u64 v[244:245], s[50:51], 0, v[140:141]
	ds_read_b128 v[184:187], v173 offset:32768
	ds_read_b128 v[188:191], v173 offset:33792
	ds_read_b128 v[204:207], v173 offset:34816
	ds_read_b128 v[208:211], v173 offset:35840
	ds_read_b128 v[212:215], v173 offset:36864
	ds_read_b128 v[216:219], v173 offset:37888
	ds_read_b128 v[220:223], v173 offset:38912
	ds_read_b128 v[224:227], v173 offset:39936
	s_mov_b32 m0, s47
	s_nop 0
	global_load_lds_dwordx4 v[240:241], off
	s_mov_b32 m0, s52
	s_nop 0
	global_load_lds_dwordx4 v[242:243], off
	s_mov_b32 m0, s53
	s_nop 0
	global_load_lds_dwordx4 v[244:245], off
	v_lshl_add_u64 v[244:245], s[50:51], 0, v[142:143]
	s_mov_b32 m0, s64
	s_nop 0
	global_load_lds_dwordx4 v[244:245], off
	s_waitcnt vmcnt(8)
	s_waitcnt lgkmcnt(0)
	s_barrier
	s_setprio 1
	s_waitcnt lgkmcnt(0)
	v_mfma_f32_16x16x32_bf16 v[136:139], v[112:115], v[184:187], v[136:139]
	v_mfma_f32_16x16x32_bf16 v[136:139], v[120:123], v[188:191], v[136:139]
	v_mfma_f32_16x16x32_bf16 v[116:119], v[120:123], v[208:211], v[116:119]
	v_mfma_f32_16x16x32_bf16 v[116:119], v[112:115], v[204:207], v[116:119]
	v_mfma_f32_16x16x32_bf16 v[96:99], v[112:115], v[212:215], v[96:99]
	v_mfma_f32_16x16x32_bf16 v[96:99], v[120:123], v[216:219], v[96:99]
	v_mfma_f32_16x16x32_bf16 v[80:83], v[120:123], v[224:227], v[80:83]
	v_mfma_f32_16x16x32_bf16 v[80:83], v[112:115], v[220:223], v[80:83]
	v_mfma_f32_16x16x32_bf16 v[76:79], v[152:155], v[220:223], v[76:79]
	v_mfma_f32_16x16x32_bf16 v[76:79], v[156:159], v[224:227], v[76:79]
	v_mfma_f32_16x16x32_bf16 v[92:95], v[156:159], v[216:219], v[92:95]
	v_mfma_f32_16x16x32_bf16 v[92:95], v[152:155], v[212:215], v[92:95]
	v_mfma_f32_16x16x32_bf16 v[108:111], v[152:155], v[204:207], v[108:111]
	v_mfma_f32_16x16x32_bf16 v[108:111], v[156:159], v[208:211], v[108:111]
	v_mfma_f32_16x16x32_bf16 v[132:135], v[156:159], v[188:191], v[132:135]
	v_mfma_f32_16x16x32_bf16 v[132:135], v[152:155], v[184:187], v[132:135]
	v_mfma_f32_16x16x32_bf16 v[128:131], v[160:163], v[184:187], v[128:131]
	v_mfma_f32_16x16x32_bf16 v[128:131], v[164:167], v[188:191], v[128:131]
	v_mfma_f32_16x16x32_bf16 v[104:107], v[164:167], v[208:211], v[104:107]
	v_mfma_f32_16x16x32_bf16 v[104:107], v[160:163], v[204:207], v[104:107]
	v_mfma_f32_16x16x32_bf16 v[88:91], v[160:163], v[212:215], v[88:91]
	v_mfma_f32_16x16x32_bf16 v[88:91], v[164:167], v[216:219], v[88:91]
	v_mfma_f32_16x16x32_bf16 v[72:75], v[164:167], v[224:227], v[72:75]
	v_mfma_f32_16x16x32_bf16 v[72:75], v[160:163], v[220:223], v[72:75]
	v_mfma_f32_16x16x32_bf16 v[68:71], v[176:179], v[220:223], v[68:71]
	v_mfma_f32_16x16x32_bf16 v[68:71], v[180:183], v[224:227], v[68:71]
	v_mfma_f32_16x16x32_bf16 v[84:87], v[180:183], v[216:219], v[84:87]
	v_mfma_f32_16x16x32_bf16 v[84:87], v[176:179], v[212:215], v[84:87]
	v_mfma_f32_16x16x32_bf16 v[100:103], v[176:179], v[204:207], v[100:103]
	v_mfma_f32_16x16x32_bf16 v[100:103], v[180:183], v[208:211], v[100:103]
	v_mfma_f32_16x16x32_bf16 v[124:127], v[180:183], v[188:191], v[124:127]
	v_mfma_f32_16x16x32_bf16 v[124:127], v[176:179], v[184:187], v[124:127]
	s_setprio 0
	s_barrier
	s_add_i32 s50, s56, s46
	v_lshl_add_u64 v[168:169], v[168:169], 0, s[84:85]
	s_mov_b32 m0, s50
	ds_read_b128 v[184:187], v173 offset:49152
	ds_read_b128 v[188:191], v173 offset:50176
	ds_read_b128 v[204:207], v173 offset:51200
	ds_read_b128 v[208:211], v173 offset:52224
	ds_read_b128 v[212:215], v173 offset:53248
	ds_read_b128 v[216:219], v173 offset:54272
	ds_read_b128 v[220:223], v173 offset:55296
	ds_read_b128 v[224:227], v173 offset:56320
	global_load_lds_dwordx4 v[168:169], off
	s_add_i32 m0, s50, 0x2000
	s_add_u32 s50, s72, 0x100080
	v_lshl_add_u64 v[168:169], v[228:229], 0, s[84:85]
	s_addc_u32 s51, s73, 0
	s_add_i32 s56, s57, s46
	global_load_lds_dwordx4 v[168:169], off
	v_lshl_add_u64 v[168:169], s[50:51], 0, v[2:3]
	s_mov_b32 m0, s56
	s_nop 0
	global_load_lds_dwordx4 v[168:169], off
	v_lshl_add_u64 v[168:169], s[50:51], 0, v[144:145]
	s_add_i32 m0, s56, 0x2000
	s_nop 0
	global_load_lds_dwordx4 v[168:169], off
	s_cmp_eq_u32 s97, 60
	s_cbranch_scc0 .Ldefer_230_peel
	v_lshl_add_u64 v[168:169], v[240:241], 0, s[84:85]
	s_mov_b32 m0, s28
	s_nop 0
	global_load_lds_dwordx4 v[168:169], off
	v_lshl_add_u64 v[168:169], v[242:243], 0, s[84:85]
	s_mov_b32 m0, s65
	s_nop 0
	global_load_lds_dwordx4 v[168:169], off

; #define PG8_STAGE(bufoff, gbase, voff) do { _Pragma("unroll") for (int _i = 0; _i < 2; ++_i) \
;         __builtin_amdgcn_global_load_lds((const unsigned*)((const char*)(gbase) + (voff)[_i]), (PG8_LAS unsigned*)(lds + (bufoff) + ldsw + _i * 8192), 16, 0, 0); } while (0)
; #define PG8_LDA(dst, b, h) do { _Pragma("unroll") for (int m = 0; m < 4; ++m) _Pragma("unroll") for (int k = 0; k < 2; ++k) dst[m][k] = *(const PG8_LAS bf16x8*)(lds + PG8_SA(b, h) + aoff + m * 2048 + k * 1024); } while (0)
; #define PG8_LDB(dst, b, h) do { _Pragma("unroll") for (int n = 0; n < 2; ++n) _Pragma("unroll") for (int k = 0; k < 2; ++k) dst[n][k] = *(const PG8_LAS bf16x8*)(lds + PG8_SB(b, h) + boff + n * 2048 + k * 1024); } while (0)
; #define PG8_WAIT_V(n) asm volatile("s_waitcnt vmcnt(" #n ")" ::: "memory")
; #define PG8_WAIT_L(n) asm volatile("s_waitcnt lgkmcnt(" #n ")" ::: "memory")
; #define PG8_BAR __builtin_amdgcn_s_barrier()
; #define PG8_SCHED __builtin_amdgcn_sched_barrier(0)
; template <class Epi, class Sched, bool ALIGN_EPI = false, bool SP2 = false, bool I8 = false>
; __device__ __forceinline__ void gemm_phase(PG8_LAS unsigned char* lds, const Gemm g, const Sched& S, const Epi& E) {
;     ...
;             if constexpr (SP2) {
;             PG8_LDB(B0, 0, 0); PG8_LDB(B1, 0, 1); PG8_SCHED; PG8_LDA(At, 0, 0); PG8_STAGE(PG8_SA(1, 1), a1 + hstep, voffA);
;             PG8_WAIT_V(8); PG8_WAIT_L(0); PG8_BAR; PG8_MMA(0, 0, At, B0); PG8_MMA(0, 1, At, B1); PG8_BAR; PG8_SCHED;
;             PG8_LDA(At, 0, 1); PG8_STAGE(PG8_SB(0, 0), b2, voffB); PG8_STAGE(PG8_SB(0, 1), b2 + hstep, voffB); PG8_STAGE(PG8_SA(0, 0), a2, voffA);
;             PG8_WAIT_V(8); PG8_WAIT_L(0); PG8_BAR; PG8_MMA(1, 0, At, B0); PG8_MMA(1, 1, At, B1); PG8_BAR; PG8_SCHED;
.LBB0_230:
	s_add_u32 s50, s12, 0xfff00080
	s_addc_u32 s51, s13, -1
	s_add_i32 s56, 0, 0x10000
	s_cmp_eq_u32 s97, 60
	s_cselect_b32 s77, s11, s51
	s_cselect_b32 s76, s34, s50
	s_cselect_b32 s73, s27, s61
	s_cselect_b32 s72, s35, s37
	s_add_i32 s57, 0, 0x14000
	v_add_u32_e32 v156, s56, v171
	v_add_u32_e32 v168, s57, v171
	ds_read_b128 v[112:115], v156
	ds_read_b128 v[120:123], v156 offset:1024
	ds_read_b128 v[152:155], v156 offset:2048
	ds_read_b128 v[156:159], v156 offset:3072
	ds_read_b128 v[160:163], v168
	ds_read_b128 v[164:167], v168 offset:1024
	ds_read_b128 v[176:179], v168 offset:2048
	ds_read_b128 v[180:183], v168 offset:3072
	ds_read_b128 v[184:187], v173
	ds_read_b128 v[188:191], v173 offset:1024
	ds_read_b128 v[204:207], v173 offset:2048
	ds_read_b128 v[208:211], v173 offset:3072
	ds_read_b128 v[212:215], v173 offset:4096
	ds_read_b128 v[216:219], v173 offset:5120
	ds_read_b128 v[220:223], v173 offset:6144
	ds_read_b128 v[224:227], v173 offset:7168
	v_lshl_add_u64 v[168:169], v[240:241], 0, s[84:85]
	s_mov_b32 m0, s28
	s_nop 0
	global_load_lds_dwordx4 v[168:169], off
	v_lshl_add_u64 v[168:169], v[242:243], 0, s[84:85]
	s_mov_b32 m0, s65
	s_nop 0
	global_load_lds_dwordx4 v[168:169], off
	v_lshl_add_u64 v[168:169], s[12:13], 0, v[148:149]
	s_add_i32 m0, s47, 0xc000
	s_nop 0
	global_load_lds_dwordx4 v[168:169], off
	v_lshl_add_u64 v[168:169], s[12:13], 0, v[150:151]
	s_add_i32 m0, s47, 0xe000
	s_nop 0
	global_load_lds_dwordx4 v[168:169], off
	s_waitcnt vmcnt(8)
	s_waitcnt lgkmcnt(0)
	s_barrier
	s_setprio 1
	s_waitcnt lgkmcnt(0)
	v_mfma_f32_16x16x32_bf16 v[136:139], v[112:115], v[184:187], v[136:139]
	v_mfma_f32_16x16x32_bf16 v[136:139], v[120:123], v[188:191], v[136:139]
	v_mfma_f32_16x16x32_bf16 v[116:119], v[120:123], v[208:211], v[116:119]
	v_mfma_f32_16x16x32_bf16 v[116:119], v[112:115], v[204:207], v[116:119]
	v_mfma_f32_16x16x32_bf16 v[96:99], v[112:115], v[212:215], v[96:99]
	v_mfma_f32_16x16x32_bf16 v[96:99], v[120:123], v[216:219], v[96:99]
	v_mfma_f32_16x16x32_bf16 v[80:83], v[120:123], v[224:227], v[80:83]
	v_mfma_f32_16x16x32_bf16 v[80:83], v[112:115], v[220:223], v[80:83]
	v_mfma_f32_16x16x32_bf16 v[76:79], v[152:155], v[220:223], v[76:79]
	v_mfma_f32_16x16x32_bf16 v[76:79], v[156:159], v[224:227], v[76:79]
	v_mfma_f32_16x16x32_bf16 v[92:95], v[156:159], v[216:219], v[92:95]
	v_mfma_f32_16x16x32_bf16 v[92:95], v[152:155], v[212:215], v[92:95]
	v_mfma_f32_16x16x32_bf16 v[108:111], v[152:155], v[204:207], v[108:111]
	v_mfma_f32_16x16x32_bf16 v[108:111], v[156:159], v[208:211], v[108:111]
	v_mfma_f32_16x16x32_bf16 v[132:135], v[156:159], v[188:191], v[132:135]
	v_mfma_f32_16x16x32_bf16 v[132:135], v[152:155], v[184:187], v[132:135]
	v_mfma_f32_16x16x32_bf16 v[128:131], v[160:163], v[184:187], v[128:131]
	v_mfma_f32_16x16x32_bf16 v[128:131], v[164:167], v[188:191], v[128:131]
	v_mfma_f32_16x16x32_bf16 v[104:107], v[164:167], v[208:211], v[104:107]
	v_mfma_f32_16x16x32_bf16 v[104:107], v[160:163], v[204:207], v[104:107]
	v_mfma_f32_16x16x32_bf16 v[88:91], v[160:163], v[212:215], v[88:91]
	v_mfma_f32_16x16x32_bf16 v[88:91], v[164:167], v[216:219], v[88:91]
	v_mfma_f32_16x16x32_bf16 v[72:75], v[164:167], v[224:227], v[72:75]
	v_mfma_f32_16x16x32_bf16 v[72:75], v[160:163], v[220:223], v[72:75]
	v_mfma_f32_16x16x32_bf16 v[68:71], v[176:179], v[220:223], v[68:71]
	v_mfma_f32_16x16x32_bf16 v[68:71], v[180:183], v[224:227], v[68:71]
	v_mfma_f32_16x16x32_bf16 v[84:87], v[180:183], v[216:219], v[84:87]
	v_mfma_f32_16x16x32_bf16 v[84:87], v[176:179], v[212:215], v[84:87]
	v_mfma_f32_16x16x32_bf16 v[100:103], v[176:179], v[204:207], v[100:103]
	v_mfma_f32_16x16x32_bf16 v[100:103], v[180:183], v[208:211], v[100:103]
	v_mfma_f32_16x16x32_bf16 v[124:127], v[180:183], v[188:191], v[124:127]
	v_mfma_f32_16x16x32_bf16 v[124:127], v[176:179], v[184:187], v[124:127]
	s_setprio 0
	s_barrier
	s_add_i32 s50, s56, s46
	v_lshl_add_u64 v[168:169], s[72:73], 0, v[2:3]
	s_mov_b32 m0, s50
	ds_read_b128 v[184:187], v173 offset:16384
	ds_read_b128 v[188:191], v173 offset:17408
	ds_read_b128 v[204:207], v173 offset:18432
	ds_read_b128 v[208:211], v173 offset:19456
	ds_read_b128 v[212:215], v173 offset:20480
	ds_read_b128 v[216:219], v173 offset:21504
	ds_read_b128 v[220:223], v173 offset:22528
	ds_read_b128 v[224:227], v173 offset:23552
	global_load_lds_dwordx4 v[168:169], off
	s_add_i32 m0, s50, 0x2000
	s_add_u32 s50, s72, 0x100000
	v_lshl_add_u64 v[228:229], s[72:73], 0, v[144:145]
	s_addc_u32 s51, s73, 0
	s_add_i32 s56, s57, s46
	global_load_lds_dwordx4 v[228:229], off
	v_lshl_add_u64 v[240:241], s[50:51], 0, v[2:3]
	s_mov_b32 m0, s56
	v_lshl_add_u64 v[242:243], s[76:77], 0, v[142:143]
	global_load_lds_dwordx4 v[240:241], off
	v_lshl_add_u64 v[240:241], s[50:51], 0, v[144:145]
	s_add_i32 m0, s56, 0x2000
	s_nop 0
	global_load_lds_dwordx4 v[240:241], off
	v_lshl_add_u64 v[240:241], s[76:77], 0, v[140:141]
	s_waitcnt vmcnt(6)
	s_waitcnt lgkmcnt(0)
	s_barrier
; #define PG8_STAGE(bufoff, gbase, voff) do { _Pragma("unroll") for (int _i = 0; _i < 2; ++_i) \
;         __builtin_amdgcn_global_load_lds((const unsigned*)((const char*)(gbase) + (voff)[_i]), (PG8_LAS unsigned*)(lds + (bufoff) + ldsw + _i * 8192), 16, 0, 0); } while (0)
; #define PG8_LDA(dst, b, h) do { _Pragma("unroll") for (int m = 0; m < 4; ++m) _Pragma("unroll") for (int k = 0; k < 2; ++k) dst[m][k] = *(const PG8_LAS bf16x8*)(lds + PG8_SA(b, h) + aoff + m * 2048 + k * 1024); } while (0)
; #define PG8_LDB(dst, b, h) do { _Pragma("unroll") for (int n = 0; n < 2; ++n) _Pragma("unroll") for (int k = 0; k < 2; ++k) dst[n][k] = *(const PG8_LAS bf16x8*)(lds + PG8_SB(b, h) + boff + n * 2048 + k * 1024); } while (0)
; #define PG8_WAIT_V(n) asm volatile("s_waitcnt vmcnt(" #n ")" ::: "memory")
; #define PG8_WAIT_L(n) asm volatile("s_waitcnt lgkmcnt(" #n ")" ::: "memory")
; #define PG8_BAR __builtin_amdgcn_s_barrier()
; #define PG8_SCHED __builtin_amdgcn_sched_barrier(0)
; template <class Epi, class Sched, bool ALIGN_EPI = false, bool SP2 = false, bool I8 = false>
; __device__ __forceinline__ void gemm_phase(PG8_LAS unsigned char* lds, const Gemm g, const Sched& S, const Epi& E) {
;     ...
;             PG8_WAIT_V(8); PG8_WAIT_L(0); PG8_BAR; PG8_MMA(0, 0, At, B0); PG8_MMA(0, 1, At, B1); PG8_BAR; PG8_SCHED;
;             PG8_LDA(At, 0, 1); PG8_STAGE(PG8_SB(0, 0), b2, voffB); PG8_STAGE(PG8_SB(0, 1), b2 + hstep, voffB); PG8_STAGE(PG8_SA(0, 0), a2, voffA);
;             PG8_WAIT_V(8); PG8_WAIT_L(0); PG8_BAR; PG8_MMA(1, 0, At, B0); PG8_MMA(1, 1, At, B1); PG8_BAR; PG8_SCHED;
;             PG8_LDB(B0, 1, 0); PG8_LDB(B1, 1, 1); PG8_SCHED; PG8_LDA(At, 1, 0); PG8_STAGE(PG8_SA(0, 1), a2 + hstep, voffA);
;             PG8_WAIT_V(8); PG8_WAIT_L(0); PG8_BAR; PG8_MMA(0, 0, At, B0); PG8_MMA(0, 1, At, B1); PG8_BAR; PG8_SCHED;
;             PG8_LDA(At, 1, 1); PG8_STAGE(PG8_SB(1, 0), b3, voffB); PG8_STAGE(PG8_SB(1, 1), b3 + hstep, voffB); PG8_STAGE(PG8_SA(1, 0), a3, voffA);
;             PG8_WAIT_V(8); PG8_WAIT_L(0); PG8_BAR; PG8_MMA(1, 0, At, B0); PG8_MMA(1, 1, At, B1); PG8_BAR; PG8_SCHED;
	s_setprio 1
	s_waitcnt lgkmcnt(0)
	v_mfma_f32_16x16x32_bf16 v[64:67], v[112:115], v[184:187], v[64:67]
	v_mfma_f32_16x16x32_bf16 v[64:67], v[120:123], v[188:191], v[64:67]
	v_mfma_f32_16x16x32_bf16 v[48:51], v[120:123], v[208:211], v[48:51]
	v_mfma_f32_16x16x32_bf16 v[48:51], v[112:115], v[204:207], v[48:51]
	v_mfma_f32_16x16x32_bf16 v[32:35], v[112:115], v[212:215], v[32:35]
	v_mfma_f32_16x16x32_bf16 v[32:35], v[120:123], v[216:219], v[32:35]
	v_mfma_f32_16x16x32_bf16 v[16:19], v[120:123], v[224:227], v[16:19]
	v_mfma_f32_16x16x32_bf16 v[16:19], v[112:115], v[220:223], v[16:19]
	v_mfma_f32_16x16x32_bf16 v[12:15], v[152:155], v[220:223], v[12:15]
	v_mfma_f32_16x16x32_bf16 v[12:15], v[156:159], v[224:227], v[12:15]
	v_mfma_f32_16x16x32_bf16 v[28:31], v[156:159], v[216:219], v[28:31]
	v_mfma_f32_16x16x32_bf16 v[28:31], v[152:155], v[212:215], v[28:31]
	v_mfma_f32_16x16x32_bf16 v[44:47], v[152:155], v[204:207], v[44:47]
	v_mfma_f32_16x16x32_bf16 v[44:47], v[156:159], v[208:211], v[44:47]
	v_mfma_f32_16x16x32_bf16 v[60:63], v[156:159], v[188:191], v[60:63]
	v_mfma_f32_16x16x32_bf16 v[60:63], v[152:155], v[184:187], v[60:63]
	v_mfma_f32_16x16x32_bf16 v[56:59], v[160:163], v[184:187], v[56:59]
	v_mfma_f32_16x16x32_bf16 v[56:59], v[164:167], v[188:191], v[56:59]
	v_mfma_f32_16x16x32_bf16 v[40:43], v[164:167], v[208:211], v[40:43]
	v_mfma_f32_16x16x32_bf16 v[40:43], v[160:163], v[204:207], v[40:43]
	v_mfma_f32_16x16x32_bf16 v[24:27], v[160:163], v[212:215], v[24:27]
	v_mfma_f32_16x16x32_bf16 v[24:27], v[164:167], v[216:219], v[24:27]
	v_mfma_f32_16x16x32_bf16 v[8:11], v[164:167], v[224:227], v[8:11]
	v_mfma_f32_16x16x32_bf16 v[8:11], v[160:163], v[220:223], v[8:11]
	v_mfma_f32_16x16x32_bf16 v[4:7], v[176:179], v[220:223], v[4:7]
	v_mfma_f32_16x16x32_bf16 v[4:7], v[180:183], v[224:227], v[4:7]
	v_mfma_f32_16x16x32_bf16 v[20:23], v[180:183], v[216:219], v[20:23]
	v_mfma_f32_16x16x32_bf16 v[20:23], v[176:179], v[212:215], v[20:23]
	v_mfma_f32_16x16x32_bf16 v[36:39], v[176:179], v[204:207], v[36:39]
	v_mfma_f32_16x16x32_bf16 v[36:39], v[180:183], v[208:211], v[36:39]
	v_mfma_f32_16x16x32_bf16 v[52:55], v[180:183], v[188:191], v[52:55]
	v_mfma_f32_16x16x32_bf16 v[52:55], v[176:179], v[184:187], v[52:55]
	s_setprio 0
	s_barrier
	s_add_i32 s56, 0, 0x18000
	s_add_i32 s57, 0, 0x1c000
	v_add_u32_e32 v156, s56, v171
	v_add_u32_e32 v175, s57, v171
	ds_read_b128 v[112:115], v156
	ds_read_b128 v[120:123], v156 offset:1024
	ds_read_b128 v[152:155], v156 offset:2048
	ds_read_b128 v[156:159], v156 offset:3072
	ds_read_b128 v[160:163], v175
	ds_read_b128 v[164:167], v175 offset:1024
	ds_read_b128 v[176:179], v175 offset:2048
	ds_read_b128 v[180:183], v175 offset:3072
	s_add_u32 s50, s76, 0x100000
	s_addc_u32 s51, s77, 0
	s_mov_b32 m0, s53
	v_lshl_add_u64 v[244:245], s[50:51], 0, v[140:141]
	ds_read_b128 v[184:187], v173 offset:32768
	ds_read_b128 v[188:191], v173 offset:33792
	ds_read_b128 v[204:207], v173 offset:34816
	ds_read_b128 v[208:211], v173 offset:35840
	ds_read_b128 v[212:215], v173 offset:36864
	ds_read_b128 v[216:219], v173 offset:37888
	ds_read_b128 v[220:223], v173 offset:38912
	ds_read_b128 v[224:227], v173 offset:39936
	s_mov_b32 m0, s47
	s_nop 0
	global_load_lds_dwordx4 v[240:241], off
	s_mov_b32 m0, s52
	s_nop 0
	global_load_lds_dwordx4 v[242:243], off
	s_mov_b32 m0, s53
	s_nop 0
	global_load_lds_dwordx4 v[244:245], off
	v_lshl_add_u64 v[244:245], s[50:51], 0, v[142:143]
	s_mov_b32 m0, s64
	s_nop 0
	global_load_lds_dwordx4 v[244:245], off
	s_waitcnt vmcnt(8)
	s_waitcnt lgkmcnt(0)
	s_barrier
; #define PG8_STAGE(bufoff, gbase, voff) do { _Pragma("unroll") for (int _i = 0; _i < 2; ++_i) \
;         __builtin_amdgcn_global_load_lds((const unsigned*)((const char*)(gbase) + (voff)[_i]), (PG8_LAS unsigned*)(lds + (bufoff) + ldsw + _i * 8192), 16, 0, 0); } while (0)
; #define PG8_LDA(dst, b, h) do { _Pragma("unroll") for (int m = 0; m < 4; ++m) _Pragma("unroll") for (int k = 0; k < 2; ++k) dst[m][k] = *(const PG8_LAS bf16x8*)(lds + PG8_SA(b, h) + aoff + m * 2048 + k * 1024); } while (0)
; #define PG8_WAIT_V(n) asm volatile("s_waitcnt vmcnt(" #n ")" ::: "memory")
; #define PG8_WAIT_L(n) asm volatile("s_waitcnt lgkmcnt(" #n ")" ::: "memory")
; #define PG8_BAR __builtin_amdgcn_s_barrier()
; #define PG8_SCHED __builtin_amdgcn_sched_barrier(0)
; template <class Epi, class Sched, bool ALIGN_EPI = false, bool SP2 = false, bool I8 = false>
; __device__ __forceinline__ void gemm_phase(PG8_LAS unsigned char* lds, const Gemm g, const Sched& S, const Epi& E) {
;     ...
;             PG8_WAIT_V(8); PG8_WAIT_L(0); PG8_BAR; PG8_MMA(0, 0, At, B0); PG8_MMA(0, 1, At, B1); PG8_BAR; PG8_SCHED;
;             PG8_LDA(At, 1, 1); PG8_STAGE(PG8_SB(1, 0), b3, voffB); PG8_STAGE(PG8_SB(1, 1), b3 + hstep, voffB); PG8_STAGE(PG8_SA(1, 0), a3, voffA);
;             PG8_WAIT_V(8); PG8_WAIT_L(0); PG8_BAR; PG8_MMA(1, 0, At, B0); PG8_MMA(1, 1, At, B1); PG8_BAR; PG8_SCHED;
	s_setprio 1
	s_waitcnt lgkmcnt(0)
	v_mfma_f32_16x16x32_bf16 v[136:139], v[112:115], v[184:187], v[136:139]
	v_mfma_f32_16x16x32_bf16 v[136:139], v[120:123], v[188:191], v[136:139]
	v_mfma_f32_16x16x32_bf16 v[116:119], v[120:123], v[208:211], v[116:119]
	v_mfma_f32_16x16x32_bf16 v[116:119], v[112:115], v[204:207], v[116:119]
	v_mfma_f32_16x16x32_bf16 v[96:99], v[112:115], v[212:215], v[96:99]
	v_mfma_f32_16x16x32_bf16 v[96:99], v[120:123], v[216:219], v[96:99]
	v_mfma_f32_16x16x32_bf16 v[80:83], v[120:123], v[224:227], v[80:83]
	v_mfma_f32_16x16x32_bf16 v[80:83], v[112:115], v[220:223], v[80:83]
	v_mfma_f32_16x16x32_bf16 v[76:79], v[152:155], v[220:223], v[76:79]
	v_mfma_f32_16x16x32_bf16 v[76:79], v[156:159], v[224:227], v[76:79]
	v_mfma_f32_16x16x32_bf16 v[92:95], v[156:159], v[216:219], v[92:95]
	v_mfma_f32_16x16x32_bf16 v[92:95], v[152:155], v[212:215], v[92:95]
	v_mfma_f32_16x16x32_bf16 v[108:111], v[152:155], v[204:207], v[108:111]
	v_mfma_f32_16x16x32_bf16 v[108:111], v[156:159], v[208:211], v[108:111]
	v_mfma_f32_16x16x32_bf16 v[132:135], v[156:159], v[188:191], v[132:135]
	v_mfma_f32_16x16x32_bf16 v[132:135], v[152:155], v[184:187], v[132:135]
	v_mfma_f32_16x16x32_bf16 v[128:131], v[160:163], v[184:187], v[128:131]
	v_mfma_f32_16x16x32_bf16 v[128:131], v[164:167], v[188:191], v[128:131]
	v_mfma_f32_16x16x32_bf16 v[104:107], v[164:167], v[208:211], v[104:107]
	v_mfma_f32_16x16x32_bf16 v[104:107], v[160:163], v[204:207], v[104:107]
	v_mfma_f32_16x16x32_bf16 v[88:91], v[160:163], v[212:215], v[88:91]
	v_mfma_f32_16x16x32_bf16 v[88:91], v[164:167], v[216:219], v[88:91]
	v_mfma_f32_16x16x32_bf16 v[72:75], v[164:167], v[224:227], v[72:75]
	v_mfma_f32_16x16x32_bf16 v[72:75], v[160:163], v[220:223], v[72:75]
	v_mfma_f32_16x16x32_bf16 v[68:71], v[176:179], v[220:223], v[68:71]
	v_mfma_f32_16x16x32_bf16 v[68:71], v[180:183], v[224:227], v[68:71]
	v_mfma_f32_16x16x32_bf16 v[84:87], v[180:183], v[216:219], v[84:87]
	v_mfma_f32_16x16x32_bf16 v[84:87], v[176:179], v[212:215], v[84:87]
	v_mfma_f32_16x16x32_bf16 v[100:103], v[176:179], v[204:207], v[100:103]
	v_mfma_f32_16x16x32_bf16 v[100:103], v[180:183], v[208:211], v[100:103]
	v_mfma_f32_16x16x32_bf16 v[124:127], v[180:183], v[188:191], v[124:127]
	v_mfma_f32_16x16x32_bf16 v[124:127], v[176:179], v[184:187], v[124:127]
	s_setprio 0
	s_barrier
	s_add_i32 s50, s56, s46
	v_lshl_add_u64 v[168:169], v[168:169], 0, s[84:85]
	s_mov_b32 m0, s50
	ds_read_b128 v[184:187], v173 offset:49152
	ds_read_b128 v[188:191], v173 offset:50176
	ds_read_b128 v[204:207], v173 offset:51200
	ds_read_b128 v[208:211], v173 offset:52224
	ds_read_b128 v[212:215], v173 offset:53248
	ds_read_b128 v[216:219], v173 offset:54272
	ds_read_b128 v[220:223], v173 offset:55296
	ds_read_b128 v[224:227], v173 offset:56320
	global_load_lds_dwordx4 v[168:169], off
	s_add_i32 m0, s50, 0x2000
	s_add_u32 s50, s72, 0x100080
	v_lshl_add_u64 v[168:169], v[228:229], 0, s[84:85]
	s_addc_u32 s51, s73, 0
	s_add_i32 s56, s57, s46
	global_load_lds_dwordx4 v[168:169], off
	v_lshl_add_u64 v[168:169], s[50:51], 0, v[2:3]
	s_mov_b32 m0, s56
	s_nop 0
	global_load_lds_dwordx4 v[168:169], off
	v_lshl_add_u64 v[168:169], s[50:51], 0, v[144:145]
	s_add_i32 m0, s56, 0x2000
	s_nop 0
	global_load_lds_dwordx4 v[168:169], off
	s_cmp_eq_u32 s97, 60
	s_cbranch_scc0 .Ldefer_230_body
	v_lshl_add_u64 v[168:169], v[240:241], 0, s[84:85]
	s_mov_b32 m0, s28
	s_nop 0
	global_load_lds_dwordx4 v[168:169], off
	v_lshl_add_u64 v[168:169], v[242:243], 0, s[84:85]
	s_mov_b32 m0, s65
	s_nop 0
	global_load_lds_dwordx4 v[168:169], off

; #define PG8_STAGE(bufoff, gbase, voff) do { _Pragma("unroll") for (int _i = 0; _i < 2; ++_i) \
;         __builtin_amdgcn_global_load_lds((const unsigned*)((const char*)(gbase) + (voff)[_i]), (PG8_LAS unsigned*)(lds + (bufoff) + ldsw + _i * 8192), 16, 0, 0); } while (0)
; #define PG8_LDA(dst, b, h) do { _Pragma("unroll") for (int m = 0; m < 4; ++m) _Pragma("unroll") for (int k = 0; k < 2; ++k) dst[m][k] = *(const PG8_LAS bf16x8*)(lds + PG8_SA(b, h) + aoff + m * 2048 + k * 1024); } while (0)
; #define PG8_LDB(dst, b, h) do { _Pragma("unroll") for (int n = 0; n < 2; ++n) _Pragma("unroll") for (int k = 0; k < 2; ++k) dst[n][k] = *(const PG8_LAS bf16x8*)(lds + PG8_SB(b, h) + boff + n * 2048 + k * 1024); } while (0)
; #define PG8_WAIT_V(n) asm volatile("s_waitcnt vmcnt(" #n ")" ::: "memory")
; #define PG8_WAIT_L(n) asm volatile("s_waitcnt lgkmcnt(" #n ")" ::: "memory")
; #define PG8_BAR __builtin_amdgcn_s_barrier()
; #define PG8_SCHED __builtin_amdgcn_sched_barrier(0)
; template <class Epi, class Sched, bool ALIGN_EPI = false, bool SP2 = false, bool I8 = false>
; __device__ __forceinline__ void gemm_phase(PG8_LAS unsigned char* lds, const Gemm g, const Sched& S, const Epi& E) {
;     ...
;         const bool has_next = S.next(ui + 1, nxt);
;         const char* nA = has_next ? (const char*)g.A + (size_t)nxt.pm * tstep : cA; const char* nB = has_next ? (const char*)g.Bt + (size_t)nxt.pn * tstep : cB;
;         for (int t = 0; t < nt; t += 2) {
;             const bool last = (t == nt - 2);
;             const char* a1 = cA + (size_t)(t + 1) * kstep;
;             const char* a2 = last ? nA : cA + (size_t)(t + 2) * kstep; const char* b2 = last ? nB : cB + (size_t)(t + 2) * kstep;
;             const char* a3 = a2 + kstep; const char* b3 = b2 + kstep;
;             if (last && has_next) S.a_ready(nxt);
;             if constexpr (SP2) {
;             PG8_LDB(B0, 0, 0); PG8_LDB(B1, 0, 1); PG8_SCHED; PG8_LDA(At, 0, 0); PG8_STAGE(PG8_SA(1, 1), a1 + hstep, voffA);
;             PG8_WAIT_V(8); PG8_WAIT_L(0); PG8_BAR; PG8_MMA(0, 0, At, B0); PG8_MMA(0, 1, At, B1); PG8_BAR; PG8_SCHED;
;             PG8_LDA(At, 0, 1); PG8_STAGE(PG8_SB(0, 0), b2, voffB); PG8_STAGE(PG8_SB(0, 1), b2 + hstep, voffB); PG8_STAGE(PG8_SA(0, 0), a2, voffA);
;             PG8_WAIT_V(8); PG8_WAIT_L(0); PG8_BAR; PG8_MMA(1, 0, At, B0); PG8_MMA(1, 1, At, B1); PG8_BAR; PG8_SCHED;
.LBB0_1455:
	s_ashr_i32 s17, s16, 31
	s_lshl_b64 s[20:21], s[16:17], 21
	s_add_u32 s20, s28, s20
	s_addc_u32 s21, s34, s21
	s_and_b64 s[22:23], s[8:9], exec
	s_cselect_b32 s17, s21, s25
	s_cselect_b32 s51, s20, s24
	s_ashr_i32 s19, s18, 31
	s_lshl_b64 s[22:23], s[18:19], 21
	s_add_u32 s22, s35, s22
	s_addc_u32 s23, s39, s23
	s_and_b64 s[36:37], s[8:9], exec
	s_cselect_b32 s19, s23, s27
	s_cselect_b32 s52, s22, s26
	s_add_u32 s24, s24, 0x100080
	s_addc_u32 s25, s25, 0
	s_add_u32 s53, s26, 0x100
	s_addc_u32 s54, s27, 0
	s_mov_b32 s55, -2
	s_waitcnt vmcnt(0)
	s_add_u32 s26, s24, 0xfff00080
	s_addc_u32 s27, s25, -1
	s_add_i32 s56, 0, 0x10000
	s_cmp_eq_u32 s55, 60
	s_cselect_b32 s37, s17, s27
	s_cselect_b32 s36, s51, s26
	s_cselect_b32 s27, s19, s54
	s_cselect_b32 s26, s52, s53
	s_add_i32 s58, 0, 0x14000
	v_add_u32_e32 v144, s56, v240
	v_add_u32_e32 v160, s58, v240
	ds_read_b128 v[124:127], v144
	ds_read_b128 v[128:131], v144 offset:1024
	ds_read_b128 v[132:135], v144 offset:2048
	ds_read_b128 v[144:147], v144 offset:3072
	ds_read_b128 v[148:151], v160
	ds_read_b128 v[152:155], v160 offset:1024
	ds_read_b128 v[156:159], v160 offset:2048
	ds_read_b128 v[160:163], v160 offset:3072
	v_lshl_add_u64 v[218:219], s[24:25], 0, v[210:211]
	s_add_i32 m0, s41, 0xc000
	ds_read_b128 v[164:167], v242
	ds_read_b128 v[168:171], v242 offset:1024
	ds_read_b128 v[172:175], v242 offset:2048
	ds_read_b128 v[176:179], v242 offset:3072
	ds_read_b128 v[180:183], v242 offset:4096
	ds_read_b128 v[184:187], v242 offset:5120
	ds_read_b128 v[188:191], v242 offset:6144
	ds_read_b128 v[214:217], v242 offset:7168
	global_load_lds_dwordx4 v[218:219], off
	v_lshl_add_u64 v[218:219], s[24:25], 0, v[212:213]
	s_add_i32 m0, s41, 0xe000
	s_nop 0
	global_load_lds_dwordx4 v[218:219], off
	s_waitcnt vmcnt(8)
	s_waitcnt lgkmcnt(0)
	s_barrier
	s_setprio 1
	s_waitcnt lgkmcnt(0)
	v_mfma_f32_16x16x32_bf16 v[140:143], v[124:127], v[164:167], 0
	v_mfma_f32_16x16x32_bf16 v[140:143], v[128:131], v[168:171], v[140:143]
	v_mfma_f32_16x16x32_bf16 v[112:115], v[128:131], v[176:179], 0
	v_mfma_f32_16x16x32_bf16 v[112:115], v[124:127], v[172:175], v[112:115]
	v_mfma_f32_16x16x32_bf16 v[96:99], v[124:127], v[180:183], 0
	v_mfma_f32_16x16x32_bf16 v[96:99], v[128:131], v[184:187], v[96:99]
	v_mfma_f32_16x16x32_bf16 v[80:83], v[128:131], v[214:217], 0
	v_mfma_f32_16x16x32_bf16 v[80:83], v[124:127], v[188:191], v[80:83]
	v_mfma_f32_16x16x32_bf16 v[76:79], v[132:135], v[188:191], 0
	v_mfma_f32_16x16x32_bf16 v[76:79], v[144:147], v[214:217], v[76:79]
	v_mfma_f32_16x16x32_bf16 v[92:95], v[144:147], v[184:187], 0
	v_mfma_f32_16x16x32_bf16 v[92:95], v[132:135], v[180:183], v[92:95]
	v_mfma_f32_16x16x32_bf16 v[108:111], v[132:135], v[172:175], 0
	v_mfma_f32_16x16x32_bf16 v[108:111], v[144:147], v[176:179], v[108:111]
	v_mfma_f32_16x16x32_bf16 v[136:139], v[144:147], v[168:171], 0
	v_mfma_f32_16x16x32_bf16 v[136:139], v[132:135], v[164:167], v[136:139]
	v_mfma_f32_16x16x32_bf16 v[120:123], v[148:151], v[164:167], 0
	v_mfma_f32_16x16x32_bf16 v[120:123], v[152:155], v[168:171], v[120:123]
	v_mfma_f32_16x16x32_bf16 v[104:107], v[152:155], v[176:179], 0
	v_mfma_f32_16x16x32_bf16 v[104:107], v[148:151], v[172:175], v[104:107]
	v_mfma_f32_16x16x32_bf16 v[88:91], v[148:151], v[180:183], 0
	v_mfma_f32_16x16x32_bf16 v[88:91], v[152:155], v[184:187], v[88:91]
	v_mfma_f32_16x16x32_bf16 v[72:75], v[152:155], v[214:217], 0
	v_mfma_f32_16x16x32_bf16 v[72:75], v[148:151], v[188:191], v[72:75]
	v_mfma_f32_16x16x32_bf16 v[68:71], v[156:159], v[188:191], 0
	v_mfma_f32_16x16x32_bf16 v[68:71], v[160:163], v[214:217], v[68:71]
	v_mfma_f32_16x16x32_bf16 v[84:87], v[160:163], v[184:187], 0
	v_mfma_f32_16x16x32_bf16 v[84:87], v[156:159], v[180:183], v[84:87]
	v_mfma_f32_16x16x32_bf16 v[100:103], v[156:159], v[172:175], 0
	v_mfma_f32_16x16x32_bf16 v[100:103], v[160:163], v[176:179], v[100:103]
	v_mfma_f32_16x16x32_bf16 v[116:119], v[160:163], v[168:171], 0
	v_mfma_f32_16x16x32_bf16 v[116:119], v[156:159], v[164:167], v[116:119]
	s_setprio 0
	s_barrier
	s_add_i32 s56, s56, s40
	v_lshl_add_u64 v[218:219], s[26:27], 0, v[2:3]
	s_mov_b32 m0, s56
	ds_read_b128 v[164:167], v242 offset:16384
	ds_read_b128 v[168:171], v242 offset:17408
	ds_read_b128 v[172:175], v242 offset:18432
	ds_read_b128 v[176:179], v242 offset:19456
	ds_read_b128 v[180:183], v242 offset:20480
	ds_read_b128 v[184:187], v242 offset:21504
	ds_read_b128 v[188:191], v242 offset:22528
	ds_read_b128 v[214:217], v242 offset:23552
	global_load_lds_dwordx4 v[218:219], off
	s_add_i32 m0, s56, 0x2000
	s_add_u32 s56, s26, 0x100000
	v_lshl_add_u64 v[220:221], s[26:27], 0, v[204:205]
	s_addc_u32 s57, s27, 0
	s_add_i32 s58, s58, s40
	global_load_lds_dwordx4 v[220:221], off
	v_lshl_add_u64 v[222:223], s[56:57], 0, v[2:3]
	s_mov_b32 m0, s58
	v_lshl_add_u64 v[224:225], s[36:37], 0, v[206:207]
	global_load_lds_dwordx4 v[222:223], off
	v_lshl_add_u64 v[222:223], s[56:57], 0, v[204:205]
	s_add_i32 m0, s58, 0x2000
	s_nop 0
	global_load_lds_dwordx4 v[222:223], off
	v_lshl_add_u64 v[222:223], s[36:37], 0, v[208:209]
	s_waitcnt vmcnt(6)
	s_waitcnt lgkmcnt(0)
	s_barrier
; #define PG8_STAGE(bufoff, gbase, voff) do { _Pragma("unroll") for (int _i = 0; _i < 2; ++_i) \
;         __builtin_amdgcn_global_load_lds((const unsigned*)((const char*)(gbase) + (voff)[_i]), (PG8_LAS unsigned*)(lds + (bufoff) + ldsw + _i * 8192), 16, 0, 0); } while (0)
; #define PG8_LDA(dst, b, h) do { _Pragma("unroll") for (int m = 0; m < 4; ++m) _Pragma("unroll") for (int k = 0; k < 2; ++k) dst[m][k] = *(const PG8_LAS bf16x8*)(lds + PG8_SA(b, h) + aoff + m * 2048 + k * 1024); } while (0)
; #define PG8_LDB(dst, b, h) do { _Pragma("unroll") for (int n = 0; n < 2; ++n) _Pragma("unroll") for (int k = 0; k < 2; ++k) dst[n][k] = *(const PG8_LAS bf16x8*)(lds + PG8_SB(b, h) + boff + n * 2048 + k * 1024); } while (0)
; #define PG8_WAIT_V(n) asm volatile("s_waitcnt vmcnt(" #n ")" ::: "memory")
; #define PG8_WAIT_L(n) asm volatile("s_waitcnt lgkmcnt(" #n ")" ::: "memory")
; #define PG8_BAR __builtin_amdgcn_s_barrier()
; #define PG8_SCHED __builtin_amdgcn_sched_barrier(0)
; template <class Epi, class Sched, bool ALIGN_EPI = false, bool SP2 = false, bool I8 = false>
; __device__ __forceinline__ void gemm_phase(PG8_LAS unsigned char* lds, const Gemm g, const Sched& S, const Epi& E) {
;     ...
;             PG8_WAIT_V(8); PG8_WAIT_L(0); PG8_BAR; PG8_MMA(0, 0, At, B0); PG8_MMA(0, 1, At, B1); PG8_BAR; PG8_SCHED;
;             PG8_LDA(At, 0, 1); PG8_STAGE(PG8_SB(0, 0), b2, voffB); PG8_STAGE(PG8_SB(0, 1), b2 + hstep, voffB); PG8_STAGE(PG8_SA(0, 0), a2, voffA);
;             PG8_WAIT_V(8); PG8_WAIT_L(0); PG8_BAR; PG8_MMA(1, 0, At, B0); PG8_MMA(1, 1, At, B1); PG8_BAR; PG8_SCHED;
;             PG8_LDB(B0, 1, 0); PG8_LDB(B1, 1, 1); PG8_SCHED; PG8_LDA(At, 1, 0); PG8_STAGE(PG8_SA(0, 1), a2 + hstep, voffA);
;             PG8_WAIT_V(8); PG8_WAIT_L(0); PG8_BAR; PG8_MMA(0, 0, At, B0); PG8_MMA(0, 1, At, B1); PG8_BAR; PG8_SCHED;
;             PG8_LDA(At, 1, 1); PG8_STAGE(PG8_SB(1, 0), b3, voffB); PG8_STAGE(PG8_SB(1, 1), b3 + hstep, voffB); PG8_STAGE(PG8_SA(1, 0), a3, voffA);
;             PG8_WAIT_V(8); PG8_WAIT_L(0); PG8_BAR; PG8_MMA(1, 0, At, B0); PG8_MMA(1, 1, At, B1); PG8_BAR; PG8_SCHED;
	s_setprio 1
	s_waitcnt lgkmcnt(0)
	v_mfma_f32_16x16x32_bf16 v[64:67], v[124:127], v[164:167], 0
	v_mfma_f32_16x16x32_bf16 v[64:67], v[128:131], v[168:171], v[64:67]
	v_mfma_f32_16x16x32_bf16 v[48:51], v[128:131], v[176:179], 0
	v_mfma_f32_16x16x32_bf16 v[48:51], v[124:127], v[172:175], v[48:51]
	v_mfma_f32_16x16x32_bf16 v[32:35], v[124:127], v[180:183], 0
	v_mfma_f32_16x16x32_bf16 v[32:35], v[128:131], v[184:187], v[32:35]
	v_mfma_f32_16x16x32_bf16 v[16:19], v[128:131], v[214:217], 0
	v_mfma_f32_16x16x32_bf16 v[16:19], v[124:127], v[188:191], v[16:19]
	v_mfma_f32_16x16x32_bf16 v[12:15], v[132:135], v[188:191], 0
	v_mfma_f32_16x16x32_bf16 v[12:15], v[144:147], v[214:217], v[12:15]
	v_mfma_f32_16x16x32_bf16 v[28:31], v[144:147], v[184:187], 0
	v_mfma_f32_16x16x32_bf16 v[28:31], v[132:135], v[180:183], v[28:31]
	v_mfma_f32_16x16x32_bf16 v[44:47], v[132:135], v[172:175], 0
	v_mfma_f32_16x16x32_bf16 v[44:47], v[144:147], v[176:179], v[44:47]
	v_mfma_f32_16x16x32_bf16 v[60:63], v[144:147], v[168:171], 0
	v_mfma_f32_16x16x32_bf16 v[60:63], v[132:135], v[164:167], v[60:63]
	v_mfma_f32_16x16x32_bf16 v[56:59], v[148:151], v[164:167], 0
	v_mfma_f32_16x16x32_bf16 v[56:59], v[152:155], v[168:171], v[56:59]
	v_mfma_f32_16x16x32_bf16 v[40:43], v[152:155], v[176:179], 0
	v_mfma_f32_16x16x32_bf16 v[40:43], v[148:151], v[172:175], v[40:43]
	v_mfma_f32_16x16x32_bf16 v[24:27], v[148:151], v[180:183], 0
	v_mfma_f32_16x16x32_bf16 v[24:27], v[152:155], v[184:187], v[24:27]
	v_mfma_f32_16x16x32_bf16 v[8:11], v[152:155], v[214:217], 0
	v_mfma_f32_16x16x32_bf16 v[8:11], v[148:151], v[188:191], v[8:11]
	v_mfma_f32_16x16x32_bf16 v[4:7], v[156:159], v[188:191], 0
	v_mfma_f32_16x16x32_bf16 v[4:7], v[160:163], v[214:217], v[4:7]
	v_mfma_f32_16x16x32_bf16 v[20:23], v[160:163], v[184:187], 0
	v_mfma_f32_16x16x32_bf16 v[20:23], v[156:159], v[180:183], v[20:23]
	v_mfma_f32_16x16x32_bf16 v[36:39], v[156:159], v[172:175], 0
	v_mfma_f32_16x16x32_bf16 v[36:39], v[160:163], v[176:179], v[36:39]
	v_mfma_f32_16x16x32_bf16 v[52:55], v[160:163], v[168:171], 0
	v_mfma_f32_16x16x32_bf16 v[52:55], v[156:159], v[164:167], v[52:55]
	s_setprio 0
	s_barrier
	s_add_i32 s56, 0, 0x18000
	s_add_i32 s57, 0, 0x1c000
	v_add_u32_e32 v144, s56, v240
	v_add_u32_e32 v160, s57, v240
	ds_read_b128 v[124:127], v144
	ds_read_b128 v[128:131], v144 offset:1024
	ds_read_b128 v[132:135], v144 offset:2048
	ds_read_b128 v[144:147], v144 offset:3072
	ds_read_b128 v[148:151], v160
	ds_read_b128 v[152:155], v160 offset:1024
	ds_read_b128 v[156:159], v160 offset:2048
	ds_read_b128 v[160:163], v160 offset:3072
	s_add_u32 s36, s36, 0x100000
	s_addc_u32 s37, s37, 0
	s_mov_b32 m0, s43
	v_lshl_add_u64 v[226:227], s[36:37], 0, v[208:209]
	ds_read_b128 v[164:167], v242 offset:32768
	ds_read_b128 v[168:171], v242 offset:33792
	ds_read_b128 v[172:175], v242 offset:34816
	ds_read_b128 v[176:179], v242 offset:35840
	ds_read_b128 v[180:183], v242 offset:36864
	ds_read_b128 v[184:187], v242 offset:37888
	ds_read_b128 v[188:191], v242 offset:38912
	ds_read_b128 v[214:217], v242 offset:39936
	s_mov_b32 m0, s41
	s_nop 0
	global_load_lds_dwordx4 v[222:223], off
	s_mov_b32 m0, s42
	s_nop 0
	global_load_lds_dwordx4 v[224:225], off
	s_mov_b32 m0, s43
	s_nop 0
	global_load_lds_dwordx4 v[226:227], off
	v_lshl_add_u64 v[226:227], s[36:37], 0, v[206:207]
	s_mov_b32 m0, s44
	s_nop 0
	global_load_lds_dwordx4 v[226:227], off
	s_waitcnt vmcnt(8)
	s_waitcnt lgkmcnt(0)
	s_barrier
	s_setprio 1
	s_waitcnt lgkmcnt(0)
	v_mfma_f32_16x16x32_bf16 v[140:143], v[124:127], v[164:167], v[140:143]
	v_mfma_f32_16x16x32_bf16 v[140:143], v[128:131], v[168:171], v[140:143]
	v_mfma_f32_16x16x32_bf16 v[112:115], v[128:131], v[176:179], v[112:115]
	v_mfma_f32_16x16x32_bf16 v[112:115], v[124:127], v[172:175], v[112:115]
	v_mfma_f32_16x16x32_bf16 v[96:99], v[124:127], v[180:183], v[96:99]
	v_mfma_f32_16x16x32_bf16 v[96:99], v[128:131], v[184:187], v[96:99]
	v_mfma_f32_16x16x32_bf16 v[80:83], v[128:131], v[214:217], v[80:83]
	v_mfma_f32_16x16x32_bf16 v[80:83], v[124:127], v[188:191], v[80:83]
	v_mfma_f32_16x16x32_bf16 v[76:79], v[132:135], v[188:191], v[76:79]
	v_mfma_f32_16x16x32_bf16 v[76:79], v[144:147], v[214:217], v[76:79]
	v_mfma_f32_16x16x32_bf16 v[92:95], v[144:147], v[184:187], v[92:95]
	v_mfma_f32_16x16x32_bf16 v[92:95], v[132:135], v[180:183], v[92:95]
	v_mfma_f32_16x16x32_bf16 v[108:111], v[132:135], v[172:175], v[108:111]
	v_mfma_f32_16x16x32_bf16 v[108:111], v[144:147], v[176:179], v[108:111]
	v_mfma_f32_16x16x32_bf16 v[136:139], v[144:147], v[168:171], v[136:139]
	v_mfma_f32_16x16x32_bf16 v[136:139], v[132:135], v[164:167], v[136:139]
	v_mfma_f32_16x16x32_bf16 v[120:123], v[148:151], v[164:167], v[120:123]
	v_mfma_f32_16x16x32_bf16 v[120:123], v[152:155], v[168:171], v[120:123]
	v_mfma_f32_16x16x32_bf16 v[104:107], v[152:155], v[176:179], v[104:107]
	v_mfma_f32_16x16x32_bf16 v[104:107], v[148:151], v[172:175], v[104:107]
	v_mfma_f32_16x16x32_bf16 v[88:91], v[148:151], v[180:183], v[88:91]
	v_mfma_f32_16x16x32_bf16 v[88:91], v[152:155], v[184:187], v[88:91]
	v_mfma_f32_16x16x32_bf16 v[72:75], v[152:155], v[214:217], v[72:75]
	v_mfma_f32_16x16x32_bf16 v[72:75], v[148:151], v[188:191], v[72:75]
	v_mfma_f32_16x16x32_bf16 v[68:71], v[156:159], v[188:191], v[68:71]
	v_mfma_f32_16x16x32_bf16 v[68:71], v[160:163], v[214:217], v[68:71]
	v_mfma_f32_16x16x32_bf16 v[84:87], v[160:163], v[184:187], v[84:87]
	v_mfma_f32_16x16x32_bf16 v[84:87], v[156:159], v[180:183], v[84:87]
	v_mfma_f32_16x16x32_bf16 v[100:103], v[156:159], v[172:175], v[100:103]
	v_mfma_f32_16x16x32_bf16 v[100:103], v[160:163], v[176:179], v[100:103]
	v_mfma_f32_16x16x32_bf16 v[116:119], v[160:163], v[168:171], v[116:119]
	v_mfma_f32_16x16x32_bf16 v[116:119], v[156:159], v[164:167], v[116:119]
	s_setprio 0
	s_barrier
	s_add_i32 s36, s56, s40
	v_lshl_add_u64 v[218:219], v[218:219], 0, s[84:85]
	s_mov_b32 m0, s36
	ds_read_b128 v[164:167], v242 offset:49152
	ds_read_b128 v[168:171], v242 offset:50176
	ds_read_b128 v[172:175], v242 offset:51200
	ds_read_b128 v[176:179], v242 offset:52224
	ds_read_b128 v[180:183], v242 offset:53248
	ds_read_b128 v[184:187], v242 offset:54272
	ds_read_b128 v[188:191], v242 offset:55296
	ds_read_b128 v[214:217], v242 offset:56320
	global_load_lds_dwordx4 v[218:219], off
	s_add_i32 m0, s36, 0x2000
	s_add_u32 s26, s26, 0x100080
	v_lshl_add_u64 v[218:219], v[220:221], 0, s[84:85]
	s_addc_u32 s27, s27, 0
	s_add_i32 s36, s57, s40
	global_load_lds_dwordx4 v[218:219], off
	v_lshl_add_u64 v[218:219], s[26:27], 0, v[2:3]
	s_mov_b32 m0, s36
	s_nop 0
	global_load_lds_dwordx4 v[218:219], off
	v_lshl_add_u64 v[218:219], s[26:27], 0, v[204:205]
	s_add_i32 m0, s36, 0x2000
	s_nop 0
	global_load_lds_dwordx4 v[218:219], off
	s_cmp_eq_u32 s55, 60
	s_cbranch_scc0 .Ldefer_1456_peel
	v_lshl_add_u64 v[218:219], v[222:223], 0, s[84:85]
	s_mov_b32 m0, s45
	s_nop 0
	global_load_lds_dwordx4 v[218:219], off
	v_lshl_add_u64 v[218:219], v[224:225], 0, s[84:85]
	s_mov_b32 m0, s46
	s_nop 0
	global_load_lds_dwordx4 v[218:219], off

; #define PG8_STAGE(bufoff, gbase, voff) do { _Pragma("unroll") for (int _i = 0; _i < 2; ++_i) \
;         __builtin_amdgcn_global_load_lds((const unsigned*)((const char*)(gbase) + (voff)[_i]), (PG8_LAS unsigned*)(lds + (bufoff) + ldsw + _i * 8192), 16, 0, 0); } while (0)
; #define PG8_LDA(dst, b, h) do { _Pragma("unroll") for (int m = 0; m < 4; ++m) _Pragma("unroll") for (int k = 0; k < 2; ++k) dst[m][k] = *(const PG8_LAS bf16x8*)(lds + PG8_SA(b, h) + aoff + m * 2048 + k * 1024); } while (0)
; #define PG8_LDB(dst, b, h) do { _Pragma("unroll") for (int n = 0; n < 2; ++n) _Pragma("unroll") for (int k = 0; k < 2; ++k) dst[n][k] = *(const PG8_LAS bf16x8*)(lds + PG8_SB(b, h) + boff + n * 2048 + k * 1024); } while (0)
; #define PG8_WAIT_V(n) asm volatile("s_waitcnt vmcnt(" #n ")" ::: "memory")
; #define PG8_WAIT_L(n) asm volatile("s_waitcnt lgkmcnt(" #n ")" ::: "memory")
; #define PG8_BAR __builtin_amdgcn_s_barrier()
; #define PG8_SCHED __builtin_amdgcn_sched_barrier(0)
; template <class Epi, class Sched, bool ALIGN_EPI = false, bool SP2 = false, bool I8 = false>
; __device__ __forceinline__ void gemm_phase(PG8_LAS unsigned char* lds, const Gemm g, const Sched& S, const Epi& E) {
;     ...
;             if constexpr (SP2) {
;             PG8_LDB(B0, 0, 0); PG8_LDB(B1, 0, 1); PG8_SCHED; PG8_LDA(At, 0, 0); PG8_STAGE(PG8_SA(1, 1), a1 + hstep, voffA);
;             PG8_WAIT_V(8); PG8_WAIT_L(0); PG8_BAR; PG8_MMA(0, 0, At, B0); PG8_MMA(0, 1, At, B1); PG8_BAR; PG8_SCHED;
;             PG8_LDA(At, 0, 1); PG8_STAGE(PG8_SB(0, 0), b2, voffB); PG8_STAGE(PG8_SB(0, 1), b2 + hstep, voffB); PG8_STAGE(PG8_SA(0, 0), a2, voffA);
;             PG8_WAIT_V(8); PG8_WAIT_L(0); PG8_BAR; PG8_MMA(1, 0, At, B0); PG8_MMA(1, 1, At, B1); PG8_BAR; PG8_SCHED;
.LBB0_1456:
	s_add_u32 s26, s24, 0xfff00080
	s_addc_u32 s27, s25, -1
	s_add_i32 s56, 0, 0x10000
	s_cmp_eq_u32 s55, 60
	s_cselect_b32 s37, s17, s27
	s_cselect_b32 s36, s51, s26
	s_cselect_b32 s27, s19, s54
	s_cselect_b32 s26, s52, s53
	s_add_i32 s58, 0, 0x14000
	v_add_u32_e32 v144, s56, v240
	v_add_u32_e32 v160, s58, v240
	ds_read_b128 v[124:127], v144
	ds_read_b128 v[128:131], v144 offset:1024
	ds_read_b128 v[132:135], v144 offset:2048
	ds_read_b128 v[144:147], v144 offset:3072
	ds_read_b128 v[148:151], v160
	ds_read_b128 v[152:155], v160 offset:1024
	ds_read_b128 v[156:159], v160 offset:2048
	ds_read_b128 v[160:163], v160 offset:3072
	ds_read_b128 v[164:167], v242
	ds_read_b128 v[168:171], v242 offset:1024
	ds_read_b128 v[172:175], v242 offset:2048
	ds_read_b128 v[176:179], v242 offset:3072
	ds_read_b128 v[180:183], v242 offset:4096
	ds_read_b128 v[184:187], v242 offset:5120
	ds_read_b128 v[188:191], v242 offset:6144
	ds_read_b128 v[214:217], v242 offset:7168
	v_lshl_add_u64 v[218:219], v[222:223], 0, s[84:85]
	s_mov_b32 m0, s45
	s_nop 0
	global_load_lds_dwordx4 v[218:219], off
	v_lshl_add_u64 v[218:219], v[224:225], 0, s[84:85]
	s_mov_b32 m0, s46
	s_nop 0
	global_load_lds_dwordx4 v[218:219], off
	v_lshl_add_u64 v[218:219], s[24:25], 0, v[210:211]
	s_add_i32 m0, s41, 0xc000
	s_nop 0
	global_load_lds_dwordx4 v[218:219], off
	v_lshl_add_u64 v[218:219], s[24:25], 0, v[212:213]
	s_add_i32 m0, s41, 0xe000
	s_nop 0
	global_load_lds_dwordx4 v[218:219], off
	s_waitcnt vmcnt(8)
	s_waitcnt lgkmcnt(0)
	s_barrier
	s_setprio 1
	s_waitcnt lgkmcnt(0)
	v_mfma_f32_16x16x32_bf16 v[140:143], v[124:127], v[164:167], v[140:143]
	v_mfma_f32_16x16x32_bf16 v[140:143], v[128:131], v[168:171], v[140:143]
	v_mfma_f32_16x16x32_bf16 v[112:115], v[128:131], v[176:179], v[112:115]
	v_mfma_f32_16x16x32_bf16 v[112:115], v[124:127], v[172:175], v[112:115]
	v_mfma_f32_16x16x32_bf16 v[96:99], v[124:127], v[180:183], v[96:99]
	v_mfma_f32_16x16x32_bf16 v[96:99], v[128:131], v[184:187], v[96:99]
	v_mfma_f32_16x16x32_bf16 v[80:83], v[128:131], v[214:217], v[80:83]
	v_mfma_f32_16x16x32_bf16 v[80:83], v[124:127], v[188:191], v[80:83]
	v_mfma_f32_16x16x32_bf16 v[76:79], v[132:135], v[188:191], v[76:79]
	v_mfma_f32_16x16x32_bf16 v[76:79], v[144:147], v[214:217], v[76:79]
	v_mfma_f32_16x16x32_bf16 v[92:95], v[144:147], v[184:187], v[92:95]
	v_mfma_f32_16x16x32_bf16 v[92:95], v[132:135], v[180:183], v[92:95]
	v_mfma_f32_16x16x32_bf16 v[108:111], v[132:135], v[172:175], v[108:111]
	v_mfma_f32_16x16x32_bf16 v[108:111], v[144:147], v[176:179], v[108:111]
	v_mfma_f32_16x16x32_bf16 v[136:139], v[144:147], v[168:171], v[136:139]
	v_mfma_f32_16x16x32_bf16 v[136:139], v[132:135], v[164:167], v[136:139]
	v_mfma_f32_16x16x32_bf16 v[120:123], v[148:151], v[164:167], v[120:123]
	v_mfma_f32_16x16x32_bf16 v[120:123], v[152:155], v[168:171], v[120:123]
	v_mfma_f32_16x16x32_bf16 v[104:107], v[152:155], v[176:179], v[104:107]
	v_mfma_f32_16x16x32_bf16 v[104:107], v[148:151], v[172:175], v[104:107]
	v_mfma_f32_16x16x32_bf16 v[88:91], v[148:151], v[180:183], v[88:91]
	v_mfma_f32_16x16x32_bf16 v[88:91], v[152:155], v[184:187], v[88:91]
	v_mfma_f32_16x16x32_bf16 v[72:75], v[152:155], v[214:217], v[72:75]
	v_mfma_f32_16x16x32_bf16 v[72:75], v[148:151], v[188:191], v[72:75]
	v_mfma_f32_16x16x32_bf16 v[68:71], v[156:159], v[188:191], v[68:71]
	v_mfma_f32_16x16x32_bf16 v[68:71], v[160:163], v[214:217], v[68:71]
	v_mfma_f32_16x16x32_bf16 v[84:87], v[160:163], v[184:187], v[84:87]
	v_mfma_f32_16x16x32_bf16 v[84:87], v[156:159], v[180:183], v[84:87]
	v_mfma_f32_16x16x32_bf16 v[100:103], v[156:159], v[172:175], v[100:103]
	v_mfma_f32_16x16x32_bf16 v[100:103], v[160:163], v[176:179], v[100:103]
	v_mfma_f32_16x16x32_bf16 v[116:119], v[160:163], v[168:171], v[116:119]
	v_mfma_f32_16x16x32_bf16 v[116:119], v[156:159], v[164:167], v[116:119]
	s_setprio 0
	s_barrier
	s_add_i32 s56, s56, s40
	v_lshl_add_u64 v[218:219], s[26:27], 0, v[2:3]
	s_mov_b32 m0, s56
	ds_read_b128 v[164:167], v242 offset:16384
	ds_read_b128 v[168:171], v242 offset:17408
	ds_read_b128 v[172:175], v242 offset:18432
	ds_read_b128 v[176:179], v242 offset:19456
	ds_read_b128 v[180:183], v242 offset:20480
	ds_read_b128 v[184:187], v242 offset:21504
	ds_read_b128 v[188:191], v242 offset:22528
	ds_read_b128 v[214:217], v242 offset:23552
	global_load_lds_dwordx4 v[218:219], off
	s_add_i32 m0, s56, 0x2000
	s_add_u32 s56, s26, 0x100000
	v_lshl_add_u64 v[220:221], s[26:27], 0, v[204:205]
	s_addc_u32 s57, s27, 0
	s_add_i32 s58, s58, s40
	global_load_lds_dwordx4 v[220:221], off
	v_lshl_add_u64 v[222:223], s[56:57], 0, v[2:3]
	s_mov_b32 m0, s58
	v_lshl_add_u64 v[224:225], s[36:37], 0, v[206:207]
	global_load_lds_dwordx4 v[222:223], off
	v_lshl_add_u64 v[222:223], s[56:57], 0, v[204:205]
	s_add_i32 m0, s58, 0x2000
	s_nop 0
	global_load_lds_dwordx4 v[222:223], off
	v_lshl_add_u64 v[222:223], s[36:37], 0, v[208:209]
	s_waitcnt vmcnt(6)
	s_waitcnt lgkmcnt(0)
	s_barrier
; #define PG8_STAGE(bufoff, gbase, voff) do { _Pragma("unroll") for (int _i = 0; _i < 2; ++_i) \
;         __builtin_amdgcn_global_load_lds((const unsigned*)((const char*)(gbase) + (voff)[_i]), (PG8_LAS unsigned*)(lds + (bufoff) + ldsw + _i * 8192), 16, 0, 0); } while (0)
; #define PG8_LDA(dst, b, h) do { _Pragma("unroll") for (int m = 0; m < 4; ++m) _Pragma("unroll") for (int k = 0; k < 2; ++k) dst[m][k] = *(const PG8_LAS bf16x8*)(lds + PG8_SA(b, h) + aoff + m * 2048 + k * 1024); } while (0)
; #define PG8_LDB(dst, b, h) do { _Pragma("unroll") for (int n = 0; n < 2; ++n) _Pragma("unroll") for (int k = 0; k < 2; ++k) dst[n][k] = *(const PG8_LAS bf16x8*)(lds + PG8_SB(b, h) + boff + n * 2048 + k * 1024); } while (0)
; #define PG8_WAIT_V(n) asm volatile("s_waitcnt vmcnt(" #n ")" ::: "memory")
; #define PG8_WAIT_L(n) asm volatile("s_waitcnt lgkmcnt(" #n ")" ::: "memory")
; #define PG8_BAR __builtin_amdgcn_s_barrier()
; #define PG8_SCHED __builtin_amdgcn_sched_barrier(0)
; template <class Epi, class Sched, bool ALIGN_EPI = false, bool SP2 = false, bool I8 = false>
; __device__ __forceinline__ void gemm_phase(PG8_LAS unsigned char* lds, const Gemm g, const Sched& S, const Epi& E) {
;     ...
;             PG8_WAIT_V(8); PG8_WAIT_L(0); PG8_BAR; PG8_MMA(1, 0, At, B0); PG8_MMA(1, 1, At, B1); PG8_BAR; PG8_SCHED;
;             PG8_LDB(B0, 1, 0); PG8_LDB(B1, 1, 1); PG8_SCHED; PG8_LDA(At, 1, 0); PG8_STAGE(PG8_SA(0, 1), a2 + hstep, voffA);
;             PG8_WAIT_V(8); PG8_WAIT_L(0); PG8_BAR; PG8_MMA(0, 0, At, B0); PG8_MMA(0, 1, At, B1); PG8_BAR; PG8_SCHED;
	s_setprio 1
	s_waitcnt lgkmcnt(0)
	v_mfma_f32_16x16x32_bf16 v[64:67], v[124:127], v[164:167], v[64:67]
	v_mfma_f32_16x16x32_bf16 v[64:67], v[128:131], v[168:171], v[64:67]
	v_mfma_f32_16x16x32_bf16 v[48:51], v[128:131], v[176:179], v[48:51]
	v_mfma_f32_16x16x32_bf16 v[48:51], v[124:127], v[172:175], v[48:51]
	v_mfma_f32_16x16x32_bf16 v[32:35], v[124:127], v[180:183], v[32:35]
	v_mfma_f32_16x16x32_bf16 v[32:35], v[128:131], v[184:187], v[32:35]
	v_mfma_f32_16x16x32_bf16 v[16:19], v[128:131], v[214:217], v[16:19]
	v_mfma_f32_16x16x32_bf16 v[16:19], v[124:127], v[188:191], v[16:19]
	v_mfma_f32_16x16x32_bf16 v[12:15], v[132:135], v[188:191], v[12:15]
	v_mfma_f32_16x16x32_bf16 v[12:15], v[144:147], v[214:217], v[12:15]
	v_mfma_f32_16x16x32_bf16 v[28:31], v[144:147], v[184:187], v[28:31]
	v_mfma_f32_16x16x32_bf16 v[28:31], v[132:135], v[180:183], v[28:31]
	v_mfma_f32_16x16x32_bf16 v[44:47], v[132:135], v[172:175], v[44:47]
	v_mfma_f32_16x16x32_bf16 v[44:47], v[144:147], v[176:179], v[44:47]
	v_mfma_f32_16x16x32_bf16 v[60:63], v[144:147], v[168:171], v[60:63]
	v_mfma_f32_16x16x32_bf16 v[60:63], v[132:135], v[164:167], v[60:63]
	v_mfma_f32_16x16x32_bf16 v[56:59], v[148:151], v[164:167], v[56:59]
	v_mfma_f32_16x16x32_bf16 v[56:59], v[152:155], v[168:171], v[56:59]
	v_mfma_f32_16x16x32_bf16 v[40:43], v[152:155], v[176:179], v[40:43]
	v_mfma_f32_16x16x32_bf16 v[40:43], v[148:151], v[172:175], v[40:43]
	v_mfma_f32_16x16x32_bf16 v[24:27], v[148:151], v[180:183], v[24:27]
	v_mfma_f32_16x16x32_bf16 v[24:27], v[152:155], v[184:187], v[24:27]
	v_mfma_f32_16x16x32_bf16 v[8:11], v[152:155], v[214:217], v[8:11]
	v_mfma_f32_16x16x32_bf16 v[8:11], v[148:151], v[188:191], v[8:11]
	v_mfma_f32_16x16x32_bf16 v[4:7], v[156:159], v[188:191], v[4:7]
	v_mfma_f32_16x16x32_bf16 v[4:7], v[160:163], v[214:217], v[4:7]
	v_mfma_f32_16x16x32_bf16 v[20:23], v[160:163], v[184:187], v[20:23]
	v_mfma_f32_16x16x32_bf16 v[20:23], v[156:159], v[180:183], v[20:23]
	v_mfma_f32_16x16x32_bf16 v[36:39], v[156:159], v[172:175], v[36:39]
	v_mfma_f32_16x16x32_bf16 v[36:39], v[160:163], v[176:179], v[36:39]
	v_mfma_f32_16x16x32_bf16 v[52:55], v[160:163], v[168:171], v[52:55]
	v_mfma_f32_16x16x32_bf16 v[52:55], v[156:159], v[164:167], v[52:55]
	s_setprio 0
	s_barrier
	s_add_i32 s56, 0, 0x18000
	s_add_i32 s57, 0, 0x1c000
	v_add_u32_e32 v144, s56, v240
	v_add_u32_e32 v160, s57, v240
	ds_read_b128 v[124:127], v144
	ds_read_b128 v[128:131], v144 offset:1024
	ds_read_b128 v[132:135], v144 offset:2048
	ds_read_b128 v[144:147], v144 offset:3072
	ds_read_b128 v[148:151], v160
	ds_read_b128 v[152:155], v160 offset:1024
	ds_read_b128 v[156:159], v160 offset:2048
	ds_read_b128 v[160:163], v160 offset:3072
	s_add_u32 s36, s36, 0x100000
	s_addc_u32 s37, s37, 0
	s_mov_b32 m0, s43
	v_lshl_add_u64 v[226:227], s[36:37], 0, v[208:209]
	ds_read_b128 v[164:167], v242 offset:32768
	ds_read_b128 v[168:171], v242 offset:33792
	ds_read_b128 v[172:175], v242 offset:34816
	ds_read_b128 v[176:179], v242 offset:35840
	ds_read_b128 v[180:183], v242 offset:36864
	ds_read_b128 v[184:187], v242 offset:37888
	ds_read_b128 v[188:191], v242 offset:38912
	ds_read_b128 v[214:217], v242 offset:39936
	s_mov_b32 m0, s41
	s_nop 0
	global_load_lds_dwordx4 v[222:223], off
	s_mov_b32 m0, s42
	s_nop 0
	global_load_lds_dwordx4 v[224:225], off
	s_mov_b32 m0, s43
	s_nop 0
	global_load_lds_dwordx4 v[226:227], off
	v_lshl_add_u64 v[226:227], s[36:37], 0, v[206:207]
	s_mov_b32 m0, s44
	s_nop 0
	global_load_lds_dwordx4 v[226:227], off
	s_waitcnt vmcnt(8)
	s_waitcnt lgkmcnt(0)
	s_barrier
; #define PG8_STAGE(bufoff, gbase, voff) do { _Pragma("unroll") for (int _i = 0; _i < 2; ++_i) \
;         __builtin_amdgcn_global_load_lds((const unsigned*)((const char*)(gbase) + (voff)[_i]), (PG8_LAS unsigned*)(lds + (bufoff) + ldsw + _i * 8192), 16, 0, 0); } while (0)
; #define PG8_LDA(dst, b, h) do { _Pragma("unroll") for (int m = 0; m < 4; ++m) _Pragma("unroll") for (int k = 0; k < 2; ++k) dst[m][k] = *(const PG8_LAS bf16x8*)(lds + PG8_SA(b, h) + aoff + m * 2048 + k * 1024); } while (0)
; #define PG8_WAIT_V(n) asm volatile("s_waitcnt vmcnt(" #n ")" ::: "memory")
; #define PG8_WAIT_L(n) asm volatile("s_waitcnt lgkmcnt(" #n ")" ::: "memory")
; #define PG8_BAR __builtin_amdgcn_s_barrier()
; #define PG8_SCHED __builtin_amdgcn_sched_barrier(0)
; template <class Epi, class Sched, bool ALIGN_EPI = false, bool SP2 = false, bool I8 = false>
; __device__ __forceinline__ void gemm_phase(PG8_LAS unsigned char* lds, const Gemm g, const Sched& S, const Epi& E) {
;     ...
;             PG8_WAIT_V(8); PG8_WAIT_L(0); PG8_BAR; PG8_MMA(0, 0, At, B0); PG8_MMA(0, 1, At, B1); PG8_BAR; PG8_SCHED;
;             PG8_LDA(At, 1, 1); PG8_STAGE(PG8_SB(1, 0), b3, voffB); PG8_STAGE(PG8_SB(1, 1), b3 + hstep, voffB); PG8_STAGE(PG8_SA(1, 0), a3, voffA);
	s_setprio 1
	s_waitcnt lgkmcnt(0)
	v_mfma_f32_16x16x32_bf16 v[140:143], v[124:127], v[164:167], v[140:143]
	v_mfma_f32_16x16x32_bf16 v[140:143], v[128:131], v[168:171], v[140:143]
	v_mfma_f32_16x16x32_bf16 v[112:115], v[128:131], v[176:179], v[112:115]
	v_mfma_f32_16x16x32_bf16 v[112:115], v[124:127], v[172:175], v[112:115]
	v_mfma_f32_16x16x32_bf16 v[96:99], v[124:127], v[180:183], v[96:99]
	v_mfma_f32_16x16x32_bf16 v[96:99], v[128:131], v[184:187], v[96:99]
	v_mfma_f32_16x16x32_bf16 v[80:83], v[128:131], v[214:217], v[80:83]
	v_mfma_f32_16x16x32_bf16 v[80:83], v[124:127], v[188:191], v[80:83]
	v_mfma_f32_16x16x32_bf16 v[76:79], v[132:135], v[188:191], v[76:79]
	v_mfma_f32_16x16x32_bf16 v[76:79], v[144:147], v[214:217], v[76:79]
	v_mfma_f32_16x16x32_bf16 v[92:95], v[144:147], v[184:187], v[92:95]
	v_mfma_f32_16x16x32_bf16 v[92:95], v[132:135], v[180:183], v[92:95]
	v_mfma_f32_16x16x32_bf16 v[108:111], v[132:135], v[172:175], v[108:111]
	v_mfma_f32_16x16x32_bf16 v[108:111], v[144:147], v[176:179], v[108:111]
	v_mfma_f32_16x16x32_bf16 v[136:139], v[144:147], v[168:171], v[136:139]
	v_mfma_f32_16x16x32_bf16 v[136:139], v[132:135], v[164:167], v[136:139]
	v_mfma_f32_16x16x32_bf16 v[120:123], v[148:151], v[164:167], v[120:123]
	v_mfma_f32_16x16x32_bf16 v[120:123], v[152:155], v[168:171], v[120:123]
	v_mfma_f32_16x16x32_bf16 v[104:107], v[152:155], v[176:179], v[104:107]
	v_mfma_f32_16x16x32_bf16 v[104:107], v[148:151], v[172:175], v[104:107]
	v_mfma_f32_16x16x32_bf16 v[88:91], v[148:151], v[180:183], v[88:91]
	v_mfma_f32_16x16x32_bf16 v[88:91], v[152:155], v[184:187], v[88:91]
	v_mfma_f32_16x16x32_bf16 v[72:75], v[152:155], v[214:217], v[72:75]
	v_mfma_f32_16x16x32_bf16 v[72:75], v[148:151], v[188:191], v[72:75]
	v_mfma_f32_16x16x32_bf16 v[68:71], v[156:159], v[188:191], v[68:71]
	v_mfma_f32_16x16x32_bf16 v[68:71], v[160:163], v[214:217], v[68:71]
	v_mfma_f32_16x16x32_bf16 v[84:87], v[160:163], v[184:187], v[84:87]
	v_mfma_f32_16x16x32_bf16 v[84:87], v[156:159], v[180:183], v[84:87]
	v_mfma_f32_16x16x32_bf16 v[100:103], v[156:159], v[172:175], v[100:103]
	v_mfma_f32_16x16x32_bf16 v[100:103], v[160:163], v[176:179], v[100:103]
	v_mfma_f32_16x16x32_bf16 v[116:119], v[160:163], v[168:171], v[116:119]
	v_mfma_f32_16x16x32_bf16 v[116:119], v[156:159], v[164:167], v[116:119]
	s_setprio 0
	s_barrier
	s_add_i32 s36, s56, s40
	v_lshl_add_u64 v[218:219], v[218:219], 0, s[84:85]
	s_mov_b32 m0, s36
	ds_read_b128 v[164:167], v242 offset:49152
	ds_read_b128 v[168:171], v242 offset:50176
	ds_read_b128 v[172:175], v242 offset:51200
	ds_read_b128 v[176:179], v242 offset:52224
	ds_read_b128 v[180:183], v242 offset:53248
	ds_read_b128 v[184:187], v242 offset:54272
	ds_read_b128 v[188:191], v242 offset:55296
	ds_read_b128 v[214:217], v242 offset:56320
	global_load_lds_dwordx4 v[218:219], off
	s_add_i32 m0, s36, 0x2000
	s_add_u32 s26, s26, 0x100080
	v_lshl_add_u64 v[218:219], v[220:221], 0, s[84:85]
	s_addc_u32 s27, s27, 0
	s_add_i32 s36, s57, s40
	global_load_lds_dwordx4 v[218:219], off
	v_lshl_add_u64 v[218:219], s[26:27], 0, v[2:3]
	s_mov_b32 m0, s36
	s_nop 0
	global_load_lds_dwordx4 v[218:219], off
	v_lshl_add_u64 v[218:219], s[26:27], 0, v[204:205]
	s_add_i32 m0, s36, 0x2000
	s_nop 0
	global_load_lds_dwordx4 v[218:219], off
	s_cmp_eq_u32 s55, 60
	s_cbranch_scc0 .Ldefer_1456_body
	v_lshl_add_u64 v[218:219], v[222:223], 0, s[84:85]
	s_mov_b32 m0, s45
	s_nop 0
	global_load_lds_dwordx4 v[218:219], off
	v_lshl_add_u64 v[218:219], v[224:225], 0, s[84:85]
	s_mov_b32 m0, s46
	s_nop 0
	global_load_lds_dwordx4 v[218:219], off

; #define PG8_STAGE(bufoff, gbase, voff) do { _Pragma("unroll") for (int _i = 0; _i < 2; ++_i) \
;         __builtin_amdgcn_global_load_lds((const unsigned*)((const char*)(gbase) + (voff)[_i]), (PG8_LAS unsigned*)(lds + (bufoff) + ldsw + _i * 8192), 16, 0, 0); } while (0)
; #define PG8_LDA(dst, b, h) do { _Pragma("unroll") for (int m = 0; m < 4; ++m) _Pragma("unroll") for (int k = 0; k < 2; ++k) dst[m][k] = *(const PG8_LAS bf16x8*)(lds + PG8_SA(b, h) + aoff + m * 2048 + k * 1024); } while (0)
; #define PG8_LDB(dst, b, h) do { _Pragma("unroll") for (int n = 0; n < 2; ++n) _Pragma("unroll") for (int k = 0; k < 2; ++k) dst[n][k] = *(const PG8_LAS bf16x8*)(lds + PG8_SB(b, h) + boff + n * 2048 + k * 1024); } while (0)
; #define PG8_WAIT_V(n) asm volatile("s_waitcnt vmcnt(" #n ")" ::: "memory")
; #define PG8_WAIT_L(n) asm volatile("s_waitcnt lgkmcnt(" #n ")" ::: "memory")
; #define PG8_BAR __builtin_amdgcn_s_barrier()
; #define PG8_SCHED __builtin_amdgcn_sched_barrier(0)
; template <class Epi, class Sched, bool ALIGN_EPI = false, bool SP2 = false, bool I8 = false>
; __device__ __forceinline__ void gemm_phase(PG8_LAS unsigned char* lds, const Gemm g, const Sched& S, const Epi& E) {
;     ...
;     for (;;) {
;         const bool has_next = S.next(ui + 1, nxt);
;         const char* nA = has_next ? (const char*)g.A + (size_t)nxt.pm * tstep : cA; const char* nB = has_next ? (const char*)g.Bt + (size_t)nxt.pn * tstep : cB;
;         for (int t = 0; t < nt; t += 2) {
;             const bool last = (t == nt - 2);
;             const char* a1 = cA + (size_t)(t + 1) * kstep;
;             const char* a2 = last ? nA : cA + (size_t)(t + 2) * kstep; const char* b2 = last ? nB : cB + (size_t)(t + 2) * kstep;
;             const char* a3 = a2 + kstep; const char* b3 = b2 + kstep;
;             if (last && has_next) S.a_ready(nxt);
;             if constexpr (SP2) {
;             PG8_LDB(B0, 0, 0); PG8_LDB(B1, 0, 1); PG8_SCHED; PG8_LDA(At, 0, 0); PG8_STAGE(PG8_SA(1, 1), a1 + hstep, voffA);
;             PG8_WAIT_V(8); PG8_WAIT_L(0); PG8_BAR; PG8_MMA(0, 0, At, B0); PG8_MMA(0, 1, At, B1); PG8_BAR; PG8_SCHED;
;             PG8_LDA(At, 0, 1); PG8_STAGE(PG8_SB(0, 0), b2, voffB); PG8_STAGE(PG8_SB(0, 1), b2 + hstep, voffB); PG8_STAGE(PG8_SA(0, 0), a2, voffA);
.LBB0_1590:
	s_ashr_i32 s25, s24, 31
	s_lshl_b64 s[26:27], s[24:25], 20
	s_add_u32 s26, s28, s26
	s_addc_u32 s27, s42, s27
	s_and_b64 s[36:37], s[10:11], exec
	s_cselect_b32 s25, s27, s41
	s_cselect_b32 s57, s26, s40
	s_ashr_i32 s23, s22, 31
	s_lshl_b64 s[36:37], s[22:23], 20
	s_add_u32 s36, s43, s36
	s_addc_u32 s37, s46, s37
	s_and_b64 s[48:49], s[10:11], exec
	s_cselect_b32 s23, s37, s45
	s_cselect_b32 s58, s36, s44
	s_add_u32 s40, s40, 0x80080
	s_addc_u32 s41, s41, 0
	s_add_u32 s59, s44, 0x100
	s_addc_u32 s60, s45, 0
	s_mov_b32 s61, -2
	s_add_u32 s44, s40, 0xfff80080
	s_addc_u32 s45, s41, -1
	s_add_i32 s64, 0, 0x10000
	s_cmp_eq_u32 s61, 28
	s_cselect_b32 s49, s25, s45
	s_cselect_b32 s48, s57, s44
	s_cselect_b32 s45, s23, s60
	s_cselect_b32 s44, s58, s59
	s_add_i32 s67, 0, 0x14000
	v_add_u32_e32 v144, s64, v167
	v_add_u32_e32 v158, s67, v167
	ds_read_b128 v[36:39], v144
	ds_read_b128 v[44:47], v144 offset:1024
	ds_read_b128 v[140:143], v144 offset:2048
	ds_read_b128 v[144:147], v144 offset:3072
	ds_read_b128 v[160:163], v158
	ds_read_b128 v[172:175], v158 offset:1024
	ds_read_b128 v[176:179], v158 offset:2048
	ds_read_b128 v[180:183], v158 offset:3072
	v_lshl_add_u64 v[164:165], s[40:41], 0, v[154:155]
	s_add_i32 m0, s50, 0xc000
	ds_read_b128 v[184:187], v171
	ds_read_b128 v[188:191], v171 offset:1024
	ds_read_b128 v[204:207], v171 offset:2048
	ds_read_b128 v[208:211], v171 offset:3072
	ds_read_b128 v[212:215], v171 offset:4096
	ds_read_b128 v[216:219], v171 offset:5120
	ds_read_b128 v[220:223], v171 offset:6144
	ds_read_b128 v[224:227], v171 offset:7168
	global_load_lds_dwordx4 v[164:165], off
	v_lshl_add_u64 v[164:165], s[40:41], 0, v[156:157]
	s_add_i32 m0, s50, 0xe000
	s_nop 0
	global_load_lds_dwordx4 v[164:165], off
	s_waitcnt vmcnt(8)
	s_waitcnt lgkmcnt(0)
	s_barrier
	s_setprio 1
	s_waitcnt lgkmcnt(0)
	v_mfma_i32_16x16x64_i8 v[136:139], v[36:39], v[184:187], 0
	v_mfma_i32_16x16x64_i8 v[136:139], v[44:47], v[188:191], v[136:139]
	v_mfma_i32_16x16x64_i8 v[120:123], v[44:47], v[208:211], 0
	v_mfma_i32_16x16x64_i8 v[120:123], v[36:39], v[204:207], v[120:123]
	v_mfma_i32_16x16x64_i8 v[104:107], v[36:39], v[212:215], 0
	v_mfma_i32_16x16x64_i8 v[104:107], v[44:47], v[216:219], v[104:107]
	v_mfma_i32_16x16x64_i8 v[88:91], v[44:47], v[224:227], 0
	v_mfma_i32_16x16x64_i8 v[88:91], v[36:39], v[220:223], v[88:91]
	v_mfma_i32_16x16x64_i8 v[80:83], v[140:143], v[220:223], 0
	v_mfma_i32_16x16x64_i8 v[80:83], v[144:147], v[224:227], v[80:83]
	v_mfma_i32_16x16x64_i8 v[96:99], v[144:147], v[216:219], 0
	v_mfma_i32_16x16x64_i8 v[96:99], v[140:143], v[212:215], v[96:99]
	v_mfma_i32_16x16x64_i8 v[112:115], v[140:143], v[204:207], 0
	v_mfma_i32_16x16x64_i8 v[112:115], v[144:147], v[208:211], v[112:115]
	v_mfma_i32_16x16x64_i8 v[128:131], v[144:147], v[188:191], 0
	v_mfma_i32_16x16x64_i8 v[128:131], v[140:143], v[184:187], v[128:131]
	v_mfma_i32_16x16x64_i8 v[132:135], v[160:163], v[184:187], 0
	v_mfma_i32_16x16x64_i8 v[132:135], v[172:175], v[188:191], v[132:135]
	v_mfma_i32_16x16x64_i8 v[116:119], v[172:175], v[208:211], 0
	v_mfma_i32_16x16x64_i8 v[116:119], v[160:163], v[204:207], v[116:119]
	v_mfma_i32_16x16x64_i8 v[100:103], v[160:163], v[212:215], 0
	v_mfma_i32_16x16x64_i8 v[100:103], v[172:175], v[216:219], v[100:103]
	v_mfma_i32_16x16x64_i8 v[84:87], v[172:175], v[224:227], 0
	v_mfma_i32_16x16x64_i8 v[84:87], v[160:163], v[220:223], v[84:87]
	v_mfma_i32_16x16x64_i8 v[76:79], v[176:179], v[220:223], 0
	v_mfma_i32_16x16x64_i8 v[76:79], v[180:183], v[224:227], v[76:79]
	v_mfma_i32_16x16x64_i8 v[92:95], v[180:183], v[216:219], 0
	v_mfma_i32_16x16x64_i8 v[92:95], v[176:179], v[212:215], v[92:95]
	v_mfma_i32_16x16x64_i8 v[108:111], v[176:179], v[204:207], 0
	v_mfma_i32_16x16x64_i8 v[108:111], v[180:183], v[208:211], v[108:111]
	v_mfma_i32_16x16x64_i8 v[124:127], v[180:183], v[188:191], 0
	v_mfma_i32_16x16x64_i8 v[124:127], v[176:179], v[184:187], v[124:127]
	s_setprio 0
	s_barrier
	s_add_i32 s64, s64, s47
	v_lshl_add_u64 v[164:165], s[44:45], 0, v[2:3]
	s_mov_b32 m0, s64
	ds_read_b128 v[184:187], v171 offset:16384
	ds_read_b128 v[188:191], v171 offset:17408
	ds_read_b128 v[204:207], v171 offset:18432
	ds_read_b128 v[208:211], v171 offset:19456
	ds_read_b128 v[212:215], v171 offset:20480
	ds_read_b128 v[216:219], v171 offset:21504
	ds_read_b128 v[220:223], v171 offset:22528
	ds_read_b128 v[224:227], v171 offset:23552
	global_load_lds_dwordx4 v[164:165], off
	s_add_i32 m0, s64, 0x2000
	s_add_u32 s64, s44, 0x80000
	v_lshl_add_u64 v[228:229], s[44:45], 0, v[148:149]
	s_addc_u32 s65, s45, 0
	s_add_i32 s67, s67, s47
	global_load_lds_dwordx4 v[228:229], off
	v_lshl_add_u64 v[240:241], s[64:65], 0, v[2:3]
	s_mov_b32 m0, s67
	v_lshl_add_u64 v[242:243], s[48:49], 0, v[150:151]
	global_load_lds_dwordx4 v[240:241], off
	v_lshl_add_u64 v[240:241], s[64:65], 0, v[148:149]
	s_add_i32 m0, s67, 0x2000
	s_nop 0
	global_load_lds_dwordx4 v[240:241], off
	v_lshl_add_u64 v[240:241], s[48:49], 0, v[152:153]
	s_waitcnt vmcnt(6)
	s_waitcnt lgkmcnt(0)
	s_barrier
; #define PG8_STAGE(bufoff, gbase, voff) do { _Pragma("unroll") for (int _i = 0; _i < 2; ++_i) \
;         __builtin_amdgcn_global_load_lds((const unsigned*)((const char*)(gbase) + (voff)[_i]), (PG8_LAS unsigned*)(lds + (bufoff) + ldsw + _i * 8192), 16, 0, 0); } while (0)
; #define PG8_LDA(dst, b, h) do { _Pragma("unroll") for (int m = 0; m < 4; ++m) _Pragma("unroll") for (int k = 0; k < 2; ++k) dst[m][k] = *(const PG8_LAS bf16x8*)(lds + PG8_SA(b, h) + aoff + m * 2048 + k * 1024); } while (0)
; #define PG8_LDB(dst, b, h) do { _Pragma("unroll") for (int n = 0; n < 2; ++n) _Pragma("unroll") for (int k = 0; k < 2; ++k) dst[n][k] = *(const PG8_LAS bf16x8*)(lds + PG8_SB(b, h) + boff + n * 2048 + k * 1024); } while (0)
; #define PG8_WAIT_V(n) asm volatile("s_waitcnt vmcnt(" #n ")" ::: "memory")
; #define PG8_WAIT_L(n) asm volatile("s_waitcnt lgkmcnt(" #n ")" ::: "memory")
; #define PG8_BAR __builtin_amdgcn_s_barrier()
; #define PG8_SCHED __builtin_amdgcn_sched_barrier(0)
; template <class Epi, class Sched, bool ALIGN_EPI = false, bool SP2 = false, bool I8 = false>
; __device__ __forceinline__ void gemm_phase(PG8_LAS unsigned char* lds, const Gemm g, const Sched& S, const Epi& E) {
;     ...
;             PG8_WAIT_V(8); PG8_WAIT_L(0); PG8_BAR; PG8_MMA(1, 0, At, B0); PG8_MMA(1, 1, At, B1); PG8_BAR; PG8_SCHED;
;             PG8_LDB(B0, 1, 0); PG8_LDB(B1, 1, 1); PG8_SCHED; PG8_LDA(At, 1, 0); PG8_STAGE(PG8_SA(0, 1), a2 + hstep, voffA);
;             PG8_WAIT_V(8); PG8_WAIT_L(0); PG8_BAR; PG8_MMA(0, 0, At, B0); PG8_MMA(0, 1, At, B1); PG8_BAR; PG8_SCHED;
;             PG8_LDA(At, 1, 1); PG8_STAGE(PG8_SB(1, 0), b3, voffB); PG8_STAGE(PG8_SB(1, 1), b3 + hstep, voffB); PG8_STAGE(PG8_SA(1, 0), a3, voffA);
	s_setprio 1
	s_waitcnt lgkmcnt(0)
	v_mfma_i32_16x16x64_i8 v[72:75], v[36:39], v[184:187], 0
	v_mfma_i32_16x16x64_i8 v[72:75], v[44:47], v[188:191], v[72:75]
	v_mfma_i32_16x16x64_i8 v[56:59], v[44:47], v[208:211], 0
	v_mfma_i32_16x16x64_i8 v[56:59], v[36:39], v[204:207], v[56:59]
	v_mfma_i32_16x16x64_i8 v[32:35], v[36:39], v[212:215], 0
	v_mfma_i32_16x16x64_i8 v[32:35], v[44:47], v[216:219], v[32:35]
	v_mfma_i32_16x16x64_i8 v[16:19], v[44:47], v[224:227], 0
	v_mfma_i32_16x16x64_i8 v[16:19], v[36:39], v[220:223], v[16:19]
	v_mfma_i32_16x16x64_i8 v[8:11], v[140:143], v[220:223], 0
	v_mfma_i32_16x16x64_i8 v[8:11], v[144:147], v[224:227], v[8:11]
	v_mfma_i32_16x16x64_i8 v[24:27], v[144:147], v[216:219], 0
	v_mfma_i32_16x16x64_i8 v[24:27], v[140:143], v[212:215], v[24:27]
	v_mfma_i32_16x16x64_i8 v[48:51], v[140:143], v[204:207], 0
	v_mfma_i32_16x16x64_i8 v[48:51], v[144:147], v[208:211], v[48:51]
	v_mfma_i32_16x16x64_i8 v[64:67], v[144:147], v[188:191], 0
	v_mfma_i32_16x16x64_i8 v[64:67], v[140:143], v[184:187], v[64:67]
	v_mfma_i32_16x16x64_i8 v[36:39], v[160:163], v[184:187], 0
	v_mfma_i32_16x16x64_i8 v[36:39], v[172:175], v[188:191], v[36:39]
	v_mfma_i32_16x16x64_i8 v[52:55], v[172:175], v[208:211], 0
	v_mfma_i32_16x16x64_i8 v[52:55], v[160:163], v[204:207], v[52:55]
	v_mfma_i32_16x16x64_i8 v[28:31], v[160:163], v[212:215], 0
	v_mfma_i32_16x16x64_i8 v[28:31], v[172:175], v[216:219], v[28:31]
	v_mfma_i32_16x16x64_i8 v[12:15], v[172:175], v[224:227], 0
	v_mfma_i32_16x16x64_i8 v[12:15], v[160:163], v[220:223], v[12:15]
	v_mfma_i32_16x16x64_i8 v[4:7], v[176:179], v[220:223], 0
	v_mfma_i32_16x16x64_i8 v[4:7], v[180:183], v[224:227], v[4:7]
	v_mfma_i32_16x16x64_i8 v[20:23], v[180:183], v[216:219], 0
	v_mfma_i32_16x16x64_i8 v[20:23], v[176:179], v[212:215], v[20:23]
	v_mfma_i32_16x16x64_i8 v[40:43], v[176:179], v[204:207], 0
	v_mfma_i32_16x16x64_i8 v[40:43], v[180:183], v[208:211], v[40:43]
	v_mfma_i32_16x16x64_i8 v[44:47], v[180:183], v[188:191], 0
	v_mfma_i32_16x16x64_i8 v[44:47], v[176:179], v[184:187], v[44:47]
	s_setprio 0
	s_barrier
	s_add_i32 s64, 0, 0x18000
	s_add_i32 s65, 0, 0x1c000
	v_add_u32_e32 v144, s64, v167
	v_add_u32_e32 v158, s65, v167
	ds_read_b128 v[60:63], v144
	ds_read_b128 v[68:71], v144 offset:1024
	ds_read_b128 v[140:143], v144 offset:2048
	ds_read_b128 v[144:147], v144 offset:3072
	ds_read_b128 v[160:163], v158
	ds_read_b128 v[172:175], v158 offset:1024
	ds_read_b128 v[176:179], v158 offset:2048
	ds_read_b128 v[180:183], v158 offset:3072
	s_add_u32 s48, s48, 0x80000
	s_addc_u32 s49, s49, 0
	s_mov_b32 m0, s52
	v_lshl_add_u64 v[244:245], s[48:49], 0, v[152:153]
	ds_read_b128 v[184:187], v171 offset:32768
	ds_read_b128 v[188:191], v171 offset:33792
	ds_read_b128 v[204:207], v171 offset:34816
	ds_read_b128 v[208:211], v171 offset:35840
	ds_read_b128 v[212:215], v171 offset:36864
	ds_read_b128 v[216:219], v171 offset:37888
	ds_read_b128 v[220:223], v171 offset:38912
	ds_read_b128 v[224:227], v171 offset:39936
	s_mov_b32 m0, s50
	s_nop 0
	global_load_lds_dwordx4 v[240:241], off
	s_mov_b32 m0, s51
	s_nop 0
	global_load_lds_dwordx4 v[242:243], off
	s_mov_b32 m0, s52
	s_nop 0
	global_load_lds_dwordx4 v[244:245], off
	v_lshl_add_u64 v[244:245], s[48:49], 0, v[150:151]
	s_mov_b32 m0, s53
	s_nop 0
	global_load_lds_dwordx4 v[244:245], off
	s_waitcnt vmcnt(8)
	s_waitcnt lgkmcnt(0)
	s_barrier
	s_setprio 1
	s_waitcnt lgkmcnt(0)
	v_mfma_i32_16x16x64_i8 v[136:139], v[60:63], v[184:187], v[136:139]
	v_mfma_i32_16x16x64_i8 v[136:139], v[68:71], v[188:191], v[136:139]
	v_mfma_i32_16x16x64_i8 v[120:123], v[68:71], v[208:211], v[120:123]
	v_mfma_i32_16x16x64_i8 v[120:123], v[60:63], v[204:207], v[120:123]
	v_mfma_i32_16x16x64_i8 v[104:107], v[60:63], v[212:215], v[104:107]
	v_mfma_i32_16x16x64_i8 v[104:107], v[68:71], v[216:219], v[104:107]
	v_mfma_i32_16x16x64_i8 v[88:91], v[68:71], v[224:227], v[88:91]
	v_mfma_i32_16x16x64_i8 v[88:91], v[60:63], v[220:223], v[88:91]
	v_mfma_i32_16x16x64_i8 v[80:83], v[140:143], v[220:223], v[80:83]
	v_mfma_i32_16x16x64_i8 v[80:83], v[144:147], v[224:227], v[80:83]
	v_mfma_i32_16x16x64_i8 v[96:99], v[144:147], v[216:219], v[96:99]
	v_mfma_i32_16x16x64_i8 v[96:99], v[140:143], v[212:215], v[96:99]
	v_mfma_i32_16x16x64_i8 v[112:115], v[140:143], v[204:207], v[112:115]
	v_mfma_i32_16x16x64_i8 v[112:115], v[144:147], v[208:211], v[112:115]
	v_mfma_i32_16x16x64_i8 v[128:131], v[144:147], v[188:191], v[128:131]
	v_mfma_i32_16x16x64_i8 v[128:131], v[140:143], v[184:187], v[128:131]
	v_mfma_i32_16x16x64_i8 v[132:135], v[160:163], v[184:187], v[132:135]
	v_mfma_i32_16x16x64_i8 v[132:135], v[172:175], v[188:191], v[132:135]
	v_mfma_i32_16x16x64_i8 v[116:119], v[172:175], v[208:211], v[116:119]
	v_mfma_i32_16x16x64_i8 v[116:119], v[160:163], v[204:207], v[116:119]
	v_mfma_i32_16x16x64_i8 v[100:103], v[160:163], v[212:215], v[100:103]
	v_mfma_i32_16x16x64_i8 v[100:103], v[172:175], v[216:219], v[100:103]
	v_mfma_i32_16x16x64_i8 v[84:87], v[172:175], v[224:227], v[84:87]
	v_mfma_i32_16x16x64_i8 v[84:87], v[160:163], v[220:223], v[84:87]
	v_mfma_i32_16x16x64_i8 v[76:79], v[176:179], v[220:223], v[76:79]
	v_mfma_i32_16x16x64_i8 v[76:79], v[180:183], v[224:227], v[76:79]
	v_mfma_i32_16x16x64_i8 v[92:95], v[180:183], v[216:219], v[92:95]
	v_mfma_i32_16x16x64_i8 v[92:95], v[176:179], v[212:215], v[92:95]
	v_mfma_i32_16x16x64_i8 v[108:111], v[176:179], v[204:207], v[108:111]
	v_mfma_i32_16x16x64_i8 v[108:111], v[180:183], v[208:211], v[108:111]
	v_mfma_i32_16x16x64_i8 v[124:127], v[180:183], v[188:191], v[124:127]
	v_mfma_i32_16x16x64_i8 v[124:127], v[176:179], v[184:187], v[124:127]
	s_setprio 0
	s_barrier
	s_add_i32 s48, s64, s47
	v_lshl_add_u64 v[164:165], v[164:165], 0, s[84:85]
	s_mov_b32 m0, s48
	ds_read_b128 v[184:187], v171 offset:49152
	ds_read_b128 v[188:191], v171 offset:50176
	ds_read_b128 v[204:207], v171 offset:51200
	ds_read_b128 v[208:211], v171 offset:52224
	ds_read_b128 v[212:215], v171 offset:53248
	ds_read_b128 v[216:219], v171 offset:54272
	ds_read_b128 v[220:223], v171 offset:55296
	ds_read_b128 v[224:227], v171 offset:56320
	global_load_lds_dwordx4 v[164:165], off
	s_add_i32 m0, s48, 0x2000
	s_add_u32 s44, s44, 0x80080
	v_lshl_add_u64 v[164:165], v[228:229], 0, s[84:85]
	s_addc_u32 s45, s45, 0
	s_add_i32 s48, s65, s47
	global_load_lds_dwordx4 v[164:165], off
	v_lshl_add_u64 v[164:165], s[44:45], 0, v[2:3]
	s_mov_b32 m0, s48
	s_nop 0
	global_load_lds_dwordx4 v[164:165], off
	v_lshl_add_u64 v[164:165], s[44:45], 0, v[148:149]
	s_add_i32 m0, s48, 0x2000
	s_nop 0
	global_load_lds_dwordx4 v[164:165], off
	s_cmp_eq_u32 s61, 28
	s_cbranch_scc0 .Ldefer_1591_peel
	v_lshl_add_u64 v[164:165], v[240:241], 0, s[84:85]
	s_mov_b32 m0, s54
	s_nop 0
	global_load_lds_dwordx4 v[164:165], off
	v_lshl_add_u64 v[164:165], v[242:243], 0, s[84:85]
	s_mov_b32 m0, s55
	s_nop 0
	global_load_lds_dwordx4 v[164:165], off

; #define PG8_STAGE(bufoff, gbase, voff) do { _Pragma("unroll") for (int _i = 0; _i < 2; ++_i) \
;         __builtin_amdgcn_global_load_lds((const unsigned*)((const char*)(gbase) + (voff)[_i]), (PG8_LAS unsigned*)(lds + (bufoff) + ldsw + _i * 8192), 16, 0, 0); } while (0)
; #define PG8_LDA(dst, b, h) do { _Pragma("unroll") for (int m = 0; m < 4; ++m) _Pragma("unroll") for (int k = 0; k < 2; ++k) dst[m][k] = *(const PG8_LAS bf16x8*)(lds + PG8_SA(b, h) + aoff + m * 2048 + k * 1024); } while (0)
; #define PG8_LDB(dst, b, h) do { _Pragma("unroll") for (int n = 0; n < 2; ++n) _Pragma("unroll") for (int k = 0; k < 2; ++k) dst[n][k] = *(const PG8_LAS bf16x8*)(lds + PG8_SB(b, h) + boff + n * 2048 + k * 1024); } while (0)
; #define PG8_WAIT_V(n) asm volatile("s_waitcnt vmcnt(" #n ")" ::: "memory")
; #define PG8_WAIT_L(n) asm volatile("s_waitcnt lgkmcnt(" #n ")" ::: "memory")
; #define PG8_BAR __builtin_amdgcn_s_barrier()
; #define PG8_SCHED __builtin_amdgcn_sched_barrier(0)
; template <class Epi, class Sched, bool ALIGN_EPI = false, bool SP2 = false, bool I8 = false>
; __device__ __forceinline__ void gemm_phase(PG8_LAS unsigned char* lds, const Gemm g, const Sched& S, const Epi& E) {
;     ...
;         for (int t = 0; t < nt; t += 2) {
;             const bool last = (t == nt - 2);
;             const char* a1 = cA + (size_t)(t + 1) * kstep;
;             const char* a2 = last ? nA : cA + (size_t)(t + 2) * kstep; const char* b2 = last ? nB : cB + (size_t)(t + 2) * kstep;
;             const char* a3 = a2 + kstep; const char* b3 = b2 + kstep;
;             if (last && has_next) S.a_ready(nxt);
;             if constexpr (SP2) {
;             PG8_LDB(B0, 0, 0); PG8_LDB(B1, 0, 1); PG8_SCHED; PG8_LDA(At, 0, 0); PG8_STAGE(PG8_SA(1, 1), a1 + hstep, voffA);
;             PG8_WAIT_V(8); PG8_WAIT_L(0); PG8_BAR; PG8_MMA(0, 0, At, B0); PG8_MMA(0, 1, At, B1); PG8_BAR; PG8_SCHED;
;             PG8_LDA(At, 0, 1); PG8_STAGE(PG8_SB(0, 0), b2, voffB); PG8_STAGE(PG8_SB(0, 1), b2 + hstep, voffB); PG8_STAGE(PG8_SA(0, 0), a2, voffA);
.LBB0_1591:
	s_add_u32 s44, s40, 0xfff80080
	s_addc_u32 s45, s41, -1
	s_add_i32 s64, 0, 0x10000
	s_cmp_eq_u32 s61, 28
	s_cselect_b32 s49, s25, s45
	s_cselect_b32 s48, s57, s44
	s_cselect_b32 s45, s23, s60
	s_cselect_b32 s44, s58, s59
	s_add_i32 s67, 0, 0x14000
	v_add_u32_e32 v144, s64, v167
	v_add_u32_e32 v158, s67, v167
	ds_read_b128 v[36:39], v144
	ds_read_b128 v[44:47], v144 offset:1024
	ds_read_b128 v[140:143], v144 offset:2048
	ds_read_b128 v[144:147], v144 offset:3072
	ds_read_b128 v[160:163], v158
	ds_read_b128 v[172:175], v158 offset:1024
	ds_read_b128 v[176:179], v158 offset:2048
	ds_read_b128 v[180:183], v158 offset:3072
	ds_read_b128 v[184:187], v171
	ds_read_b128 v[188:191], v171 offset:1024
	ds_read_b128 v[204:207], v171 offset:2048
	ds_read_b128 v[208:211], v171 offset:3072
	ds_read_b128 v[212:215], v171 offset:4096
	ds_read_b128 v[216:219], v171 offset:5120
	ds_read_b128 v[220:223], v171 offset:6144
	ds_read_b128 v[224:227], v171 offset:7168
	v_lshl_add_u64 v[164:165], v[240:241], 0, s[84:85]
	s_mov_b32 m0, s54
	s_nop 0
	global_load_lds_dwordx4 v[164:165], off
	v_lshl_add_u64 v[164:165], v[242:243], 0, s[84:85]
	s_mov_b32 m0, s55
	s_nop 0
	global_load_lds_dwordx4 v[164:165], off
	v_lshl_add_u64 v[164:165], s[40:41], 0, v[154:155]
	s_add_i32 m0, s50, 0xc000
	s_nop 0
	global_load_lds_dwordx4 v[164:165], off
	v_lshl_add_u64 v[164:165], s[40:41], 0, v[156:157]
	s_add_i32 m0, s50, 0xe000
	s_nop 0
	global_load_lds_dwordx4 v[164:165], off
	s_waitcnt vmcnt(8)
	s_waitcnt lgkmcnt(0)
	s_barrier
	s_setprio 1
	s_waitcnt lgkmcnt(0)
	v_mfma_i32_16x16x64_i8 v[136:139], v[36:39], v[184:187], v[136:139]
	v_mfma_i32_16x16x64_i8 v[136:139], v[44:47], v[188:191], v[136:139]
	v_mfma_i32_16x16x64_i8 v[120:123], v[44:47], v[208:211], v[120:123]
	v_mfma_i32_16x16x64_i8 v[120:123], v[36:39], v[204:207], v[120:123]
	v_mfma_i32_16x16x64_i8 v[104:107], v[36:39], v[212:215], v[104:107]
	v_mfma_i32_16x16x64_i8 v[104:107], v[44:47], v[216:219], v[104:107]
	v_mfma_i32_16x16x64_i8 v[88:91], v[44:47], v[224:227], v[88:91]
	v_mfma_i32_16x16x64_i8 v[88:91], v[36:39], v[220:223], v[88:91]
	v_mfma_i32_16x16x64_i8 v[80:83], v[140:143], v[220:223], v[80:83]
	v_mfma_i32_16x16x64_i8 v[80:83], v[144:147], v[224:227], v[80:83]
	v_mfma_i32_16x16x64_i8 v[96:99], v[144:147], v[216:219], v[96:99]
	v_mfma_i32_16x16x64_i8 v[96:99], v[140:143], v[212:215], v[96:99]
	v_mfma_i32_16x16x64_i8 v[112:115], v[140:143], v[204:207], v[112:115]
	v_mfma_i32_16x16x64_i8 v[112:115], v[144:147], v[208:211], v[112:115]
	v_mfma_i32_16x16x64_i8 v[128:131], v[144:147], v[188:191], v[128:131]
	v_mfma_i32_16x16x64_i8 v[128:131], v[140:143], v[184:187], v[128:131]
	v_mfma_i32_16x16x64_i8 v[132:135], v[160:163], v[184:187], v[132:135]
	v_mfma_i32_16x16x64_i8 v[132:135], v[172:175], v[188:191], v[132:135]
	v_mfma_i32_16x16x64_i8 v[116:119], v[172:175], v[208:211], v[116:119]
	v_mfma_i32_16x16x64_i8 v[116:119], v[160:163], v[204:207], v[116:119]
	v_mfma_i32_16x16x64_i8 v[100:103], v[160:163], v[212:215], v[100:103]
	v_mfma_i32_16x16x64_i8 v[100:103], v[172:175], v[216:219], v[100:103]
	v_mfma_i32_16x16x64_i8 v[84:87], v[172:175], v[224:227], v[84:87]
	v_mfma_i32_16x16x64_i8 v[84:87], v[160:163], v[220:223], v[84:87]
	v_mfma_i32_16x16x64_i8 v[76:79], v[176:179], v[220:223], v[76:79]
	v_mfma_i32_16x16x64_i8 v[76:79], v[180:183], v[224:227], v[76:79]
	v_mfma_i32_16x16x64_i8 v[92:95], v[180:183], v[216:219], v[92:95]
	v_mfma_i32_16x16x64_i8 v[92:95], v[176:179], v[212:215], v[92:95]
	v_mfma_i32_16x16x64_i8 v[108:111], v[176:179], v[204:207], v[108:111]
	v_mfma_i32_16x16x64_i8 v[108:111], v[180:183], v[208:211], v[108:111]
	v_mfma_i32_16x16x64_i8 v[124:127], v[180:183], v[188:191], v[124:127]
	v_mfma_i32_16x16x64_i8 v[124:127], v[176:179], v[184:187], v[124:127]
	s_setprio 0
	s_barrier
	s_add_i32 s64, s64, s47
	v_lshl_add_u64 v[164:165], s[44:45], 0, v[2:3]
	s_mov_b32 m0, s64
	ds_read_b128 v[184:187], v171 offset:16384
	ds_read_b128 v[188:191], v171 offset:17408
	ds_read_b128 v[204:207], v171 offset:18432
	ds_read_b128 v[208:211], v171 offset:19456
	ds_read_b128 v[212:215], v171 offset:20480
	ds_read_b128 v[216:219], v171 offset:21504
	ds_read_b128 v[220:223], v171 offset:22528
	ds_read_b128 v[224:227], v171 offset:23552
	global_load_lds_dwordx4 v[164:165], off
	s_add_i32 m0, s64, 0x2000
	s_add_u32 s64, s44, 0x80000
	v_lshl_add_u64 v[228:229], s[44:45], 0, v[148:149]
	s_addc_u32 s65, s45, 0
	s_add_i32 s67, s67, s47
	global_load_lds_dwordx4 v[228:229], off
	v_lshl_add_u64 v[240:241], s[64:65], 0, v[2:3]
	s_mov_b32 m0, s67
	v_lshl_add_u64 v[242:243], s[48:49], 0, v[150:151]
	global_load_lds_dwordx4 v[240:241], off
	v_lshl_add_u64 v[240:241], s[64:65], 0, v[148:149]
	s_add_i32 m0, s67, 0x2000
	s_nop 0
	global_load_lds_dwordx4 v[240:241], off
	v_lshl_add_u64 v[240:241], s[48:49], 0, v[152:153]
	s_waitcnt vmcnt(6)
	s_waitcnt lgkmcnt(0)
	s_barrier
; #define PG8_STAGE(bufoff, gbase, voff) do { _Pragma("unroll") for (int _i = 0; _i < 2; ++_i) \
;         __builtin_amdgcn_global_load_lds((const unsigned*)((const char*)(gbase) + (voff)[_i]), (PG8_LAS unsigned*)(lds + (bufoff) + ldsw + _i * 8192), 16, 0, 0); } while (0)
; #define PG8_LDA(dst, b, h) do { _Pragma("unroll") for (int m = 0; m < 4; ++m) _Pragma("unroll") for (int k = 0; k < 2; ++k) dst[m][k] = *(const PG8_LAS bf16x8*)(lds + PG8_SA(b, h) + aoff + m * 2048 + k * 1024); } while (0)
; #define PG8_LDB(dst, b, h) do { _Pragma("unroll") for (int n = 0; n < 2; ++n) _Pragma("unroll") for (int k = 0; k < 2; ++k) dst[n][k] = *(const PG8_LAS bf16x8*)(lds + PG8_SB(b, h) + boff + n * 2048 + k * 1024); } while (0)
; #define PG8_WAIT_V(n) asm volatile("s_waitcnt vmcnt(" #n ")" ::: "memory")
; #define PG8_WAIT_L(n) asm volatile("s_waitcnt lgkmcnt(" #n ")" ::: "memory")
; #define PG8_BAR __builtin_amdgcn_s_barrier()
; #define PG8_SCHED __builtin_amdgcn_sched_barrier(0)
; template <class Epi, class Sched, bool ALIGN_EPI = false, bool SP2 = false, bool I8 = false>
; __device__ __forceinline__ void gemm_phase(PG8_LAS unsigned char* lds, const Gemm g, const Sched& S, const Epi& E) {
;     ...
;             PG8_WAIT_V(8); PG8_WAIT_L(0); PG8_BAR; PG8_MMA(1, 0, At, B0); PG8_MMA(1, 1, At, B1); PG8_BAR; PG8_SCHED;
;             PG8_LDB(B0, 1, 0); PG8_LDB(B1, 1, 1); PG8_SCHED; PG8_LDA(At, 1, 0); PG8_STAGE(PG8_SA(0, 1), a2 + hstep, voffA);
;             PG8_WAIT_V(8); PG8_WAIT_L(0); PG8_BAR; PG8_MMA(0, 0, At, B0); PG8_MMA(0, 1, At, B1); PG8_BAR; PG8_SCHED;
;             PG8_LDA(At, 1, 1); PG8_STAGE(PG8_SB(1, 0), b3, voffB); PG8_STAGE(PG8_SB(1, 1), b3 + hstep, voffB); PG8_STAGE(PG8_SA(1, 0), a3, voffA);
	s_setprio 1
	s_waitcnt lgkmcnt(0)
	v_mfma_i32_16x16x64_i8 v[72:75], v[36:39], v[184:187], v[72:75]
	v_mfma_i32_16x16x64_i8 v[72:75], v[44:47], v[188:191], v[72:75]
	v_mfma_i32_16x16x64_i8 v[56:59], v[44:47], v[208:211], v[56:59]
	v_mfma_i32_16x16x64_i8 v[56:59], v[36:39], v[204:207], v[56:59]
	v_mfma_i32_16x16x64_i8 v[32:35], v[36:39], v[212:215], v[32:35]
	v_mfma_i32_16x16x64_i8 v[32:35], v[44:47], v[216:219], v[32:35]
	v_mfma_i32_16x16x64_i8 v[16:19], v[44:47], v[224:227], v[16:19]
	v_mfma_i32_16x16x64_i8 v[16:19], v[36:39], v[220:223], v[16:19]
	v_mfma_i32_16x16x64_i8 v[8:11], v[140:143], v[220:223], v[8:11]
	v_mfma_i32_16x16x64_i8 v[8:11], v[144:147], v[224:227], v[8:11]
	v_mfma_i32_16x16x64_i8 v[24:27], v[144:147], v[216:219], v[24:27]
	v_mfma_i32_16x16x64_i8 v[24:27], v[140:143], v[212:215], v[24:27]
	v_mfma_i32_16x16x64_i8 v[48:51], v[140:143], v[204:207], v[48:51]
	v_mfma_i32_16x16x64_i8 v[48:51], v[144:147], v[208:211], v[48:51]
	v_mfma_i32_16x16x64_i8 v[64:67], v[144:147], v[188:191], v[64:67]
	v_mfma_i32_16x16x64_i8 v[64:67], v[140:143], v[184:187], v[64:67]
	v_mfma_i32_16x16x64_i8 v[36:39], v[160:163], v[184:187], v[68:71]
	v_mfma_i32_16x16x64_i8 v[36:39], v[172:175], v[188:191], v[36:39]
	v_mfma_i32_16x16x64_i8 v[52:55], v[172:175], v[208:211], v[52:55]
	v_mfma_i32_16x16x64_i8 v[52:55], v[160:163], v[204:207], v[52:55]
	v_mfma_i32_16x16x64_i8 v[28:31], v[160:163], v[212:215], v[28:31]
	v_mfma_i32_16x16x64_i8 v[28:31], v[172:175], v[216:219], v[28:31]
	v_mfma_i32_16x16x64_i8 v[12:15], v[172:175], v[224:227], v[12:15]
	v_mfma_i32_16x16x64_i8 v[12:15], v[160:163], v[220:223], v[12:15]
	v_mfma_i32_16x16x64_i8 v[4:7], v[176:179], v[220:223], v[4:7]
	v_mfma_i32_16x16x64_i8 v[4:7], v[180:183], v[224:227], v[4:7]
	v_mfma_i32_16x16x64_i8 v[20:23], v[180:183], v[216:219], v[20:23]
	v_mfma_i32_16x16x64_i8 v[20:23], v[176:179], v[212:215], v[20:23]
	v_mfma_i32_16x16x64_i8 v[40:43], v[176:179], v[204:207], v[40:43]
	v_mfma_i32_16x16x64_i8 v[40:43], v[180:183], v[208:211], v[40:43]
	v_mfma_i32_16x16x64_i8 v[44:47], v[180:183], v[188:191], v[60:63]
	v_mfma_i32_16x16x64_i8 v[44:47], v[176:179], v[184:187], v[44:47]
	s_setprio 0
	s_barrier
	s_add_i32 s64, 0, 0x18000
	s_add_i32 s65, 0, 0x1c000
	v_add_u32_e32 v144, s64, v167
	v_add_u32_e32 v158, s65, v167
	ds_read_b128 v[60:63], v144
	ds_read_b128 v[68:71], v144 offset:1024
	ds_read_b128 v[140:143], v144 offset:2048
	ds_read_b128 v[144:147], v144 offset:3072
	ds_read_b128 v[160:163], v158
	ds_read_b128 v[172:175], v158 offset:1024
	ds_read_b128 v[176:179], v158 offset:2048
	ds_read_b128 v[180:183], v158 offset:3072
	s_add_u32 s48, s48, 0x80000
	s_addc_u32 s49, s49, 0
	s_mov_b32 m0, s52
	v_lshl_add_u64 v[244:245], s[48:49], 0, v[152:153]
	ds_read_b128 v[184:187], v171 offset:32768
	ds_read_b128 v[188:191], v171 offset:33792
	ds_read_b128 v[204:207], v171 offset:34816
	ds_read_b128 v[208:211], v171 offset:35840
	ds_read_b128 v[212:215], v171 offset:36864
	ds_read_b128 v[216:219], v171 offset:37888
	ds_read_b128 v[220:223], v171 offset:38912
	ds_read_b128 v[224:227], v171 offset:39936
	s_mov_b32 m0, s50
	s_nop 0
	global_load_lds_dwordx4 v[240:241], off
	s_mov_b32 m0, s51
	s_nop 0
	global_load_lds_dwordx4 v[242:243], off
	s_mov_b32 m0, s52
	s_nop 0
	global_load_lds_dwordx4 v[244:245], off
	v_lshl_add_u64 v[244:245], s[48:49], 0, v[150:151]
	s_mov_b32 m0, s53
	s_nop 0
	global_load_lds_dwordx4 v[244:245], off
	s_waitcnt vmcnt(8)
	s_waitcnt lgkmcnt(0)
	s_barrier
	s_setprio 1
	s_waitcnt lgkmcnt(0)
	v_mfma_i32_16x16x64_i8 v[136:139], v[60:63], v[184:187], v[136:139]
	v_mfma_i32_16x16x64_i8 v[136:139], v[68:71], v[188:191], v[136:139]
	v_mfma_i32_16x16x64_i8 v[120:123], v[68:71], v[208:211], v[120:123]
	v_mfma_i32_16x16x64_i8 v[120:123], v[60:63], v[204:207], v[120:123]
	v_mfma_i32_16x16x64_i8 v[104:107], v[60:63], v[212:215], v[104:107]
	v_mfma_i32_16x16x64_i8 v[104:107], v[68:71], v[216:219], v[104:107]
	v_mfma_i32_16x16x64_i8 v[88:91], v[68:71], v[224:227], v[88:91]
	v_mfma_i32_16x16x64_i8 v[88:91], v[60:63], v[220:223], v[88:91]
	v_mfma_i32_16x16x64_i8 v[80:83], v[140:143], v[220:223], v[80:83]
	v_mfma_i32_16x16x64_i8 v[80:83], v[144:147], v[224:227], v[80:83]
	v_mfma_i32_16x16x64_i8 v[96:99], v[144:147], v[216:219], v[96:99]
	v_mfma_i32_16x16x64_i8 v[96:99], v[140:143], v[212:215], v[96:99]
	v_mfma_i32_16x16x64_i8 v[112:115], v[140:143], v[204:207], v[112:115]
	v_mfma_i32_16x16x64_i8 v[112:115], v[144:147], v[208:211], v[112:115]
	v_mfma_i32_16x16x64_i8 v[128:131], v[144:147], v[188:191], v[128:131]
	v_mfma_i32_16x16x64_i8 v[128:131], v[140:143], v[184:187], v[128:131]
	v_mfma_i32_16x16x64_i8 v[132:135], v[160:163], v[184:187], v[132:135]
	v_mfma_i32_16x16x64_i8 v[132:135], v[172:175], v[188:191], v[132:135]
	v_mfma_i32_16x16x64_i8 v[116:119], v[172:175], v[208:211], v[116:119]
	v_mfma_i32_16x16x64_i8 v[116:119], v[160:163], v[204:207], v[116:119]
	v_mfma_i32_16x16x64_i8 v[100:103], v[160:163], v[212:215], v[100:103]
	v_mfma_i32_16x16x64_i8 v[100:103], v[172:175], v[216:219], v[100:103]
	v_mfma_i32_16x16x64_i8 v[84:87], v[172:175], v[224:227], v[84:87]
	v_mfma_i32_16x16x64_i8 v[84:87], v[160:163], v[220:223], v[84:87]
	v_mfma_i32_16x16x64_i8 v[76:79], v[176:179], v[220:223], v[76:79]
	v_mfma_i32_16x16x64_i8 v[76:79], v[180:183], v[224:227], v[76:79]
	v_mfma_i32_16x16x64_i8 v[92:95], v[180:183], v[216:219], v[92:95]
	v_mfma_i32_16x16x64_i8 v[92:95], v[176:179], v[212:215], v[92:95]
	v_mfma_i32_16x16x64_i8 v[108:111], v[176:179], v[204:207], v[108:111]
	v_mfma_i32_16x16x64_i8 v[108:111], v[180:183], v[208:211], v[108:111]
	v_mfma_i32_16x16x64_i8 v[124:127], v[180:183], v[188:191], v[124:127]
	v_mfma_i32_16x16x64_i8 v[124:127], v[176:179], v[184:187], v[124:127]
	s_setprio 0
	s_barrier
	s_add_i32 s48, s64, s47
	v_lshl_add_u64 v[164:165], v[164:165], 0, s[84:85]
	s_mov_b32 m0, s48
	ds_read_b128 v[184:187], v171 offset:49152
	ds_read_b128 v[188:191], v171 offset:50176
	ds_read_b128 v[204:207], v171 offset:51200
	ds_read_b128 v[208:211], v171 offset:52224
	ds_read_b128 v[212:215], v171 offset:53248
	ds_read_b128 v[216:219], v171 offset:54272
	ds_read_b128 v[220:223], v171 offset:55296
	ds_read_b128 v[224:227], v171 offset:56320
	global_load_lds_dwordx4 v[164:165], off
	s_add_i32 m0, s48, 0x2000
	s_add_u32 s44, s44, 0x80080
	v_lshl_add_u64 v[164:165], v[228:229], 0, s[84:85]
	s_addc_u32 s45, s45, 0
	s_add_i32 s48, s65, s47
	global_load_lds_dwordx4 v[164:165], off
	v_lshl_add_u64 v[164:165], s[44:45], 0, v[2:3]
	s_mov_b32 m0, s48
	s_nop 0
	global_load_lds_dwordx4 v[164:165], off
	v_lshl_add_u64 v[164:165], s[44:45], 0, v[148:149]
	s_add_i32 m0, s48, 0x2000
	s_nop 0
	global_load_lds_dwordx4 v[164:165], off
	s_cmp_eq_u32 s61, 28
	s_cbranch_scc0 .Ldefer_1591_body
	v_lshl_add_u64 v[164:165], v[240:241], 0, s[84:85]
	s_mov_b32 m0, s54
	s_nop 0
	global_load_lds_dwordx4 v[164:165], off
	v_lshl_add_u64 v[164:165], v[242:243], 0, s[84:85]
	s_mov_b32 m0, s55
	s_nop 0
	global_load_lds_dwordx4 v[164:165], off

; #define PG8_STAGE(bufoff, gbase, voff) do { _Pragma("unroll") for (int _i = 0; _i < 2; ++_i) \
;         __builtin_amdgcn_global_load_lds((const unsigned*)((const char*)(gbase) + (voff)[_i]), (PG8_LAS unsigned*)(lds + (bufoff) + ldsw + _i * 8192), 16, 0, 0); } while (0)
; #define PG8_LDA(dst, b, h) do { _Pragma("unroll") for (int m = 0; m < 4; ++m) _Pragma("unroll") for (int k = 0; k < 2; ++k) dst[m][k] = *(const PG8_LAS bf16x8*)(lds + PG8_SA(b, h) + aoff + m * 2048 + k * 1024); } while (0)
; #define PG8_LDB(dst, b, h) do { _Pragma("unroll") for (int n = 0; n < 2; ++n) _Pragma("unroll") for (int k = 0; k < 2; ++k) dst[n][k] = *(const PG8_LAS bf16x8*)(lds + PG8_SB(b, h) + boff + n * 2048 + k * 1024); } while (0)
; #define PG8_SCHED __builtin_amdgcn_sched_barrier(0)
; template <class Epi, class Sched, bool ALIGN_EPI = false, bool SP2 = false, bool I8 = false>
; __device__ __forceinline__ void gemm_phase(PG8_LAS unsigned char* lds, const Gemm g, const Sched& S, const Epi& E) {
;     ...
;         for (int t = 0; t < nt; t += 2) {
;             const bool last = (t == nt - 2);
;             const char* a1 = cA + (size_t)(t + 1) * kstep;
;             const char* a2 = last ? nA : cA + (size_t)(t + 2) * kstep; const char* b2 = last ? nB : cB + (size_t)(t + 2) * kstep;
;             const char* a3 = a2 + kstep; const char* b3 = b2 + kstep;
;             if (last && has_next) S.a_ready(nxt);
;             if constexpr (SP2) {
;             PG8_LDB(B0, 0, 0); PG8_LDB(B1, 0, 1); PG8_SCHED; PG8_LDA(At, 0, 0); PG8_STAGE(PG8_SA(1, 1), a1 + hstep, voffA);
;     ...
; #pragma unroll
;         for (int a = 0; a < 2; ++a)
; #pragma unroll
;             for (int b = 0; b < 2; ++b)
; #pragma unroll
;                 for (int m = 0; m < 4; ++m)
; #pragma unroll
;                     for (int n = 0; n < 2; ++n) acc[a][b][m][n] = (acc_t){0, 0, 0, 0};
.LBB0_1621:
	v_mov_b32_e32 v127, 0
	s_andn2_b64 vcc, exec, s[26:27]
	v_mov_b32_e32 v126, v127
	v_mov_b32_e32 v125, v127
	v_mov_b32_e32 v124, v127
	v_mov_b32_e32 v131, v127
	v_mov_b32_e32 v130, v127
	v_mov_b32_e32 v129, v127
	v_mov_b32_e32 v128, v127
	v_mov_b32_e32 v115, v127
	v_mov_b32_e32 v114, v127
	v_mov_b32_e32 v113, v127
	v_mov_b32_e32 v112, v127
	v_mov_b32_e32 v111, v127
	v_mov_b32_e32 v110, v127
	v_mov_b32_e32 v109, v127
	v_mov_b32_e32 v108, v127
	v_mov_b32_e32 v99, v127
	v_mov_b32_e32 v98, v127
	v_mov_b32_e32 v97, v127
	v_mov_b32_e32 v96, v127
	v_mov_b32_e32 v95, v127
	v_mov_b32_e32 v94, v127
	v_mov_b32_e32 v93, v127
	v_mov_b32_e32 v92, v127
	v_mov_b32_e32 v83, v127
	v_mov_b32_e32 v82, v127
	v_mov_b32_e32 v81, v127
	v_mov_b32_e32 v80, v127
	v_mov_b32_e32 v79, v127
	v_mov_b32_e32 v78, v127
	v_mov_b32_e32 v77, v127
	v_mov_b32_e32 v76, v127
	v_mov_b32_e32 v123, v127
	v_mov_b32_e32 v122, v127
	v_mov_b32_e32 v121, v127
	v_mov_b32_e32 v120, v127
	v_mov_b32_e32 v119, v127
	v_mov_b32_e32 v118, v127
	v_mov_b32_e32 v117, v127
	v_mov_b32_e32 v116, v127
	v_mov_b32_e32 v107, v127
	v_mov_b32_e32 v106, v127
	v_mov_b32_e32 v105, v127
	v_mov_b32_e32 v104, v127
	v_mov_b32_e32 v103, v127
	v_mov_b32_e32 v102, v127
	v_mov_b32_e32 v101, v127
	v_mov_b32_e32 v100, v127
	v_mov_b32_e32 v91, v127
	v_mov_b32_e32 v90, v127
	v_mov_b32_e32 v89, v127
	v_mov_b32_e32 v88, v127
	v_mov_b32_e32 v87, v127
	v_mov_b32_e32 v86, v127
	v_mov_b32_e32 v85, v127
	v_mov_b32_e32 v84, v127
	v_mov_b32_e32 v75, v127
	v_mov_b32_e32 v74, v127
	v_mov_b32_e32 v73, v127
	v_mov_b32_e32 v72, v127
	v_mov_b32_e32 v71, v127
	v_mov_b32_e32 v70, v127
	v_mov_b32_e32 v69, v127
	v_mov_b32_e32 v68, v127
	v_mov_b32_e32 v67, v127
	v_mov_b32_e32 v66, v127
	v_mov_b32_e32 v65, v127
	v_mov_b32_e32 v64, v127
	v_mov_b32_e32 v63, v127
	v_mov_b32_e32 v62, v127
	v_mov_b32_e32 v61, v127
	v_mov_b32_e32 v60, v127
	v_mov_b32_e32 v51, v127
	v_mov_b32_e32 v50, v127
	v_mov_b32_e32 v49, v127
	v_mov_b32_e32 v48, v127
	v_mov_b32_e32 v47, v127
	v_mov_b32_e32 v46, v127
	v_mov_b32_e32 v45, v127
	v_mov_b32_e32 v44, v127
	v_mov_b32_e32 v35, v127
	v_mov_b32_e32 v34, v127
	v_mov_b32_e32 v33, v127
	v_mov_b32_e32 v32, v127
	v_mov_b32_e32 v31, v127
	v_mov_b32_e32 v30, v127
	v_mov_b32_e32 v29, v127
	v_mov_b32_e32 v28, v127
	v_mov_b32_e32 v19, v127
	v_mov_b32_e32 v18, v127
	v_mov_b32_e32 v17, v127
	v_mov_b32_e32 v16, v127
	v_mov_b32_e32 v15, v127
	v_mov_b32_e32 v14, v127
	v_mov_b32_e32 v13, v127
	v_mov_b32_e32 v12, v127
	v_mov_b32_e32 v59, v127
	v_mov_b32_e32 v58, v127
	v_mov_b32_e32 v57, v127
	v_mov_b32_e32 v56, v127
	v_mov_b32_e32 v55, v127
	v_mov_b32_e32 v54, v127
	v_mov_b32_e32 v53, v127
	v_mov_b32_e32 v52, v127
	v_mov_b32_e32 v43, v127
	v_mov_b32_e32 v42, v127
	v_mov_b32_e32 v41, v127
	v_mov_b32_e32 v40, v127
	v_mov_b32_e32 v39, v127
	v_mov_b32_e32 v38, v127
	v_mov_b32_e32 v37, v127
	v_mov_b32_e32 v36, v127
	v_mov_b32_e32 v27, v127
	v_mov_b32_e32 v26, v127
	v_mov_b32_e32 v25, v127
	v_mov_b32_e32 v24, v127
	v_mov_b32_e32 v23, v127
	v_mov_b32_e32 v22, v127
	v_mov_b32_e32 v21, v127
	v_mov_b32_e32 v20, v127
	v_mov_b32_e32 v11, v127
	v_mov_b32_e32 v10, v127
	v_mov_b32_e32 v9, v127
	v_mov_b32_e32 v8, v127
	v_mov_b32_e32 v7, v127
	v_mov_b32_e32 v6, v127
	v_mov_b32_e32 v5, v127
	v_mov_b32_e32 v4, v127
	s_cbranch_vccnz .LBB0_1625
	s_add_u32 s44, s44, 0x80
	s_addc_u32 s45, s45, 0
	s_add_u32 s65, s48, 0x100
	s_addc_u32 s67, s49, 0
	s_mov_b32 s48, 0
	s_add_i32 s72, s48, 2
	s_add_u32 s73, s44, 0x80
	s_addc_u32 s49, s45, 0
	s_add_i32 s86, 0, 0x10000
	s_cmp_eq_u32 s57, s48
	s_cselect_b32 s49, s13, s49
	s_cselect_b32 s48, s12, s73
	s_cselect_b32 s77, s41, s67
	s_cselect_b32 s76, s40, s65
	s_add_i32 s73, 0, 0x14000
	v_add_u32_e32 v158, s86, v143
	v_add_u32_e32 v174, s73, v143
	ds_read_b128 v[146:149], v158
	ds_read_b128 v[150:153], v158 offset:1024
	ds_read_b128 v[154:157], v158 offset:2048
	ds_read_b128 v[158:161], v158 offset:3072
	ds_read_b128 v[162:165], v174
	ds_read_b128 v[166:169], v174 offset:1024
	ds_read_b128 v[170:173], v174 offset:2048
	ds_read_b128 v[174:177], v174 offset:3072
	v_lshl_add_u64 v[190:191], s[44:45], 0, v[138:139]
	s_add_i32 m0, s47, 0xc000
	ds_read_b128 v[178:181], v145
	ds_read_b128 v[182:185], v145 offset:1024
	ds_read_b128 v[186:189], v145 offset:2048
	ds_read_b128 v[204:207], v145 offset:3072
	ds_read_b128 v[208:211], v145 offset:4096
	ds_read_b128 v[212:215], v145 offset:5120
	ds_read_b128 v[216:219], v145 offset:6144
	ds_read_b128 v[220:223], v145 offset:7168
	global_load_lds_dwordx4 v[190:191], off
	v_lshl_add_u64 v[190:191], s[44:45], 0, v[140:141]
	s_add_i32 m0, s47, 0xe000
	s_nop 0
	global_load_lds_dwordx4 v[190:191], off
	s_waitcnt vmcnt(8)
	s_waitcnt lgkmcnt(0)
	s_barrier
; #define PG8_STAGE(bufoff, gbase, voff) do { _Pragma("unroll") for (int _i = 0; _i < 2; ++_i) \
;         __builtin_amdgcn_global_load_lds((const unsigned*)((const char*)(gbase) + (voff)[_i]), (PG8_LAS unsigned*)(lds + (bufoff) + ldsw + _i * 8192), 16, 0, 0); } while (0)
; #define PG8_LDA(dst, b, h) do { _Pragma("unroll") for (int m = 0; m < 4; ++m) _Pragma("unroll") for (int k = 0; k < 2; ++k) dst[m][k] = *(const PG8_LAS bf16x8*)(lds + PG8_SA(b, h) + aoff + m * 2048 + k * 1024); } while (0)
; #define PG8_WAIT_V(n) asm volatile("s_waitcnt vmcnt(" #n ")" ::: "memory")
; #define PG8_WAIT_L(n) asm volatile("s_waitcnt lgkmcnt(" #n ")" ::: "memory")
; #define PG8_BAR __builtin_amdgcn_s_barrier()
; #define PG8_SCHED __builtin_amdgcn_sched_barrier(0)
; template <class Epi, class Sched, bool ALIGN_EPI = false, bool SP2 = false, bool I8 = false>
; __device__ __forceinline__ void gemm_phase(PG8_LAS unsigned char* lds, const Gemm g, const Sched& S, const Epi& E) {
;     ...
;             PG8_WAIT_V(8); PG8_WAIT_L(0); PG8_BAR; PG8_MMA(0, 0, At, B0); PG8_MMA(0, 1, At, B1); PG8_BAR; PG8_SCHED;
;             PG8_LDA(At, 0, 1); PG8_STAGE(PG8_SB(0, 0), b2, voffB); PG8_STAGE(PG8_SB(0, 1), b2 + hstep, voffB); PG8_STAGE(PG8_SA(0, 0), a2, voffA);
;             PG8_WAIT_V(8); PG8_WAIT_L(0); PG8_BAR; PG8_MMA(1, 0, At, B0); PG8_MMA(1, 1, At, B1); PG8_BAR; PG8_SCHED;
	s_setprio 1
	s_waitcnt lgkmcnt(0)
	v_mfma_f32_16x16x32_bf16 v[124:127], v[146:149], v[178:181], 0
	v_mfma_f32_16x16x32_bf16 v[124:127], v[150:153], v[182:185], v[124:127]
	v_mfma_f32_16x16x32_bf16 v[112:115], v[150:153], v[204:207], 0
	v_mfma_f32_16x16x32_bf16 v[112:115], v[146:149], v[186:189], v[112:115]
	v_mfma_f32_16x16x32_bf16 v[96:99], v[146:149], v[208:211], 0
	v_mfma_f32_16x16x32_bf16 v[96:99], v[150:153], v[212:215], v[96:99]
	v_mfma_f32_16x16x32_bf16 v[80:83], v[150:153], v[220:223], 0
	v_mfma_f32_16x16x32_bf16 v[80:83], v[146:149], v[216:219], v[80:83]
	v_mfma_f32_16x16x32_bf16 v[76:79], v[154:157], v[216:219], 0
	v_mfma_f32_16x16x32_bf16 v[76:79], v[158:161], v[220:223], v[76:79]
	v_mfma_f32_16x16x32_bf16 v[92:95], v[158:161], v[212:215], 0
	v_mfma_f32_16x16x32_bf16 v[92:95], v[154:157], v[208:211], v[92:95]
	v_mfma_f32_16x16x32_bf16 v[108:111], v[154:157], v[186:189], 0
	v_mfma_f32_16x16x32_bf16 v[108:111], v[158:161], v[204:207], v[108:111]
	v_mfma_f32_16x16x32_bf16 v[128:131], v[158:161], v[182:185], 0
	v_mfma_f32_16x16x32_bf16 v[128:131], v[154:157], v[178:181], v[128:131]
	v_mfma_f32_16x16x32_bf16 v[120:123], v[162:165], v[178:181], 0
	v_mfma_f32_16x16x32_bf16 v[120:123], v[166:169], v[182:185], v[120:123]
	v_mfma_f32_16x16x32_bf16 v[104:107], v[166:169], v[204:207], 0
	v_mfma_f32_16x16x32_bf16 v[104:107], v[162:165], v[186:189], v[104:107]
	v_mfma_f32_16x16x32_bf16 v[88:91], v[162:165], v[208:211], 0
	v_mfma_f32_16x16x32_bf16 v[88:91], v[166:169], v[212:215], v[88:91]
	v_mfma_f32_16x16x32_bf16 v[72:75], v[166:169], v[220:223], 0
	v_mfma_f32_16x16x32_bf16 v[72:75], v[162:165], v[216:219], v[72:75]
	v_mfma_f32_16x16x32_bf16 v[68:71], v[170:173], v[216:219], 0
	v_mfma_f32_16x16x32_bf16 v[68:71], v[174:177], v[220:223], v[68:71]
	v_mfma_f32_16x16x32_bf16 v[84:87], v[174:177], v[212:215], 0
	v_mfma_f32_16x16x32_bf16 v[84:87], v[170:173], v[208:211], v[84:87]
	v_mfma_f32_16x16x32_bf16 v[100:103], v[170:173], v[186:189], 0
	v_mfma_f32_16x16x32_bf16 v[100:103], v[174:177], v[204:207], v[100:103]
	v_mfma_f32_16x16x32_bf16 v[116:119], v[174:177], v[182:185], 0
	v_mfma_f32_16x16x32_bf16 v[116:119], v[170:173], v[178:181], v[116:119]
	s_setprio 0
	s_barrier
	s_add_i32 s86, s86, s28
	v_lshl_add_u64 v[190:191], s[76:77], 0, v[2:3]
	s_mov_b32 m0, s86
	ds_read_b128 v[178:181], v145 offset:16384
	ds_read_b128 v[182:185], v145 offset:17408
	ds_read_b128 v[186:189], v145 offset:18432
	ds_read_b128 v[204:207], v145 offset:19456
	ds_read_b128 v[208:211], v145 offset:20480
	ds_read_b128 v[212:215], v145 offset:21504
	ds_read_b128 v[216:219], v145 offset:22528
	ds_read_b128 v[220:223], v145 offset:23552
	global_load_lds_dwordx4 v[190:191], off
	s_add_i32 m0, s86, 0x2000
	v_lshl_add_u64 v[224:225], s[76:77], 0, v[136:137]
	s_add_u32 s76, s76, s18
	s_addc_u32 s77, s77, s19
	s_add_i32 s73, s73, s28
	global_load_lds_dwordx4 v[224:225], off
	v_lshl_add_u64 v[226:227], s[76:77], 0, v[2:3]
	s_mov_b32 m0, s73
	v_lshl_add_u64 v[228:229], s[76:77], 0, v[136:137]
	global_load_lds_dwordx4 v[226:227], off
	s_add_i32 m0, s73, 0x2000
	v_lshl_add_u64 v[240:241], s[48:49], 0, v[132:133]
	global_load_lds_dwordx4 v[228:229], off
	v_lshl_add_u64 v[242:243], s[48:49], 0, v[134:135]
	s_waitcnt vmcnt(6)
	s_waitcnt lgkmcnt(0)
	s_barrier
	s_setprio 1
	s_waitcnt lgkmcnt(0)
	v_mfma_f32_16x16x32_bf16 v[64:67], v[146:149], v[178:181], 0
	v_mfma_f32_16x16x32_bf16 v[64:67], v[150:153], v[182:185], v[64:67]
	v_mfma_f32_16x16x32_bf16 v[48:51], v[150:153], v[204:207], 0
	v_mfma_f32_16x16x32_bf16 v[48:51], v[146:149], v[186:189], v[48:51]
	v_mfma_f32_16x16x32_bf16 v[32:35], v[146:149], v[208:211], 0
	v_mfma_f32_16x16x32_bf16 v[32:35], v[150:153], v[212:215], v[32:35]
	v_mfma_f32_16x16x32_bf16 v[16:19], v[150:153], v[220:223], 0
	v_mfma_f32_16x16x32_bf16 v[16:19], v[146:149], v[216:219], v[16:19]
	v_mfma_f32_16x16x32_bf16 v[12:15], v[154:157], v[216:219], 0
	v_mfma_f32_16x16x32_bf16 v[12:15], v[158:161], v[220:223], v[12:15]
	v_mfma_f32_16x16x32_bf16 v[28:31], v[158:161], v[212:215], 0
	v_mfma_f32_16x16x32_bf16 v[28:31], v[154:157], v[208:211], v[28:31]
	v_mfma_f32_16x16x32_bf16 v[44:47], v[154:157], v[186:189], 0
	v_mfma_f32_16x16x32_bf16 v[44:47], v[158:161], v[204:207], v[44:47]
	v_mfma_f32_16x16x32_bf16 v[60:63], v[158:161], v[182:185], 0
	v_mfma_f32_16x16x32_bf16 v[60:63], v[154:157], v[178:181], v[60:63]
	v_mfma_f32_16x16x32_bf16 v[56:59], v[162:165], v[178:181], 0
	v_mfma_f32_16x16x32_bf16 v[56:59], v[166:169], v[182:185], v[56:59]
	v_mfma_f32_16x16x32_bf16 v[40:43], v[166:169], v[204:207], 0
	v_mfma_f32_16x16x32_bf16 v[40:43], v[162:165], v[186:189], v[40:43]
	v_mfma_f32_16x16x32_bf16 v[24:27], v[162:165], v[208:211], 0
	v_mfma_f32_16x16x32_bf16 v[24:27], v[166:169], v[212:215], v[24:27]
	v_mfma_f32_16x16x32_bf16 v[8:11], v[166:169], v[220:223], 0
	v_mfma_f32_16x16x32_bf16 v[8:11], v[162:165], v[216:219], v[8:11]
	v_mfma_f32_16x16x32_bf16 v[4:7], v[170:173], v[216:219], 0
	v_mfma_f32_16x16x32_bf16 v[4:7], v[174:177], v[220:223], v[4:7]
	v_mfma_f32_16x16x32_bf16 v[20:23], v[174:177], v[212:215], 0
	v_mfma_f32_16x16x32_bf16 v[20:23], v[170:173], v[208:211], v[20:23]
	v_mfma_f32_16x16x32_bf16 v[36:39], v[170:173], v[186:189], 0
	v_mfma_f32_16x16x32_bf16 v[36:39], v[174:177], v[204:207], v[36:39]
	v_mfma_f32_16x16x32_bf16 v[52:55], v[174:177], v[182:185], 0
	v_mfma_f32_16x16x32_bf16 v[52:55], v[170:173], v[178:181], v[52:55]
	s_setprio 0
	s_barrier
; #define PG8_STAGE(bufoff, gbase, voff) do { _Pragma("unroll") for (int _i = 0; _i < 2; ++_i) \
;         __builtin_amdgcn_global_load_lds((const unsigned*)((const char*)(gbase) + (voff)[_i]), (PG8_LAS unsigned*)(lds + (bufoff) + ldsw + _i * 8192), 16, 0, 0); } while (0)
; #define PG8_LDA(dst, b, h) do { _Pragma("unroll") for (int m = 0; m < 4; ++m) _Pragma("unroll") for (int k = 0; k < 2; ++k) dst[m][k] = *(const PG8_LAS bf16x8*)(lds + PG8_SA(b, h) + aoff + m * 2048 + k * 1024); } while (0)
; #define PG8_LDB(dst, b, h) do { _Pragma("unroll") for (int n = 0; n < 2; ++n) _Pragma("unroll") for (int k = 0; k < 2; ++k) dst[n][k] = *(const PG8_LAS bf16x8*)(lds + PG8_SB(b, h) + boff + n * 2048 + k * 1024); } while (0)
; #define PG8_WAIT_V(n) asm volatile("s_waitcnt vmcnt(" #n ")" ::: "memory")
; #define PG8_WAIT_L(n) asm volatile("s_waitcnt lgkmcnt(" #n ")" ::: "memory")
; #define PG8_BAR __builtin_amdgcn_s_barrier()
; #define PG8_SCHED __builtin_amdgcn_sched_barrier(0)
; template <class Epi, class Sched, bool ALIGN_EPI = false, bool SP2 = false, bool I8 = false>
; __device__ __forceinline__ void gemm_phase(PG8_LAS unsigned char* lds, const Gemm g, const Sched& S, const Epi& E) {
;     ...
;             PG8_LDB(B0, 1, 0); PG8_LDB(B1, 1, 1); PG8_SCHED; PG8_LDA(At, 1, 0); PG8_STAGE(PG8_SA(0, 1), a2 + hstep, voffA);
;             PG8_WAIT_V(8); PG8_WAIT_L(0); PG8_BAR; PG8_MMA(0, 0, At, B0); PG8_MMA(0, 1, At, B1); PG8_BAR; PG8_SCHED;
;             PG8_LDA(At, 1, 1); PG8_STAGE(PG8_SB(1, 0), b3, voffB); PG8_STAGE(PG8_SB(1, 1), b3 + hstep, voffB); PG8_STAGE(PG8_SA(1, 0), a3, voffA);
;             PG8_WAIT_V(8); PG8_WAIT_L(0); PG8_BAR; PG8_MMA(1, 0, At, B0); PG8_MMA(1, 1, At, B1); PG8_BAR; PG8_SCHED;
	s_add_i32 s73, 0, 0x18000
	s_add_i32 s76, 0, 0x1c000
	v_add_u32_e32 v158, s73, v143
	v_add_u32_e32 v174, s76, v143
	ds_read_b128 v[146:149], v158
	ds_read_b128 v[150:153], v158 offset:1024
	ds_read_b128 v[154:157], v158 offset:2048
	ds_read_b128 v[158:161], v158 offset:3072
	ds_read_b128 v[162:165], v174
	ds_read_b128 v[166:169], v174 offset:1024
	ds_read_b128 v[170:173], v174 offset:2048
	ds_read_b128 v[174:177], v174 offset:3072
	s_add_u32 s48, s48, s18
	s_addc_u32 s49, s49, s19
	s_mov_b32 m0, s51
	v_lshl_add_u64 v[244:245], s[48:49], 0, v[132:133]
	ds_read_b128 v[178:181], v145 offset:32768
	ds_read_b128 v[182:185], v145 offset:33792
	ds_read_b128 v[186:189], v145 offset:34816
	ds_read_b128 v[204:207], v145 offset:35840
	ds_read_b128 v[208:211], v145 offset:36864
	ds_read_b128 v[212:215], v145 offset:37888
	ds_read_b128 v[216:219], v145 offset:38912
	ds_read_b128 v[220:223], v145 offset:39936
	s_mov_b32 m0, s47
	s_nop 0
	global_load_lds_dwordx4 v[240:241], off
	s_mov_b32 m0, s50
	s_nop 0
	global_load_lds_dwordx4 v[242:243], off
	s_mov_b32 m0, s51
	s_nop 0
	global_load_lds_dwordx4 v[244:245], off
	v_lshl_add_u64 v[244:245], s[48:49], 0, v[134:135]
	s_mov_b32 m0, s52
	s_nop 0
	global_load_lds_dwordx4 v[244:245], off
	s_waitcnt vmcnt(8)
	s_waitcnt lgkmcnt(0)
	s_barrier
	s_setprio 1
	s_waitcnt lgkmcnt(0)
	v_mfma_f32_16x16x32_bf16 v[124:127], v[146:149], v[178:181], v[124:127]
	v_mfma_f32_16x16x32_bf16 v[124:127], v[150:153], v[182:185], v[124:127]
	v_mfma_f32_16x16x32_bf16 v[112:115], v[150:153], v[204:207], v[112:115]
	v_mfma_f32_16x16x32_bf16 v[112:115], v[146:149], v[186:189], v[112:115]
	v_mfma_f32_16x16x32_bf16 v[96:99], v[146:149], v[208:211], v[96:99]
	v_mfma_f32_16x16x32_bf16 v[96:99], v[150:153], v[212:215], v[96:99]
	v_mfma_f32_16x16x32_bf16 v[80:83], v[150:153], v[220:223], v[80:83]
	v_mfma_f32_16x16x32_bf16 v[80:83], v[146:149], v[216:219], v[80:83]
	v_mfma_f32_16x16x32_bf16 v[76:79], v[154:157], v[216:219], v[76:79]
	v_mfma_f32_16x16x32_bf16 v[76:79], v[158:161], v[220:223], v[76:79]
	v_mfma_f32_16x16x32_bf16 v[92:95], v[158:161], v[212:215], v[92:95]
	v_mfma_f32_16x16x32_bf16 v[92:95], v[154:157], v[208:211], v[92:95]
	v_mfma_f32_16x16x32_bf16 v[108:111], v[154:157], v[186:189], v[108:111]
	v_mfma_f32_16x16x32_bf16 v[108:111], v[158:161], v[204:207], v[108:111]
	v_mfma_f32_16x16x32_bf16 v[128:131], v[158:161], v[182:185], v[128:131]
	v_mfma_f32_16x16x32_bf16 v[128:131], v[154:157], v[178:181], v[128:131]
	v_mfma_f32_16x16x32_bf16 v[120:123], v[162:165], v[178:181], v[120:123]
	v_mfma_f32_16x16x32_bf16 v[120:123], v[166:169], v[182:185], v[120:123]
	v_mfma_f32_16x16x32_bf16 v[104:107], v[166:169], v[204:207], v[104:107]
	v_mfma_f32_16x16x32_bf16 v[104:107], v[162:165], v[186:189], v[104:107]
	v_mfma_f32_16x16x32_bf16 v[88:91], v[162:165], v[208:211], v[88:91]
	v_mfma_f32_16x16x32_bf16 v[88:91], v[166:169], v[212:215], v[88:91]
	v_mfma_f32_16x16x32_bf16 v[72:75], v[166:169], v[220:223], v[72:75]
	v_mfma_f32_16x16x32_bf16 v[72:75], v[162:165], v[216:219], v[72:75]
	v_mfma_f32_16x16x32_bf16 v[68:71], v[170:173], v[216:219], v[68:71]
	v_mfma_f32_16x16x32_bf16 v[68:71], v[174:177], v[220:223], v[68:71]
	v_mfma_f32_16x16x32_bf16 v[84:87], v[174:177], v[212:215], v[84:87]
	v_mfma_f32_16x16x32_bf16 v[84:87], v[170:173], v[208:211], v[84:87]
	v_mfma_f32_16x16x32_bf16 v[100:103], v[170:173], v[186:189], v[100:103]
	v_mfma_f32_16x16x32_bf16 v[100:103], v[174:177], v[204:207], v[100:103]
	v_mfma_f32_16x16x32_bf16 v[116:119], v[174:177], v[182:185], v[116:119]
	v_mfma_f32_16x16x32_bf16 v[116:119], v[170:173], v[178:181], v[116:119]
	s_setprio 0
	s_barrier
	s_add_i32 s48, s73, s28
	v_lshl_add_u64 v[190:191], v[190:191], 0, s[84:85]
	s_mov_b32 m0, s48
	ds_read_b128 v[178:181], v145 offset:49152
	ds_read_b128 v[182:185], v145 offset:50176
	ds_read_b128 v[186:189], v145 offset:51200
	ds_read_b128 v[204:207], v145 offset:52224
	ds_read_b128 v[208:211], v145 offset:53248
	ds_read_b128 v[212:215], v145 offset:54272
	ds_read_b128 v[216:219], v145 offset:55296
	ds_read_b128 v[220:223], v145 offset:56320
	global_load_lds_dwordx4 v[190:191], off
	v_lshl_add_u64 v[190:191], v[224:225], 0, s[84:85]
	s_add_i32 m0, s48, 0x2000
	s_add_i32 s48, s76, s28
	global_load_lds_dwordx4 v[190:191], off
	v_lshl_add_u64 v[190:191], v[226:227], 0, s[84:85]
	s_mov_b32 m0, s48
	s_nop 0
	global_load_lds_dwordx4 v[190:191], off
	v_lshl_add_u64 v[190:191], v[228:229], 0, s[84:85]
	s_add_i32 m0, s48, 0x2000
	s_nop 0
	global_load_lds_dwordx4 v[190:191], off
	v_lshl_add_u64 v[190:191], v[240:241], 0, s[84:85]
	s_mov_b32 m0, s55
	s_nop 0
	global_load_lds_dwordx4 v[190:191], off
	v_lshl_add_u64 v[190:191], v[242:243], 0, s[84:85]
	s_mov_b32 m0, s56
	s_nop 0
	global_load_lds_dwordx4 v[190:191], off
	s_waitcnt vmcnt(8)
	s_waitcnt lgkmcnt(0)
	s_barrier
; #define PG8_STAGE(bufoff, gbase, voff) do { _Pragma("unroll") for (int _i = 0; _i < 2; ++_i) \
;         __builtin_amdgcn_global_load_lds((const unsigned*)((const char*)(gbase) + (voff)[_i]), (PG8_LAS unsigned*)(lds + (bufoff) + ldsw + _i * 8192), 16, 0, 0); } while (0)
; #define PG8_LDA(dst, b, h) do { _Pragma("unroll") for (int m = 0; m < 4; ++m) _Pragma("unroll") for (int k = 0; k < 2; ++k) dst[m][k] = *(const PG8_LAS bf16x8*)(lds + PG8_SA(b, h) + aoff + m * 2048 + k * 1024); } while (0)
; #define PG8_WAIT_V(n) asm volatile("s_waitcnt vmcnt(" #n ")" ::: "memory")
; #define PG8_WAIT_L(n) asm volatile("s_waitcnt lgkmcnt(" #n ")" ::: "memory")
; #define PG8_BAR __builtin_amdgcn_s_barrier()
; template <class Epi, class Sched, bool ALIGN_EPI = false, bool SP2 = false, bool I8 = false>
; __device__ __forceinline__ void gemm_phase(PG8_LAS unsigned char* lds, const Gemm g, const Sched& S, const Epi& E) {
;     ...
;         for (int t = 0; t < nt; t += 2) {
;             const bool last = (t == nt - 2);
;             const char* a1 = cA + (size_t)(t + 1) * kstep;
;             const char* a2 = last ? nA : cA + (size_t)(t + 2) * kstep; const char* b2 = last ? nB : cB + (size_t)(t + 2) * kstep;
;             const char* a3 = a2 + kstep; const char* b3 = b2 + kstep;
;             if (last && has_next) S.a_ready(nxt);
;             if constexpr (SP2) {
;             PG8_LDB(B0, 0, 0); PG8_LDB(B1, 0, 1); PG8_SCHED; PG8_LDA(At, 0, 0); PG8_STAGE(PG8_SA(1, 1), a1 + hstep, voffA);
;             PG8_WAIT_V(8); PG8_WAIT_L(0); PG8_BAR; PG8_MMA(0, 0, At, B0); PG8_MMA(0, 1, At, B1); PG8_BAR; PG8_SCHED;
;             PG8_LDA(At, 0, 1); PG8_STAGE(PG8_SB(0, 0), b2, voffB); PG8_STAGE(PG8_SB(0, 1), b2 + hstep, voffB); PG8_STAGE(PG8_SA(0, 0), a2, voffA);
;             PG8_WAIT_V(8); PG8_WAIT_L(0); PG8_BAR; PG8_MMA(1, 0, At, B0); PG8_MMA(1, 1, At, B1); PG8_BAR; PG8_SCHED;
;             PG8_LDB(B0, 1, 0); PG8_LDB(B1, 1, 1); PG8_SCHED; PG8_LDA(At, 1, 0); PG8_STAGE(PG8_SA(0, 1), a2 + hstep, voffA);
;             PG8_WAIT_V(8); PG8_WAIT_L(0); PG8_BAR; PG8_MMA(0, 0, At, B0); PG8_MMA(0, 1, At, B1); PG8_BAR; PG8_SCHED;
;             PG8_LDA(At, 1, 1); PG8_STAGE(PG8_SB(1, 0), b3, voffB); PG8_STAGE(PG8_SB(1, 1), b3 + hstep, voffB); PG8_STAGE(PG8_SA(1, 0), a3, voffA);
;             PG8_WAIT_V(8); PG8_WAIT_L(0); PG8_BAR; PG8_MMA(1, 0, At, B0); PG8_MMA(1, 1, At, B1); PG8_BAR; PG8_SCHED;
	s_setprio 1
	s_waitcnt lgkmcnt(0)
	v_mfma_f32_16x16x32_bf16 v[64:67], v[146:149], v[178:181], v[64:67]
	v_mfma_f32_16x16x32_bf16 v[64:67], v[150:153], v[182:185], v[64:67]
	v_mfma_f32_16x16x32_bf16 v[48:51], v[150:153], v[204:207], v[48:51]
	v_mfma_f32_16x16x32_bf16 v[48:51], v[146:149], v[186:189], v[48:51]
	v_mfma_f32_16x16x32_bf16 v[32:35], v[146:149], v[208:211], v[32:35]
	v_mfma_f32_16x16x32_bf16 v[32:35], v[150:153], v[212:215], v[32:35]
	v_mfma_f32_16x16x32_bf16 v[16:19], v[150:153], v[220:223], v[16:19]
	v_mfma_f32_16x16x32_bf16 v[16:19], v[146:149], v[216:219], v[16:19]
	v_mfma_f32_16x16x32_bf16 v[12:15], v[154:157], v[216:219], v[12:15]
	v_mfma_f32_16x16x32_bf16 v[12:15], v[158:161], v[220:223], v[12:15]
	v_mfma_f32_16x16x32_bf16 v[28:31], v[158:161], v[212:215], v[28:31]
	v_mfma_f32_16x16x32_bf16 v[28:31], v[154:157], v[208:211], v[28:31]
	v_mfma_f32_16x16x32_bf16 v[44:47], v[154:157], v[186:189], v[44:47]
	v_mfma_f32_16x16x32_bf16 v[44:47], v[158:161], v[204:207], v[44:47]
	v_mfma_f32_16x16x32_bf16 v[60:63], v[158:161], v[182:185], v[60:63]
	v_mfma_f32_16x16x32_bf16 v[60:63], v[154:157], v[178:181], v[60:63]
	v_mfma_f32_16x16x32_bf16 v[56:59], v[162:165], v[178:181], v[56:59]
	v_mfma_f32_16x16x32_bf16 v[56:59], v[166:169], v[182:185], v[56:59]
	v_mfma_f32_16x16x32_bf16 v[40:43], v[166:169], v[204:207], v[40:43]
	v_mfma_f32_16x16x32_bf16 v[40:43], v[162:165], v[186:189], v[40:43]
	v_mfma_f32_16x16x32_bf16 v[24:27], v[162:165], v[208:211], v[24:27]
	v_mfma_f32_16x16x32_bf16 v[24:27], v[166:169], v[212:215], v[24:27]
	v_mfma_f32_16x16x32_bf16 v[8:11], v[166:169], v[220:223], v[8:11]
	v_mfma_f32_16x16x32_bf16 v[8:11], v[162:165], v[216:219], v[8:11]
	v_mfma_f32_16x16x32_bf16 v[4:7], v[170:173], v[216:219], v[4:7]
	v_mfma_f32_16x16x32_bf16 v[4:7], v[174:177], v[220:223], v[4:7]
	v_mfma_f32_16x16x32_bf16 v[20:23], v[174:177], v[212:215], v[20:23]
	v_mfma_f32_16x16x32_bf16 v[20:23], v[170:173], v[208:211], v[20:23]
	v_mfma_f32_16x16x32_bf16 v[36:39], v[170:173], v[186:189], v[36:39]
	v_mfma_f32_16x16x32_bf16 v[36:39], v[174:177], v[204:207], v[36:39]
	v_mfma_f32_16x16x32_bf16 v[52:55], v[174:177], v[182:185], v[52:55]
	v_mfma_f32_16x16x32_bf16 v[52:55], v[170:173], v[178:181], v[52:55]
	s_setprio 0
	s_barrier
	s_add_u32 s44, s44, 0x100
	s_addc_u32 s45, s45, 0
	s_add_u32 s65, s65, 0x100
	s_addc_u32 s67, s67, 0
	s_cmp_ge_i32 s72, s53
	s_mov_b32 s48, s72
	s_cbranch_scc1 .Lkloop_exit_4
.LBB0_1623:
	s_add_i32 s72, s48, 2
	s_add_u32 s73, s44, 0x80
	s_addc_u32 s49, s45, 0
	s_add_i32 s86, 0, 0x10000
	s_cmp_eq_u32 s57, s48
	s_cselect_b32 s49, s13, s49
	s_cselect_b32 s48, s12, s73
	s_cselect_b32 s77, s41, s67
	s_cselect_b32 s76, s40, s65
	s_add_i32 s73, 0, 0x14000
	v_add_u32_e32 v158, s86, v143
	v_add_u32_e32 v174, s73, v143
	ds_read_b128 v[146:149], v158
	ds_read_b128 v[150:153], v158 offset:1024
	ds_read_b128 v[154:157], v158 offset:2048
	ds_read_b128 v[158:161], v158 offset:3072
	ds_read_b128 v[162:165], v174
	ds_read_b128 v[166:169], v174 offset:1024
	ds_read_b128 v[170:173], v174 offset:2048
	ds_read_b128 v[174:177], v174 offset:3072
	v_lshl_add_u64 v[190:191], s[44:45], 0, v[138:139]
	s_add_i32 m0, s47, 0xc000
	ds_read_b128 v[178:181], v145
	ds_read_b128 v[182:185], v145 offset:1024
	ds_read_b128 v[186:189], v145 offset:2048
	ds_read_b128 v[204:207], v145 offset:3072
	ds_read_b128 v[208:211], v145 offset:4096
	ds_read_b128 v[212:215], v145 offset:5120
	ds_read_b128 v[216:219], v145 offset:6144
	ds_read_b128 v[220:223], v145 offset:7168
	global_load_lds_dwordx4 v[190:191], off
	v_lshl_add_u64 v[190:191], s[44:45], 0, v[140:141]
	s_add_i32 m0, s47, 0xe000
	s_nop 0
	global_load_lds_dwordx4 v[190:191], off
	s_waitcnt vmcnt(8)
	s_waitcnt lgkmcnt(0)
	s_barrier
	s_setprio 1
	s_waitcnt lgkmcnt(0)
	v_mfma_f32_16x16x32_bf16 v[124:127], v[146:149], v[178:181], v[124:127]
	v_mfma_f32_16x16x32_bf16 v[124:127], v[150:153], v[182:185], v[124:127]
	v_mfma_f32_16x16x32_bf16 v[112:115], v[150:153], v[204:207], v[112:115]
	v_mfma_f32_16x16x32_bf16 v[112:115], v[146:149], v[186:189], v[112:115]
	v_mfma_f32_16x16x32_bf16 v[96:99], v[146:149], v[208:211], v[96:99]
	v_mfma_f32_16x16x32_bf16 v[96:99], v[150:153], v[212:215], v[96:99]
	v_mfma_f32_16x16x32_bf16 v[80:83], v[150:153], v[220:223], v[80:83]
	v_mfma_f32_16x16x32_bf16 v[80:83], v[146:149], v[216:219], v[80:83]
	v_mfma_f32_16x16x32_bf16 v[76:79], v[154:157], v[216:219], v[76:79]
	v_mfma_f32_16x16x32_bf16 v[76:79], v[158:161], v[220:223], v[76:79]
	v_mfma_f32_16x16x32_bf16 v[92:95], v[158:161], v[212:215], v[92:95]
	v_mfma_f32_16x16x32_bf16 v[92:95], v[154:157], v[208:211], v[92:95]
	v_mfma_f32_16x16x32_bf16 v[108:111], v[154:157], v[186:189], v[108:111]
	v_mfma_f32_16x16x32_bf16 v[108:111], v[158:161], v[204:207], v[108:111]
	v_mfma_f32_16x16x32_bf16 v[128:131], v[158:161], v[182:185], v[128:131]
	v_mfma_f32_16x16x32_bf16 v[128:131], v[154:157], v[178:181], v[128:131]
	v_mfma_f32_16x16x32_bf16 v[120:123], v[162:165], v[178:181], v[120:123]
	v_mfma_f32_16x16x32_bf16 v[120:123], v[166:169], v[182:185], v[120:123]
	v_mfma_f32_16x16x32_bf16 v[104:107], v[166:169], v[204:207], v[104:107]
	v_mfma_f32_16x16x32_bf16 v[104:107], v[162:165], v[186:189], v[104:107]
	v_mfma_f32_16x16x32_bf16 v[88:91], v[162:165], v[208:211], v[88:91]
	v_mfma_f32_16x16x32_bf16 v[88:91], v[166:169], v[212:215], v[88:91]
	v_mfma_f32_16x16x32_bf16 v[72:75], v[166:169], v[220:223], v[72:75]
	v_mfma_f32_16x16x32_bf16 v[72:75], v[162:165], v[216:219], v[72:75]
	v_mfma_f32_16x16x32_bf16 v[68:71], v[170:173], v[216:219], v[68:71]
	v_mfma_f32_16x16x32_bf16 v[68:71], v[174:177], v[220:223], v[68:71]
	v_mfma_f32_16x16x32_bf16 v[84:87], v[174:177], v[212:215], v[84:87]
	v_mfma_f32_16x16x32_bf16 v[84:87], v[170:173], v[208:211], v[84:87]
	v_mfma_f32_16x16x32_bf16 v[100:103], v[170:173], v[186:189], v[100:103]
	v_mfma_f32_16x16x32_bf16 v[100:103], v[174:177], v[204:207], v[100:103]
	v_mfma_f32_16x16x32_bf16 v[116:119], v[174:177], v[182:185], v[116:119]
	v_mfma_f32_16x16x32_bf16 v[116:119], v[170:173], v[178:181], v[116:119]
	s_setprio 0
	s_barrier
; #define PG8_STAGE(bufoff, gbase, voff) do { _Pragma("unroll") for (int _i = 0; _i < 2; ++_i) \
;         __builtin_amdgcn_global_load_lds((const unsigned*)((const char*)(gbase) + (voff)[_i]), (PG8_LAS unsigned*)(lds + (bufoff) + ldsw + _i * 8192), 16, 0, 0); } while (0)
; #define PG8_LDA(dst, b, h) do { _Pragma("unroll") for (int m = 0; m < 4; ++m) _Pragma("unroll") for (int k = 0; k < 2; ++k) dst[m][k] = *(const PG8_LAS bf16x8*)(lds + PG8_SA(b, h) + aoff + m * 2048 + k * 1024); } while (0)
; #define PG8_LDB(dst, b, h) do { _Pragma("unroll") for (int n = 0; n < 2; ++n) _Pragma("unroll") for (int k = 0; k < 2; ++k) dst[n][k] = *(const PG8_LAS bf16x8*)(lds + PG8_SB(b, h) + boff + n * 2048 + k * 1024); } while (0)
; #define PG8_WAIT_V(n) asm volatile("s_waitcnt vmcnt(" #n ")" ::: "memory")
; #define PG8_WAIT_L(n) asm volatile("s_waitcnt lgkmcnt(" #n ")" ::: "memory")
; #define PG8_BAR __builtin_amdgcn_s_barrier()
; #define PG8_SCHED __builtin_amdgcn_sched_barrier(0)
; template <class Epi, class Sched, bool ALIGN_EPI = false, bool SP2 = false, bool I8 = false>
; __device__ __forceinline__ void gemm_phase(PG8_LAS unsigned char* lds, const Gemm g, const Sched& S, const Epi& E) {
;     ...
;             PG8_LDA(At, 0, 1); PG8_STAGE(PG8_SB(0, 0), b2, voffB); PG8_STAGE(PG8_SB(0, 1), b2 + hstep, voffB); PG8_STAGE(PG8_SA(0, 0), a2, voffA);
;             PG8_WAIT_V(8); PG8_WAIT_L(0); PG8_BAR; PG8_MMA(1, 0, At, B0); PG8_MMA(1, 1, At, B1); PG8_BAR; PG8_SCHED;
;             PG8_LDB(B0, 1, 0); PG8_LDB(B1, 1, 1); PG8_SCHED; PG8_LDA(At, 1, 0); PG8_STAGE(PG8_SA(0, 1), a2 + hstep, voffA);
;             PG8_WAIT_V(8); PG8_WAIT_L(0); PG8_BAR; PG8_MMA(0, 0, At, B0); PG8_MMA(0, 1, At, B1); PG8_BAR; PG8_SCHED;
;             PG8_LDA(At, 1, 1); PG8_STAGE(PG8_SB(1, 0), b3, voffB); PG8_STAGE(PG8_SB(1, 1), b3 + hstep, voffB); PG8_STAGE(PG8_SA(1, 0), a3, voffA);
	s_add_i32 s86, s86, s28
	v_lshl_add_u64 v[190:191], s[76:77], 0, v[2:3]
	s_mov_b32 m0, s86
	ds_read_b128 v[178:181], v145 offset:16384
	ds_read_b128 v[182:185], v145 offset:17408
	ds_read_b128 v[186:189], v145 offset:18432
	ds_read_b128 v[204:207], v145 offset:19456
	ds_read_b128 v[208:211], v145 offset:20480
	ds_read_b128 v[212:215], v145 offset:21504
	ds_read_b128 v[216:219], v145 offset:22528
	ds_read_b128 v[220:223], v145 offset:23552
	global_load_lds_dwordx4 v[190:191], off
	s_add_i32 m0, s86, 0x2000
	v_lshl_add_u64 v[224:225], s[76:77], 0, v[136:137]
	s_add_u32 s76, s76, s18
	s_addc_u32 s77, s77, s19
	s_add_i32 s73, s73, s28
	global_load_lds_dwordx4 v[224:225], off
	v_lshl_add_u64 v[226:227], s[76:77], 0, v[2:3]
	s_mov_b32 m0, s73
	v_lshl_add_u64 v[228:229], s[76:77], 0, v[136:137]
	global_load_lds_dwordx4 v[226:227], off
	s_add_i32 m0, s73, 0x2000
	v_lshl_add_u64 v[240:241], s[48:49], 0, v[132:133]
	global_load_lds_dwordx4 v[228:229], off
	v_lshl_add_u64 v[242:243], s[48:49], 0, v[134:135]
	s_waitcnt vmcnt(6)
	s_waitcnt lgkmcnt(0)
	s_barrier
	s_setprio 1
	s_waitcnt lgkmcnt(0)
	v_mfma_f32_16x16x32_bf16 v[64:67], v[146:149], v[178:181], v[64:67]
	v_mfma_f32_16x16x32_bf16 v[64:67], v[150:153], v[182:185], v[64:67]
	v_mfma_f32_16x16x32_bf16 v[48:51], v[150:153], v[204:207], v[48:51]
	v_mfma_f32_16x16x32_bf16 v[48:51], v[146:149], v[186:189], v[48:51]
	v_mfma_f32_16x16x32_bf16 v[32:35], v[146:149], v[208:211], v[32:35]
	v_mfma_f32_16x16x32_bf16 v[32:35], v[150:153], v[212:215], v[32:35]
	v_mfma_f32_16x16x32_bf16 v[16:19], v[150:153], v[220:223], v[16:19]
	v_mfma_f32_16x16x32_bf16 v[16:19], v[146:149], v[216:219], v[16:19]
	v_mfma_f32_16x16x32_bf16 v[12:15], v[154:157], v[216:219], v[12:15]
	v_mfma_f32_16x16x32_bf16 v[12:15], v[158:161], v[220:223], v[12:15]
	v_mfma_f32_16x16x32_bf16 v[28:31], v[158:161], v[212:215], v[28:31]
	v_mfma_f32_16x16x32_bf16 v[28:31], v[154:157], v[208:211], v[28:31]
	v_mfma_f32_16x16x32_bf16 v[44:47], v[154:157], v[186:189], v[44:47]
	v_mfma_f32_16x16x32_bf16 v[44:47], v[158:161], v[204:207], v[44:47]
	v_mfma_f32_16x16x32_bf16 v[60:63], v[158:161], v[182:185], v[60:63]
	v_mfma_f32_16x16x32_bf16 v[60:63], v[154:157], v[178:181], v[60:63]
	v_mfma_f32_16x16x32_bf16 v[56:59], v[162:165], v[178:181], v[56:59]
	v_mfma_f32_16x16x32_bf16 v[56:59], v[166:169], v[182:185], v[56:59]
	v_mfma_f32_16x16x32_bf16 v[40:43], v[166:169], v[204:207], v[40:43]
	v_mfma_f32_16x16x32_bf16 v[40:43], v[162:165], v[186:189], v[40:43]
	v_mfma_f32_16x16x32_bf16 v[24:27], v[162:165], v[208:211], v[24:27]
	v_mfma_f32_16x16x32_bf16 v[24:27], v[166:169], v[212:215], v[24:27]
	v_mfma_f32_16x16x32_bf16 v[8:11], v[166:169], v[220:223], v[8:11]
	v_mfma_f32_16x16x32_bf16 v[8:11], v[162:165], v[216:219], v[8:11]
	v_mfma_f32_16x16x32_bf16 v[4:7], v[170:173], v[216:219], v[4:7]
	v_mfma_f32_16x16x32_bf16 v[4:7], v[174:177], v[220:223], v[4:7]
	v_mfma_f32_16x16x32_bf16 v[20:23], v[174:177], v[212:215], v[20:23]
	v_mfma_f32_16x16x32_bf16 v[20:23], v[170:173], v[208:211], v[20:23]
	v_mfma_f32_16x16x32_bf16 v[36:39], v[170:173], v[186:189], v[36:39]
	v_mfma_f32_16x16x32_bf16 v[36:39], v[174:177], v[204:207], v[36:39]
	v_mfma_f32_16x16x32_bf16 v[52:55], v[174:177], v[182:185], v[52:55]
	v_mfma_f32_16x16x32_bf16 v[52:55], v[170:173], v[178:181], v[52:55]
	s_setprio 0
	s_barrier
	s_add_i32 s73, 0, 0x18000
	s_add_i32 s76, 0, 0x1c000
	v_add_u32_e32 v158, s73, v143
	v_add_u32_e32 v174, s76, v143
	ds_read_b128 v[146:149], v158
	ds_read_b128 v[150:153], v158 offset:1024
	ds_read_b128 v[154:157], v158 offset:2048
	ds_read_b128 v[158:161], v158 offset:3072
	ds_read_b128 v[162:165], v174
	ds_read_b128 v[166:169], v174 offset:1024
	ds_read_b128 v[170:173], v174 offset:2048
	ds_read_b128 v[174:177], v174 offset:3072
	s_add_u32 s48, s48, s18
	s_addc_u32 s49, s49, s19
	s_mov_b32 m0, s51
	v_lshl_add_u64 v[244:245], s[48:49], 0, v[132:133]
	ds_read_b128 v[178:181], v145 offset:32768
	ds_read_b128 v[182:185], v145 offset:33792
	ds_read_b128 v[186:189], v145 offset:34816
	ds_read_b128 v[204:207], v145 offset:35840
	ds_read_b128 v[208:211], v145 offset:36864
	ds_read_b128 v[212:215], v145 offset:37888
	ds_read_b128 v[216:219], v145 offset:38912
	ds_read_b128 v[220:223], v145 offset:39936
	s_mov_b32 m0, s47
	s_nop 0
	global_load_lds_dwordx4 v[240:241], off
	s_mov_b32 m0, s50
	s_nop 0
	global_load_lds_dwordx4 v[242:243], off
	s_mov_b32 m0, s51
	s_nop 0
	global_load_lds_dwordx4 v[244:245], off
	v_lshl_add_u64 v[244:245], s[48:49], 0, v[134:135]
	s_mov_b32 m0, s52
	s_nop 0
	global_load_lds_dwordx4 v[244:245], off
	s_waitcnt vmcnt(8)
	s_waitcnt lgkmcnt(0)
	s_barrier
; #define PG8_STAGE(bufoff, gbase, voff) do { _Pragma("unroll") for (int _i = 0; _i < 2; ++_i) \
;         __builtin_amdgcn_global_load_lds((const unsigned*)((const char*)(gbase) + (voff)[_i]), (PG8_LAS unsigned*)(lds + (bufoff) + ldsw + _i * 8192), 16, 0, 0); } while (0)
; #define PG8_LDA(dst, b, h) do { _Pragma("unroll") for (int m = 0; m < 4; ++m) _Pragma("unroll") for (int k = 0; k < 2; ++k) dst[m][k] = *(const PG8_LAS bf16x8*)(lds + PG8_SA(b, h) + aoff + m * 2048 + k * 1024); } while (0)
; #define PG8_WAIT_V(n) asm volatile("s_waitcnt vmcnt(" #n ")" ::: "memory")
; #define PG8_WAIT_L(n) asm volatile("s_waitcnt lgkmcnt(" #n ")" ::: "memory")
; #define PG8_BAR __builtin_amdgcn_s_barrier()
; #define PG8_SCHED __builtin_amdgcn_sched_barrier(0)
; template <class Epi, class Sched, bool ALIGN_EPI = false, bool SP2 = false, bool I8 = false>
; __device__ __forceinline__ void gemm_phase(PG8_LAS unsigned char* lds, const Gemm g, const Sched& S, const Epi& E) {
;     ...
;             PG8_WAIT_V(8); PG8_WAIT_L(0); PG8_BAR; PG8_MMA(0, 0, At, B0); PG8_MMA(0, 1, At, B1); PG8_BAR; PG8_SCHED;
;             PG8_LDA(At, 1, 1); PG8_STAGE(PG8_SB(1, 0), b3, voffB); PG8_STAGE(PG8_SB(1, 1), b3 + hstep, voffB); PG8_STAGE(PG8_SA(1, 0), a3, voffA);
;             PG8_WAIT_V(8); PG8_WAIT_L(0); PG8_BAR; PG8_MMA(1, 0, At, B0); PG8_MMA(1, 1, At, B1); PG8_BAR; PG8_SCHED;
	s_setprio 1
	s_waitcnt lgkmcnt(0)
	v_mfma_f32_16x16x32_bf16 v[124:127], v[146:149], v[178:181], v[124:127]
	v_mfma_f32_16x16x32_bf16 v[124:127], v[150:153], v[182:185], v[124:127]
	v_mfma_f32_16x16x32_bf16 v[112:115], v[150:153], v[204:207], v[112:115]
	v_mfma_f32_16x16x32_bf16 v[112:115], v[146:149], v[186:189], v[112:115]
	v_mfma_f32_16x16x32_bf16 v[96:99], v[146:149], v[208:211], v[96:99]
	v_mfma_f32_16x16x32_bf16 v[96:99], v[150:153], v[212:215], v[96:99]
	v_mfma_f32_16x16x32_bf16 v[80:83], v[150:153], v[220:223], v[80:83]
	v_mfma_f32_16x16x32_bf16 v[80:83], v[146:149], v[216:219], v[80:83]
	v_mfma_f32_16x16x32_bf16 v[76:79], v[154:157], v[216:219], v[76:79]
	v_mfma_f32_16x16x32_bf16 v[76:79], v[158:161], v[220:223], v[76:79]
	v_mfma_f32_16x16x32_bf16 v[92:95], v[158:161], v[212:215], v[92:95]
	v_mfma_f32_16x16x32_bf16 v[92:95], v[154:157], v[208:211], v[92:95]
	v_mfma_f32_16x16x32_bf16 v[108:111], v[154:157], v[186:189], v[108:111]
	v_mfma_f32_16x16x32_bf16 v[108:111], v[158:161], v[204:207], v[108:111]
	v_mfma_f32_16x16x32_bf16 v[128:131], v[158:161], v[182:185], v[128:131]
	v_mfma_f32_16x16x32_bf16 v[128:131], v[154:157], v[178:181], v[128:131]
	v_mfma_f32_16x16x32_bf16 v[120:123], v[162:165], v[178:181], v[120:123]
	v_mfma_f32_16x16x32_bf16 v[120:123], v[166:169], v[182:185], v[120:123]
	v_mfma_f32_16x16x32_bf16 v[104:107], v[166:169], v[204:207], v[104:107]
	v_mfma_f32_16x16x32_bf16 v[104:107], v[162:165], v[186:189], v[104:107]
	v_mfma_f32_16x16x32_bf16 v[88:91], v[162:165], v[208:211], v[88:91]
	v_mfma_f32_16x16x32_bf16 v[88:91], v[166:169], v[212:215], v[88:91]
	v_mfma_f32_16x16x32_bf16 v[72:75], v[166:169], v[220:223], v[72:75]
	v_mfma_f32_16x16x32_bf16 v[72:75], v[162:165], v[216:219], v[72:75]
	v_mfma_f32_16x16x32_bf16 v[68:71], v[170:173], v[216:219], v[68:71]
	v_mfma_f32_16x16x32_bf16 v[68:71], v[174:177], v[220:223], v[68:71]
	v_mfma_f32_16x16x32_bf16 v[84:87], v[174:177], v[212:215], v[84:87]
	v_mfma_f32_16x16x32_bf16 v[84:87], v[170:173], v[208:211], v[84:87]
	v_mfma_f32_16x16x32_bf16 v[100:103], v[170:173], v[186:189], v[100:103]
	v_mfma_f32_16x16x32_bf16 v[100:103], v[174:177], v[204:207], v[100:103]
	v_mfma_f32_16x16x32_bf16 v[116:119], v[174:177], v[182:185], v[116:119]
	v_mfma_f32_16x16x32_bf16 v[116:119], v[170:173], v[178:181], v[116:119]
	s_setprio 0
	s_barrier
	s_add_i32 s48, s73, s28
	v_lshl_add_u64 v[190:191], v[190:191], 0, s[84:85]
	s_mov_b32 m0, s48
	ds_read_b128 v[178:181], v145 offset:49152
	ds_read_b128 v[182:185], v145 offset:50176
	ds_read_b128 v[186:189], v145 offset:51200
	ds_read_b128 v[204:207], v145 offset:52224
	ds_read_b128 v[208:211], v145 offset:53248
	ds_read_b128 v[212:215], v145 offset:54272
	ds_read_b128 v[216:219], v145 offset:55296
	ds_read_b128 v[220:223], v145 offset:56320
	global_load_lds_dwordx4 v[190:191], off
	v_lshl_add_u64 v[190:191], v[224:225], 0, s[84:85]
	s_add_i32 m0, s48, 0x2000
	s_add_i32 s48, s76, s28
	global_load_lds_dwordx4 v[190:191], off
	v_lshl_add_u64 v[190:191], v[226:227], 0, s[84:85]
	s_mov_b32 m0, s48
	s_nop 0
	global_load_lds_dwordx4 v[190:191], off
	v_lshl_add_u64 v[190:191], v[228:229], 0, s[84:85]
	s_add_i32 m0, s48, 0x2000
	s_nop 0
	global_load_lds_dwordx4 v[190:191], off
	v_lshl_add_u64 v[190:191], v[240:241], 0, s[84:85]
	s_mov_b32 m0, s55
	s_nop 0
	global_load_lds_dwordx4 v[190:191], off
	v_lshl_add_u64 v[190:191], v[242:243], 0, s[84:85]
	s_mov_b32 m0, s56
	s_nop 0
	global_load_lds_dwordx4 v[190:191], off
	s_waitcnt vmcnt(8)
	s_waitcnt lgkmcnt(0)
	s_barrier
	s_setprio 1
	s_waitcnt lgkmcnt(0)
	v_mfma_f32_16x16x32_bf16 v[64:67], v[146:149], v[178:181], v[64:67]
	v_mfma_f32_16x16x32_bf16 v[64:67], v[150:153], v[182:185], v[64:67]
	v_mfma_f32_16x16x32_bf16 v[48:51], v[150:153], v[204:207], v[48:51]
	v_mfma_f32_16x16x32_bf16 v[48:51], v[146:149], v[186:189], v[48:51]
	v_mfma_f32_16x16x32_bf16 v[32:35], v[146:149], v[208:211], v[32:35]
	v_mfma_f32_16x16x32_bf16 v[32:35], v[150:153], v[212:215], v[32:35]
	v_mfma_f32_16x16x32_bf16 v[16:19], v[150:153], v[220:223], v[16:19]
	v_mfma_f32_16x16x32_bf16 v[16:19], v[146:149], v[216:219], v[16:19]
	v_mfma_f32_16x16x32_bf16 v[12:15], v[154:157], v[216:219], v[12:15]
	v_mfma_f32_16x16x32_bf16 v[12:15], v[158:161], v[220:223], v[12:15]
	v_mfma_f32_16x16x32_bf16 v[28:31], v[158:161], v[212:215], v[28:31]
	v_mfma_f32_16x16x32_bf16 v[28:31], v[154:157], v[208:211], v[28:31]
	v_mfma_f32_16x16x32_bf16 v[44:47], v[154:157], v[186:189], v[44:47]
	v_mfma_f32_16x16x32_bf16 v[44:47], v[158:161], v[204:207], v[44:47]
	v_mfma_f32_16x16x32_bf16 v[60:63], v[158:161], v[182:185], v[60:63]
	v_mfma_f32_16x16x32_bf16 v[60:63], v[154:157], v[178:181], v[60:63]
	v_mfma_f32_16x16x32_bf16 v[56:59], v[162:165], v[178:181], v[56:59]
	v_mfma_f32_16x16x32_bf16 v[56:59], v[166:169], v[182:185], v[56:59]
	v_mfma_f32_16x16x32_bf16 v[40:43], v[166:169], v[204:207], v[40:43]
	v_mfma_f32_16x16x32_bf16 v[40:43], v[162:165], v[186:189], v[40:43]
	v_mfma_f32_16x16x32_bf16 v[24:27], v[162:165], v[208:211], v[24:27]
	v_mfma_f32_16x16x32_bf16 v[24:27], v[166:169], v[212:215], v[24:27]
	v_mfma_f32_16x16x32_bf16 v[8:11], v[166:169], v[220:223], v[8:11]
	v_mfma_f32_16x16x32_bf16 v[8:11], v[162:165], v[216:219], v[8:11]
	v_mfma_f32_16x16x32_bf16 v[4:7], v[170:173], v[216:219], v[4:7]
	v_mfma_f32_16x16x32_bf16 v[4:7], v[174:177], v[220:223], v[4:7]
	v_mfma_f32_16x16x32_bf16 v[20:23], v[174:177], v[212:215], v[20:23]
	v_mfma_f32_16x16x32_bf16 v[20:23], v[170:173], v[208:211], v[20:23]
	v_mfma_f32_16x16x32_bf16 v[36:39], v[170:173], v[186:189], v[36:39]
	v_mfma_f32_16x16x32_bf16 v[36:39], v[174:177], v[204:207], v[36:39]
	v_mfma_f32_16x16x32_bf16 v[52:55], v[174:177], v[182:185], v[52:55]
	v_mfma_f32_16x16x32_bf16 v[52:55], v[170:173], v[178:181], v[52:55]
	s_setprio 0
	s_barrier
	s_add_u32 s44, s44, 0x100
	s_addc_u32 s45, s45, 0
	s_add_u32 s65, s65, 0x100
	s_addc_u32 s67, s67, 0
	s_cmp_ge_i32 s72, s53
	s_mov_b32 s48, s72
	s_cbranch_scc0 .LBB0_1623

; #define PG8_STAGE(bufoff, gbase, voff) do { _Pragma("unroll") for (int _i = 0; _i < 2; ++_i) \
;         __builtin_amdgcn_global_load_lds((const unsigned*)((const char*)(gbase) + (voff)[_i]), (PG8_LAS unsigned*)(lds + (bufoff) + ldsw + _i * 8192), 16, 0, 0); } while (0)
; #define PG8_LDA(dst, b, h) do { _Pragma("unroll") for (int m = 0; m < 4; ++m) _Pragma("unroll") for (int k = 0; k < 2; ++k) dst[m][k] = *(const PG8_LAS bf16x8*)(lds + PG8_SA(b, h) + aoff + m * 2048 + k * 1024); } while (0)
; #define PG8_LDB(dst, b, h) do { _Pragma("unroll") for (int n = 0; n < 2; ++n) _Pragma("unroll") for (int k = 0; k < 2; ++k) dst[n][k] = *(const PG8_LAS bf16x8*)(lds + PG8_SB(b, h) + boff + n * 2048 + k * 1024); } while (0)
; #define PG8_WAIT_V(n) asm volatile("s_waitcnt vmcnt(" #n ")" ::: "memory")
; #define PG8_WAIT_L(n) asm volatile("s_waitcnt lgkmcnt(" #n ")" ::: "memory")
; #define PG8_BAR __builtin_amdgcn_s_barrier()
; #define PG8_SCHED __builtin_amdgcn_sched_barrier(0)
; template <class Epi, class Sched, bool ALIGN_EPI = false, bool SP2 = false, bool I8 = false>
; __device__ __forceinline__ void gemm_phase(PG8_LAS unsigned char* lds, const Gemm g, const Sched& S, const Epi& E) {
;     ...
;     for (;;) {
;         const bool has_next = S.next(ui + 1, nxt);
;         const char* nA = has_next ? (const char*)g.A + (size_t)nxt.pm * tstep : cA; const char* nB = has_next ? (const char*)g.Bt + (size_t)nxt.pn * tstep : cB;
;         for (int t = 0; t < nt; t += 2) {
;             const bool last = (t == nt - 2);
;             const char* a1 = cA + (size_t)(t + 1) * kstep;
;             const char* a2 = last ? nA : cA + (size_t)(t + 2) * kstep; const char* b2 = last ? nB : cB + (size_t)(t + 2) * kstep;
;             const char* a3 = a2 + kstep; const char* b3 = b2 + kstep;
;             if (last && has_next) S.a_ready(nxt);
;             if constexpr (SP2) {
;             PG8_LDB(B0, 0, 0); PG8_LDB(B1, 0, 1); PG8_SCHED; PG8_LDA(At, 0, 0); PG8_STAGE(PG8_SA(1, 1), a1 + hstep, voffA);
;             PG8_WAIT_V(8); PG8_WAIT_L(0); PG8_BAR; PG8_MMA(0, 0, At, B0); PG8_MMA(0, 1, At, B1); PG8_BAR; PG8_SCHED;
;             PG8_LDA(At, 0, 1); PG8_STAGE(PG8_SB(0, 0), b2, voffB); PG8_STAGE(PG8_SB(0, 1), b2 + hstep, voffB); PG8_STAGE(PG8_SA(0, 0), a2, voffA);
.LBB0_1699:
	s_add_u32 s53, s24, 0x100
	s_addc_u32 s54, s25, 0
	s_mov_b32 s55, -2
	s_add_u32 s24, s22, 0x100
	s_addc_u32 s25, s23, 0
	s_add_i32 s56, 0, 0x10000
	s_cmpk_eq_i32 s55, 0xa8
	s_cselect_b32 s37, s13, s25
	s_cselect_b32 s36, s12, s24
	s_cselect_b32 s27, s21, s54
	s_cselect_b32 s26, s20, s53
	s_add_i32 s57, 0, 0x14000
	v_add_u32_e32 v144, s56, v240
	v_add_u32_e32 v160, s57, v240
	ds_read_b128 v[124:127], v144
	ds_read_b128 v[128:131], v144 offset:1024
	ds_read_b128 v[132:135], v144 offset:2048
	ds_read_b128 v[144:147], v144 offset:3072
	ds_read_b128 v[148:151], v160
	ds_read_b128 v[152:155], v160 offset:1024
	ds_read_b128 v[156:159], v160 offset:2048
	ds_read_b128 v[160:163], v160 offset:3072
	v_lshl_add_u64 v[218:219], s[22:23], 0, v[210:211]
	s_add_i32 m0, s42, 0xc000
	ds_read_b128 v[164:167], v242
	ds_read_b128 v[168:171], v242 offset:1024
	ds_read_b128 v[172:175], v242 offset:2048
	ds_read_b128 v[176:179], v242 offset:3072
	ds_read_b128 v[180:183], v242 offset:4096
	ds_read_b128 v[184:187], v242 offset:5120
	ds_read_b128 v[188:191], v242 offset:6144
	ds_read_b128 v[214:217], v242 offset:7168
	global_load_lds_dwordx4 v[218:219], off
	v_lshl_add_u64 v[218:219], s[22:23], 0, v[212:213]
	s_add_i32 m0, s42, 0xe000
	s_nop 0
	global_load_lds_dwordx4 v[218:219], off
	s_waitcnt vmcnt(8)
	s_waitcnt lgkmcnt(0)
	s_barrier
	s_setprio 1
	s_waitcnt lgkmcnt(0)
	v_mfma_f32_16x16x32_bf16 v[140:143], v[124:127], v[164:167], 0
	v_mfma_f32_16x16x32_bf16 v[140:143], v[128:131], v[168:171], v[140:143]
	v_mfma_f32_16x16x32_bf16 v[112:115], v[128:131], v[176:179], 0
	v_mfma_f32_16x16x32_bf16 v[112:115], v[124:127], v[172:175], v[112:115]
	v_mfma_f32_16x16x32_bf16 v[96:99], v[124:127], v[180:183], 0
	v_mfma_f32_16x16x32_bf16 v[96:99], v[128:131], v[184:187], v[96:99]
	v_mfma_f32_16x16x32_bf16 v[80:83], v[128:131], v[214:217], 0
	v_mfma_f32_16x16x32_bf16 v[80:83], v[124:127], v[188:191], v[80:83]
	v_mfma_f32_16x16x32_bf16 v[76:79], v[132:135], v[188:191], 0
	v_mfma_f32_16x16x32_bf16 v[76:79], v[144:147], v[214:217], v[76:79]
	v_mfma_f32_16x16x32_bf16 v[92:95], v[144:147], v[184:187], 0
	v_mfma_f32_16x16x32_bf16 v[92:95], v[132:135], v[180:183], v[92:95]
	v_mfma_f32_16x16x32_bf16 v[108:111], v[132:135], v[172:175], 0
	v_mfma_f32_16x16x32_bf16 v[108:111], v[144:147], v[176:179], v[108:111]
	v_mfma_f32_16x16x32_bf16 v[136:139], v[144:147], v[168:171], 0
	v_mfma_f32_16x16x32_bf16 v[136:139], v[132:135], v[164:167], v[136:139]
	v_mfma_f32_16x16x32_bf16 v[120:123], v[148:151], v[164:167], 0
	v_mfma_f32_16x16x32_bf16 v[120:123], v[152:155], v[168:171], v[120:123]
	v_mfma_f32_16x16x32_bf16 v[104:107], v[152:155], v[176:179], 0
	v_mfma_f32_16x16x32_bf16 v[104:107], v[148:151], v[172:175], v[104:107]
	v_mfma_f32_16x16x32_bf16 v[88:91], v[148:151], v[180:183], 0
	v_mfma_f32_16x16x32_bf16 v[88:91], v[152:155], v[184:187], v[88:91]
	v_mfma_f32_16x16x32_bf16 v[72:75], v[152:155], v[214:217], 0
	v_mfma_f32_16x16x32_bf16 v[72:75], v[148:151], v[188:191], v[72:75]
	v_mfma_f32_16x16x32_bf16 v[68:71], v[156:159], v[188:191], 0
	v_mfma_f32_16x16x32_bf16 v[68:71], v[160:163], v[214:217], v[68:71]
	v_mfma_f32_16x16x32_bf16 v[84:87], v[160:163], v[184:187], 0
	v_mfma_f32_16x16x32_bf16 v[84:87], v[156:159], v[180:183], v[84:87]
	v_mfma_f32_16x16x32_bf16 v[100:103], v[156:159], v[172:175], 0
	v_mfma_f32_16x16x32_bf16 v[100:103], v[160:163], v[176:179], v[100:103]
	v_mfma_f32_16x16x32_bf16 v[116:119], v[160:163], v[168:171], 0
	v_mfma_f32_16x16x32_bf16 v[116:119], v[156:159], v[164:167], v[116:119]
	s_setprio 0
	s_barrier
	s_add_i32 s22, s56, s41
	v_lshl_add_u64 v[218:219], s[26:27], 0, v[2:3]
	s_mov_b32 m0, s22
	ds_read_b128 v[164:167], v242 offset:16384
	ds_read_b128 v[168:171], v242 offset:17408
	ds_read_b128 v[172:175], v242 offset:18432
	ds_read_b128 v[176:179], v242 offset:19456
	ds_read_b128 v[180:183], v242 offset:20480
	ds_read_b128 v[184:187], v242 offset:21504
	ds_read_b128 v[188:191], v242 offset:22528
	ds_read_b128 v[214:217], v242 offset:23552
	global_load_lds_dwordx4 v[218:219], off
	s_add_i32 m0, s22, 0x2000
	s_add_u32 s22, s26, 0x2b0000
	v_lshl_add_u64 v[220:221], s[26:27], 0, v[204:205]
	s_addc_u32 s23, s27, 0
	s_add_i32 s56, s57, s41
	global_load_lds_dwordx4 v[220:221], off
	v_lshl_add_u64 v[222:223], s[22:23], 0, v[2:3]
	s_mov_b32 m0, s56
	v_lshl_add_u64 v[224:225], s[36:37], 0, v[206:207]
	global_load_lds_dwordx4 v[222:223], off
	v_lshl_add_u64 v[222:223], s[22:23], 0, v[204:205]
	s_add_i32 m0, s56, 0x2000
	s_nop 0
	global_load_lds_dwordx4 v[222:223], off
	v_lshl_add_u64 v[222:223], s[36:37], 0, v[208:209]
	s_waitcnt vmcnt(6)
	s_waitcnt lgkmcnt(0)
	s_barrier
; #define PG8_STAGE(bufoff, gbase, voff) do { _Pragma("unroll") for (int _i = 0; _i < 2; ++_i) \
;         __builtin_amdgcn_global_load_lds((const unsigned*)((const char*)(gbase) + (voff)[_i]), (PG8_LAS unsigned*)(lds + (bufoff) + ldsw + _i * 8192), 16, 0, 0); } while (0)
; #define PG8_LDA(dst, b, h) do { _Pragma("unroll") for (int m = 0; m < 4; ++m) _Pragma("unroll") for (int k = 0; k < 2; ++k) dst[m][k] = *(const PG8_LAS bf16x8*)(lds + PG8_SA(b, h) + aoff + m * 2048 + k * 1024); } while (0)
; #define PG8_LDB(dst, b, h) do { _Pragma("unroll") for (int n = 0; n < 2; ++n) _Pragma("unroll") for (int k = 0; k < 2; ++k) dst[n][k] = *(const PG8_LAS bf16x8*)(lds + PG8_SB(b, h) + boff + n * 2048 + k * 1024); } while (0)
; #define PG8_WAIT_V(n) asm volatile("s_waitcnt vmcnt(" #n ")" ::: "memory")
; #define PG8_WAIT_L(n) asm volatile("s_waitcnt lgkmcnt(" #n ")" ::: "memory")
; #define PG8_BAR __builtin_amdgcn_s_barrier()
; #define PG8_SCHED __builtin_amdgcn_sched_barrier(0)
; template <class Epi, class Sched, bool ALIGN_EPI = false, bool SP2 = false, bool I8 = false>
; __device__ __forceinline__ void gemm_phase(PG8_LAS unsigned char* lds, const Gemm g, const Sched& S, const Epi& E) {
;     ...
;             PG8_WAIT_V(8); PG8_WAIT_L(0); PG8_BAR; PG8_MMA(1, 0, At, B0); PG8_MMA(1, 1, At, B1); PG8_BAR; PG8_SCHED;
;             PG8_LDB(B0, 1, 0); PG8_LDB(B1, 1, 1); PG8_SCHED; PG8_LDA(At, 1, 0); PG8_STAGE(PG8_SA(0, 1), a2 + hstep, voffA);
;             PG8_WAIT_V(8); PG8_WAIT_L(0); PG8_BAR; PG8_MMA(0, 0, At, B0); PG8_MMA(0, 1, At, B1); PG8_BAR; PG8_SCHED;
;             PG8_LDA(At, 1, 1); PG8_STAGE(PG8_SB(1, 0), b3, voffB); PG8_STAGE(PG8_SB(1, 1), b3 + hstep, voffB); PG8_STAGE(PG8_SA(1, 0), a3, voffA);
	s_setprio 1
	s_waitcnt lgkmcnt(0)
	v_mfma_f32_16x16x32_bf16 v[64:67], v[124:127], v[164:167], 0
	v_mfma_f32_16x16x32_bf16 v[64:67], v[128:131], v[168:171], v[64:67]
	v_mfma_f32_16x16x32_bf16 v[48:51], v[128:131], v[176:179], 0
	v_mfma_f32_16x16x32_bf16 v[48:51], v[124:127], v[172:175], v[48:51]
	v_mfma_f32_16x16x32_bf16 v[32:35], v[124:127], v[180:183], 0
	v_mfma_f32_16x16x32_bf16 v[32:35], v[128:131], v[184:187], v[32:35]
	v_mfma_f32_16x16x32_bf16 v[16:19], v[128:131], v[214:217], 0
	v_mfma_f32_16x16x32_bf16 v[16:19], v[124:127], v[188:191], v[16:19]
	v_mfma_f32_16x16x32_bf16 v[12:15], v[132:135], v[188:191], 0
	v_mfma_f32_16x16x32_bf16 v[12:15], v[144:147], v[214:217], v[12:15]
	v_mfma_f32_16x16x32_bf16 v[28:31], v[144:147], v[184:187], 0
	v_mfma_f32_16x16x32_bf16 v[28:31], v[132:135], v[180:183], v[28:31]
	v_mfma_f32_16x16x32_bf16 v[44:47], v[132:135], v[172:175], 0
	v_mfma_f32_16x16x32_bf16 v[44:47], v[144:147], v[176:179], v[44:47]
	v_mfma_f32_16x16x32_bf16 v[60:63], v[144:147], v[168:171], 0
	v_mfma_f32_16x16x32_bf16 v[60:63], v[132:135], v[164:167], v[60:63]
	v_mfma_f32_16x16x32_bf16 v[56:59], v[148:151], v[164:167], 0
	v_mfma_f32_16x16x32_bf16 v[56:59], v[152:155], v[168:171], v[56:59]
	v_mfma_f32_16x16x32_bf16 v[40:43], v[152:155], v[176:179], 0
	v_mfma_f32_16x16x32_bf16 v[40:43], v[148:151], v[172:175], v[40:43]
	v_mfma_f32_16x16x32_bf16 v[24:27], v[148:151], v[180:183], 0
	v_mfma_f32_16x16x32_bf16 v[24:27], v[152:155], v[184:187], v[24:27]
	v_mfma_f32_16x16x32_bf16 v[8:11], v[152:155], v[214:217], 0
	v_mfma_f32_16x16x32_bf16 v[8:11], v[148:151], v[188:191], v[8:11]
	v_mfma_f32_16x16x32_bf16 v[4:7], v[156:159], v[188:191], 0
	v_mfma_f32_16x16x32_bf16 v[4:7], v[160:163], v[214:217], v[4:7]
	v_mfma_f32_16x16x32_bf16 v[20:23], v[160:163], v[184:187], 0
	v_mfma_f32_16x16x32_bf16 v[20:23], v[156:159], v[180:183], v[20:23]
	v_mfma_f32_16x16x32_bf16 v[36:39], v[156:159], v[172:175], 0
	v_mfma_f32_16x16x32_bf16 v[36:39], v[160:163], v[176:179], v[36:39]
	v_mfma_f32_16x16x32_bf16 v[52:55], v[160:163], v[168:171], 0
	v_mfma_f32_16x16x32_bf16 v[52:55], v[156:159], v[164:167], v[52:55]
	s_setprio 0
	s_barrier
	s_add_i32 s56, 0, 0x18000
	s_add_i32 s57, 0, 0x1c000
	v_add_u32_e32 v144, s56, v240
	v_add_u32_e32 v160, s57, v240
	ds_read_b128 v[124:127], v144
	ds_read_b128 v[128:131], v144 offset:1024
	ds_read_b128 v[132:135], v144 offset:2048
	ds_read_b128 v[144:147], v144 offset:3072
	ds_read_b128 v[148:151], v160
	ds_read_b128 v[152:155], v160 offset:1024
	ds_read_b128 v[156:159], v160 offset:2048
	ds_read_b128 v[160:163], v160 offset:3072
	s_add_u32 s22, s36, 0x2b0000
	s_addc_u32 s23, s37, 0
	s_mov_b32 m0, s44
	v_lshl_add_u64 v[226:227], s[22:23], 0, v[208:209]
	ds_read_b128 v[164:167], v242 offset:32768
	ds_read_b128 v[168:171], v242 offset:33792
	ds_read_b128 v[172:175], v242 offset:34816
	ds_read_b128 v[176:179], v242 offset:35840
	ds_read_b128 v[180:183], v242 offset:36864
	ds_read_b128 v[184:187], v242 offset:37888
	ds_read_b128 v[188:191], v242 offset:38912
	ds_read_b128 v[214:217], v242 offset:39936
	s_mov_b32 m0, s42
	s_nop 0
	global_load_lds_dwordx4 v[222:223], off
	s_mov_b32 m0, s43
	s_nop 0
	global_load_lds_dwordx4 v[224:225], off
	s_mov_b32 m0, s44
	s_nop 0
	global_load_lds_dwordx4 v[226:227], off
	v_lshl_add_u64 v[226:227], s[22:23], 0, v[206:207]
	s_mov_b32 m0, s45
	s_nop 0
	global_load_lds_dwordx4 v[226:227], off
	s_waitcnt vmcnt(8)
	s_waitcnt lgkmcnt(0)
	s_barrier
	s_setprio 1
	s_waitcnt lgkmcnt(0)
	v_mfma_f32_16x16x32_bf16 v[140:143], v[124:127], v[164:167], v[140:143]
	v_mfma_f32_16x16x32_bf16 v[140:143], v[128:131], v[168:171], v[140:143]
	v_mfma_f32_16x16x32_bf16 v[112:115], v[128:131], v[176:179], v[112:115]
	v_mfma_f32_16x16x32_bf16 v[112:115], v[124:127], v[172:175], v[112:115]
	v_mfma_f32_16x16x32_bf16 v[96:99], v[124:127], v[180:183], v[96:99]
	v_mfma_f32_16x16x32_bf16 v[96:99], v[128:131], v[184:187], v[96:99]
	v_mfma_f32_16x16x32_bf16 v[80:83], v[128:131], v[214:217], v[80:83]
	v_mfma_f32_16x16x32_bf16 v[80:83], v[124:127], v[188:191], v[80:83]
	v_mfma_f32_16x16x32_bf16 v[76:79], v[132:135], v[188:191], v[76:79]
	v_mfma_f32_16x16x32_bf16 v[76:79], v[144:147], v[214:217], v[76:79]
	v_mfma_f32_16x16x32_bf16 v[92:95], v[144:147], v[184:187], v[92:95]
	v_mfma_f32_16x16x32_bf16 v[92:95], v[132:135], v[180:183], v[92:95]
	v_mfma_f32_16x16x32_bf16 v[108:111], v[132:135], v[172:175], v[108:111]
	v_mfma_f32_16x16x32_bf16 v[108:111], v[144:147], v[176:179], v[108:111]
	v_mfma_f32_16x16x32_bf16 v[136:139], v[144:147], v[168:171], v[136:139]
	v_mfma_f32_16x16x32_bf16 v[136:139], v[132:135], v[164:167], v[136:139]
	v_mfma_f32_16x16x32_bf16 v[120:123], v[148:151], v[164:167], v[120:123]
	v_mfma_f32_16x16x32_bf16 v[120:123], v[152:155], v[168:171], v[120:123]
	v_mfma_f32_16x16x32_bf16 v[104:107], v[152:155], v[176:179], v[104:107]
	v_mfma_f32_16x16x32_bf16 v[104:107], v[148:151], v[172:175], v[104:107]
	v_mfma_f32_16x16x32_bf16 v[88:91], v[148:151], v[180:183], v[88:91]
	v_mfma_f32_16x16x32_bf16 v[88:91], v[152:155], v[184:187], v[88:91]
	v_mfma_f32_16x16x32_bf16 v[72:75], v[152:155], v[214:217], v[72:75]
	v_mfma_f32_16x16x32_bf16 v[72:75], v[148:151], v[188:191], v[72:75]
	v_mfma_f32_16x16x32_bf16 v[68:71], v[156:159], v[188:191], v[68:71]
	v_mfma_f32_16x16x32_bf16 v[68:71], v[160:163], v[214:217], v[68:71]
	v_mfma_f32_16x16x32_bf16 v[84:87], v[160:163], v[184:187], v[84:87]
	v_mfma_f32_16x16x32_bf16 v[84:87], v[156:159], v[180:183], v[84:87]
	v_mfma_f32_16x16x32_bf16 v[100:103], v[156:159], v[172:175], v[100:103]
	v_mfma_f32_16x16x32_bf16 v[100:103], v[160:163], v[176:179], v[100:103]
	v_mfma_f32_16x16x32_bf16 v[116:119], v[160:163], v[168:171], v[116:119]
	v_mfma_f32_16x16x32_bf16 v[116:119], v[156:159], v[164:167], v[116:119]
	s_setprio 0
	s_barrier
	s_add_i32 s22, s56, s41
	v_lshl_add_u64 v[218:219], v[218:219], 0, s[84:85]
	s_mov_b32 m0, s22
	ds_read_b128 v[164:167], v242 offset:49152
	ds_read_b128 v[168:171], v242 offset:50176
	ds_read_b128 v[172:175], v242 offset:51200
	ds_read_b128 v[176:179], v242 offset:52224
	ds_read_b128 v[180:183], v242 offset:53248
	ds_read_b128 v[184:187], v242 offset:54272
	ds_read_b128 v[188:191], v242 offset:55296
	ds_read_b128 v[214:217], v242 offset:56320
	global_load_lds_dwordx4 v[218:219], off
	s_add_i32 m0, s22, 0x2000
	s_add_u32 s22, s26, 0x2b0080
	v_lshl_add_u64 v[218:219], v[220:221], 0, s[84:85]
	s_addc_u32 s23, s27, 0
	s_add_i32 s26, s57, s41
	global_load_lds_dwordx4 v[218:219], off
	v_lshl_add_u64 v[218:219], s[22:23], 0, v[2:3]
	s_mov_b32 m0, s26
	s_nop 0
	global_load_lds_dwordx4 v[218:219], off
	v_lshl_add_u64 v[218:219], s[22:23], 0, v[204:205]
	s_add_i32 m0, s26, 0x2000
	s_nop 0
	global_load_lds_dwordx4 v[218:219], off
	s_cmpk_eq_i32 s55, 0xa8
	s_cbranch_scc0 .Ldefer_1700_peel
	v_lshl_add_u64 v[218:219], v[222:223], 0, s[84:85]
	s_mov_b32 m0, s46
	s_nop 0
	global_load_lds_dwordx4 v[218:219], off
	v_lshl_add_u64 v[218:219], v[224:225], 0, s[84:85]
	s_mov_b32 m0, s47
	s_nop 0
	global_load_lds_dwordx4 v[218:219], off

; #define PG8_STAGE(bufoff, gbase, voff) do { _Pragma("unroll") for (int _i = 0; _i < 2; ++_i) \
;         __builtin_amdgcn_global_load_lds((const unsigned*)((const char*)(gbase) + (voff)[_i]), (PG8_LAS unsigned*)(lds + (bufoff) + ldsw + _i * 8192), 16, 0, 0); } while (0)
; #define PG8_LDA(dst, b, h) do { _Pragma("unroll") for (int m = 0; m < 4; ++m) _Pragma("unroll") for (int k = 0; k < 2; ++k) dst[m][k] = *(const PG8_LAS bf16x8*)(lds + PG8_SA(b, h) + aoff + m * 2048 + k * 1024); } while (0)
; #define PG8_LDB(dst, b, h) do { _Pragma("unroll") for (int n = 0; n < 2; ++n) _Pragma("unroll") for (int k = 0; k < 2; ++k) dst[n][k] = *(const PG8_LAS bf16x8*)(lds + PG8_SB(b, h) + boff + n * 2048 + k * 1024); } while (0)
; #define PG8_WAIT_V(n) asm volatile("s_waitcnt vmcnt(" #n ")" ::: "memory")
; #define PG8_WAIT_L(n) asm volatile("s_waitcnt lgkmcnt(" #n ")" ::: "memory")
; #define PG8_BAR __builtin_amdgcn_s_barrier()
; #define PG8_SCHED __builtin_amdgcn_sched_barrier(0)
; template <class Epi, class Sched, bool ALIGN_EPI = false, bool SP2 = false, bool I8 = false>
; __device__ __forceinline__ void gemm_phase(PG8_LAS unsigned char* lds, const Gemm g, const Sched& S, const Epi& E) {
;     ...
;         for (int t = 0; t < nt; t += 2) {
;             const bool last = (t == nt - 2);
;             const char* a1 = cA + (size_t)(t + 1) * kstep;
;             const char* a2 = last ? nA : cA + (size_t)(t + 2) * kstep; const char* b2 = last ? nB : cB + (size_t)(t + 2) * kstep;
;             const char* a3 = a2 + kstep; const char* b3 = b2 + kstep;
;             if (last && has_next) S.a_ready(nxt);
;             if constexpr (SP2) {
;             PG8_LDB(B0, 0, 0); PG8_LDB(B1, 0, 1); PG8_SCHED; PG8_LDA(At, 0, 0); PG8_STAGE(PG8_SA(1, 1), a1 + hstep, voffA);
;             PG8_WAIT_V(8); PG8_WAIT_L(0); PG8_BAR; PG8_MMA(0, 0, At, B0); PG8_MMA(0, 1, At, B1); PG8_BAR; PG8_SCHED;
;             PG8_LDA(At, 0, 1); PG8_STAGE(PG8_SB(0, 0), b2, voffB); PG8_STAGE(PG8_SB(0, 1), b2 + hstep, voffB); PG8_STAGE(PG8_SA(0, 0), a2, voffA);
.LBB0_1700:
	s_add_u32 s24, s22, 0x100
	s_addc_u32 s25, s23, 0
	s_add_i32 s56, 0, 0x10000
	s_cmpk_eq_i32 s55, 0xa8
	s_cselect_b32 s37, s13, s25
	s_cselect_b32 s36, s12, s24
	s_cselect_b32 s27, s21, s54
	s_cselect_b32 s26, s20, s53
	s_add_i32 s57, 0, 0x14000
	v_add_u32_e32 v144, s56, v240
	v_add_u32_e32 v160, s57, v240
	ds_read_b128 v[124:127], v144
	ds_read_b128 v[128:131], v144 offset:1024
	ds_read_b128 v[132:135], v144 offset:2048
	ds_read_b128 v[144:147], v144 offset:3072
	ds_read_b128 v[148:151], v160
	ds_read_b128 v[152:155], v160 offset:1024
	ds_read_b128 v[156:159], v160 offset:2048
	ds_read_b128 v[160:163], v160 offset:3072
	ds_read_b128 v[164:167], v242
	ds_read_b128 v[168:171], v242 offset:1024
	ds_read_b128 v[172:175], v242 offset:2048
	ds_read_b128 v[176:179], v242 offset:3072
	ds_read_b128 v[180:183], v242 offset:4096
	ds_read_b128 v[184:187], v242 offset:5120
	ds_read_b128 v[188:191], v242 offset:6144
	ds_read_b128 v[214:217], v242 offset:7168
	v_lshl_add_u64 v[218:219], v[222:223], 0, s[84:85]
	s_mov_b32 m0, s46
	s_nop 0
	global_load_lds_dwordx4 v[218:219], off
	v_lshl_add_u64 v[218:219], v[224:225], 0, s[84:85]
	s_mov_b32 m0, s47
	s_nop 0
	global_load_lds_dwordx4 v[218:219], off
	v_lshl_add_u64 v[218:219], s[22:23], 0, v[210:211]
	s_add_i32 m0, s42, 0xc000
	s_nop 0
	global_load_lds_dwordx4 v[218:219], off
	v_lshl_add_u64 v[218:219], s[22:23], 0, v[212:213]
	s_add_i32 m0, s42, 0xe000
	s_nop 0
	global_load_lds_dwordx4 v[218:219], off
	s_waitcnt vmcnt(8)
	s_waitcnt lgkmcnt(0)
	s_barrier
	s_setprio 1
	s_waitcnt lgkmcnt(0)
	v_mfma_f32_16x16x32_bf16 v[140:143], v[124:127], v[164:167], v[140:143]
	v_mfma_f32_16x16x32_bf16 v[140:143], v[128:131], v[168:171], v[140:143]
	v_mfma_f32_16x16x32_bf16 v[112:115], v[128:131], v[176:179], v[112:115]
	v_mfma_f32_16x16x32_bf16 v[112:115], v[124:127], v[172:175], v[112:115]
	v_mfma_f32_16x16x32_bf16 v[96:99], v[124:127], v[180:183], v[96:99]
	v_mfma_f32_16x16x32_bf16 v[96:99], v[128:131], v[184:187], v[96:99]
	v_mfma_f32_16x16x32_bf16 v[80:83], v[128:131], v[214:217], v[80:83]
	v_mfma_f32_16x16x32_bf16 v[80:83], v[124:127], v[188:191], v[80:83]
	v_mfma_f32_16x16x32_bf16 v[76:79], v[132:135], v[188:191], v[76:79]
	v_mfma_f32_16x16x32_bf16 v[76:79], v[144:147], v[214:217], v[76:79]
	v_mfma_f32_16x16x32_bf16 v[92:95], v[144:147], v[184:187], v[92:95]
	v_mfma_f32_16x16x32_bf16 v[92:95], v[132:135], v[180:183], v[92:95]
	v_mfma_f32_16x16x32_bf16 v[108:111], v[132:135], v[172:175], v[108:111]
	v_mfma_f32_16x16x32_bf16 v[108:111], v[144:147], v[176:179], v[108:111]
	v_mfma_f32_16x16x32_bf16 v[136:139], v[144:147], v[168:171], v[136:139]
	v_mfma_f32_16x16x32_bf16 v[136:139], v[132:135], v[164:167], v[136:139]
	v_mfma_f32_16x16x32_bf16 v[120:123], v[148:151], v[164:167], v[120:123]
	v_mfma_f32_16x16x32_bf16 v[120:123], v[152:155], v[168:171], v[120:123]
	v_mfma_f32_16x16x32_bf16 v[104:107], v[152:155], v[176:179], v[104:107]
	v_mfma_f32_16x16x32_bf16 v[104:107], v[148:151], v[172:175], v[104:107]
	v_mfma_f32_16x16x32_bf16 v[88:91], v[148:151], v[180:183], v[88:91]
	v_mfma_f32_16x16x32_bf16 v[88:91], v[152:155], v[184:187], v[88:91]
	v_mfma_f32_16x16x32_bf16 v[72:75], v[152:155], v[214:217], v[72:75]
	v_mfma_f32_16x16x32_bf16 v[72:75], v[148:151], v[188:191], v[72:75]
	v_mfma_f32_16x16x32_bf16 v[68:71], v[156:159], v[188:191], v[68:71]
	v_mfma_f32_16x16x32_bf16 v[68:71], v[160:163], v[214:217], v[68:71]
	v_mfma_f32_16x16x32_bf16 v[84:87], v[160:163], v[184:187], v[84:87]
	v_mfma_f32_16x16x32_bf16 v[84:87], v[156:159], v[180:183], v[84:87]
	v_mfma_f32_16x16x32_bf16 v[100:103], v[156:159], v[172:175], v[100:103]
	v_mfma_f32_16x16x32_bf16 v[100:103], v[160:163], v[176:179], v[100:103]
	v_mfma_f32_16x16x32_bf16 v[116:119], v[160:163], v[168:171], v[116:119]
	v_mfma_f32_16x16x32_bf16 v[116:119], v[156:159], v[164:167], v[116:119]
	s_setprio 0
	s_barrier
	s_add_i32 s22, s56, s41
	v_lshl_add_u64 v[218:219], s[26:27], 0, v[2:3]
	s_mov_b32 m0, s22
	ds_read_b128 v[164:167], v242 offset:16384
	ds_read_b128 v[168:171], v242 offset:17408
	ds_read_b128 v[172:175], v242 offset:18432
	ds_read_b128 v[176:179], v242 offset:19456
	ds_read_b128 v[180:183], v242 offset:20480
	ds_read_b128 v[184:187], v242 offset:21504
	ds_read_b128 v[188:191], v242 offset:22528
	ds_read_b128 v[214:217], v242 offset:23552
	global_load_lds_dwordx4 v[218:219], off
	s_add_i32 m0, s22, 0x2000
	s_add_u32 s22, s26, 0x2b0000
	v_lshl_add_u64 v[220:221], s[26:27], 0, v[204:205]
	s_addc_u32 s23, s27, 0
	s_add_i32 s56, s57, s41
	global_load_lds_dwordx4 v[220:221], off
	v_lshl_add_u64 v[222:223], s[22:23], 0, v[2:3]
	s_mov_b32 m0, s56
	v_lshl_add_u64 v[224:225], s[36:37], 0, v[206:207]
	global_load_lds_dwordx4 v[222:223], off
	v_lshl_add_u64 v[222:223], s[22:23], 0, v[204:205]
	s_add_i32 m0, s56, 0x2000
	s_nop 0
	global_load_lds_dwordx4 v[222:223], off
	v_lshl_add_u64 v[222:223], s[36:37], 0, v[208:209]
	s_waitcnt vmcnt(6)
	s_waitcnt lgkmcnt(0)
	s_barrier
; #define PG8_STAGE(bufoff, gbase, voff) do { _Pragma("unroll") for (int _i = 0; _i < 2; ++_i) \
;         __builtin_amdgcn_global_load_lds((const unsigned*)((const char*)(gbase) + (voff)[_i]), (PG8_LAS unsigned*)(lds + (bufoff) + ldsw + _i * 8192), 16, 0, 0); } while (0)
; #define PG8_LDA(dst, b, h) do { _Pragma("unroll") for (int m = 0; m < 4; ++m) _Pragma("unroll") for (int k = 0; k < 2; ++k) dst[m][k] = *(const PG8_LAS bf16x8*)(lds + PG8_SA(b, h) + aoff + m * 2048 + k * 1024); } while (0)
; #define PG8_LDB(dst, b, h) do { _Pragma("unroll") for (int n = 0; n < 2; ++n) _Pragma("unroll") for (int k = 0; k < 2; ++k) dst[n][k] = *(const PG8_LAS bf16x8*)(lds + PG8_SB(b, h) + boff + n * 2048 + k * 1024); } while (0)
; #define PG8_WAIT_V(n) asm volatile("s_waitcnt vmcnt(" #n ")" ::: "memory")
; #define PG8_WAIT_L(n) asm volatile("s_waitcnt lgkmcnt(" #n ")" ::: "memory")
; #define PG8_BAR __builtin_amdgcn_s_barrier()
; #define PG8_SCHED __builtin_amdgcn_sched_barrier(0)
; template <class Epi, class Sched, bool ALIGN_EPI = false, bool SP2 = false, bool I8 = false>
; __device__ __forceinline__ void gemm_phase(PG8_LAS unsigned char* lds, const Gemm g, const Sched& S, const Epi& E) {
;     ...
;             PG8_WAIT_V(8); PG8_WAIT_L(0); PG8_BAR; PG8_MMA(1, 0, At, B0); PG8_MMA(1, 1, At, B1); PG8_BAR; PG8_SCHED;
;             PG8_LDB(B0, 1, 0); PG8_LDB(B1, 1, 1); PG8_SCHED; PG8_LDA(At, 1, 0); PG8_STAGE(PG8_SA(0, 1), a2 + hstep, voffA);
;             PG8_WAIT_V(8); PG8_WAIT_L(0); PG8_BAR; PG8_MMA(0, 0, At, B0); PG8_MMA(0, 1, At, B1); PG8_BAR; PG8_SCHED;
	s_setprio 1
	s_waitcnt lgkmcnt(0)
	v_mfma_f32_16x16x32_bf16 v[64:67], v[124:127], v[164:167], v[64:67]
	v_mfma_f32_16x16x32_bf16 v[64:67], v[128:131], v[168:171], v[64:67]
	v_mfma_f32_16x16x32_bf16 v[48:51], v[128:131], v[176:179], v[48:51]
	v_mfma_f32_16x16x32_bf16 v[48:51], v[124:127], v[172:175], v[48:51]
	v_mfma_f32_16x16x32_bf16 v[32:35], v[124:127], v[180:183], v[32:35]
	v_mfma_f32_16x16x32_bf16 v[32:35], v[128:131], v[184:187], v[32:35]
	v_mfma_f32_16x16x32_bf16 v[16:19], v[128:131], v[214:217], v[16:19]
	v_mfma_f32_16x16x32_bf16 v[16:19], v[124:127], v[188:191], v[16:19]
	v_mfma_f32_16x16x32_bf16 v[12:15], v[132:135], v[188:191], v[12:15]
	v_mfma_f32_16x16x32_bf16 v[12:15], v[144:147], v[214:217], v[12:15]
	v_mfma_f32_16x16x32_bf16 v[28:31], v[144:147], v[184:187], v[28:31]
	v_mfma_f32_16x16x32_bf16 v[28:31], v[132:135], v[180:183], v[28:31]
	v_mfma_f32_16x16x32_bf16 v[44:47], v[132:135], v[172:175], v[44:47]
	v_mfma_f32_16x16x32_bf16 v[44:47], v[144:147], v[176:179], v[44:47]
	v_mfma_f32_16x16x32_bf16 v[60:63], v[144:147], v[168:171], v[60:63]
	v_mfma_f32_16x16x32_bf16 v[60:63], v[132:135], v[164:167], v[60:63]
	v_mfma_f32_16x16x32_bf16 v[56:59], v[148:151], v[164:167], v[56:59]
	v_mfma_f32_16x16x32_bf16 v[56:59], v[152:155], v[168:171], v[56:59]
	v_mfma_f32_16x16x32_bf16 v[40:43], v[152:155], v[176:179], v[40:43]
	v_mfma_f32_16x16x32_bf16 v[40:43], v[148:151], v[172:175], v[40:43]
	v_mfma_f32_16x16x32_bf16 v[24:27], v[148:151], v[180:183], v[24:27]
	v_mfma_f32_16x16x32_bf16 v[24:27], v[152:155], v[184:187], v[24:27]
	v_mfma_f32_16x16x32_bf16 v[8:11], v[152:155], v[214:217], v[8:11]
	v_mfma_f32_16x16x32_bf16 v[8:11], v[148:151], v[188:191], v[8:11]
	v_mfma_f32_16x16x32_bf16 v[4:7], v[156:159], v[188:191], v[4:7]
	v_mfma_f32_16x16x32_bf16 v[4:7], v[160:163], v[214:217], v[4:7]
	v_mfma_f32_16x16x32_bf16 v[20:23], v[160:163], v[184:187], v[20:23]
	v_mfma_f32_16x16x32_bf16 v[20:23], v[156:159], v[180:183], v[20:23]
	v_mfma_f32_16x16x32_bf16 v[36:39], v[156:159], v[172:175], v[36:39]
	v_mfma_f32_16x16x32_bf16 v[36:39], v[160:163], v[176:179], v[36:39]
	v_mfma_f32_16x16x32_bf16 v[52:55], v[160:163], v[168:171], v[52:55]
	v_mfma_f32_16x16x32_bf16 v[52:55], v[156:159], v[164:167], v[52:55]
	s_setprio 0
	s_barrier
	s_add_i32 s56, 0, 0x18000
	s_add_i32 s57, 0, 0x1c000
	v_add_u32_e32 v144, s56, v240
	v_add_u32_e32 v160, s57, v240
	ds_read_b128 v[124:127], v144
	ds_read_b128 v[128:131], v144 offset:1024
	ds_read_b128 v[132:135], v144 offset:2048
	ds_read_b128 v[144:147], v144 offset:3072
	ds_read_b128 v[148:151], v160
	ds_read_b128 v[152:155], v160 offset:1024
	ds_read_b128 v[156:159], v160 offset:2048
	ds_read_b128 v[160:163], v160 offset:3072
	s_add_u32 s22, s36, 0x2b0000
	s_addc_u32 s23, s37, 0
	s_mov_b32 m0, s44
	v_lshl_add_u64 v[226:227], s[22:23], 0, v[208:209]
	ds_read_b128 v[164:167], v242 offset:32768
	ds_read_b128 v[168:171], v242 offset:33792
	ds_read_b128 v[172:175], v242 offset:34816
	ds_read_b128 v[176:179], v242 offset:35840
	ds_read_b128 v[180:183], v242 offset:36864
	ds_read_b128 v[184:187], v242 offset:37888
	ds_read_b128 v[188:191], v242 offset:38912
	ds_read_b128 v[214:217], v242 offset:39936
	s_mov_b32 m0, s42
	s_nop 0
	global_load_lds_dwordx4 v[222:223], off
	s_mov_b32 m0, s43
	s_nop 0
	global_load_lds_dwordx4 v[224:225], off
	s_mov_b32 m0, s44
	s_nop 0
	global_load_lds_dwordx4 v[226:227], off
	v_lshl_add_u64 v[226:227], s[22:23], 0, v[206:207]
	s_mov_b32 m0, s45
	s_nop 0
	global_load_lds_dwordx4 v[226:227], off
	s_waitcnt vmcnt(8)
	s_waitcnt lgkmcnt(0)
	s_barrier
; #define PG8_STAGE(bufoff, gbase, voff) do { _Pragma("unroll") for (int _i = 0; _i < 2; ++_i) \
;         __builtin_amdgcn_global_load_lds((const unsigned*)((const char*)(gbase) + (voff)[_i]), (PG8_LAS unsigned*)(lds + (bufoff) + ldsw + _i * 8192), 16, 0, 0); } while (0)
; #define PG8_LDA(dst, b, h) do { _Pragma("unroll") for (int m = 0; m < 4; ++m) _Pragma("unroll") for (int k = 0; k < 2; ++k) dst[m][k] = *(const PG8_LAS bf16x8*)(lds + PG8_SA(b, h) + aoff + m * 2048 + k * 1024); } while (0)
; #define PG8_WAIT_V(n) asm volatile("s_waitcnt vmcnt(" #n ")" ::: "memory")
; #define PG8_WAIT_L(n) asm volatile("s_waitcnt lgkmcnt(" #n ")" ::: "memory")
; #define PG8_BAR __builtin_amdgcn_s_barrier()
; #define PG8_SCHED __builtin_amdgcn_sched_barrier(0)
; template <class Epi, class Sched, bool ALIGN_EPI = false, bool SP2 = false, bool I8 = false>
; __device__ __forceinline__ void gemm_phase(PG8_LAS unsigned char* lds, const Gemm g, const Sched& S, const Epi& E) {
;     ...
;             PG8_WAIT_V(8); PG8_WAIT_L(0); PG8_BAR; PG8_MMA(0, 0, At, B0); PG8_MMA(0, 1, At, B1); PG8_BAR; PG8_SCHED;
;             PG8_LDA(At, 1, 1); PG8_STAGE(PG8_SB(1, 0), b3, voffB); PG8_STAGE(PG8_SB(1, 1), b3 + hstep, voffB); PG8_STAGE(PG8_SA(1, 0), a3, voffA);
	s_setprio 1
	s_waitcnt lgkmcnt(0)
	v_mfma_f32_16x16x32_bf16 v[140:143], v[124:127], v[164:167], v[140:143]
	v_mfma_f32_16x16x32_bf16 v[140:143], v[128:131], v[168:171], v[140:143]
	v_mfma_f32_16x16x32_bf16 v[112:115], v[128:131], v[176:179], v[112:115]
	v_mfma_f32_16x16x32_bf16 v[112:115], v[124:127], v[172:175], v[112:115]
	v_mfma_f32_16x16x32_bf16 v[96:99], v[124:127], v[180:183], v[96:99]
	v_mfma_f32_16x16x32_bf16 v[96:99], v[128:131], v[184:187], v[96:99]
	v_mfma_f32_16x16x32_bf16 v[80:83], v[128:131], v[214:217], v[80:83]
	v_mfma_f32_16x16x32_bf16 v[80:83], v[124:127], v[188:191], v[80:83]
	v_mfma_f32_16x16x32_bf16 v[76:79], v[132:135], v[188:191], v[76:79]
	v_mfma_f32_16x16x32_bf16 v[76:79], v[144:147], v[214:217], v[76:79]
	v_mfma_f32_16x16x32_bf16 v[92:95], v[144:147], v[184:187], v[92:95]
	v_mfma_f32_16x16x32_bf16 v[92:95], v[132:135], v[180:183], v[92:95]
	v_mfma_f32_16x16x32_bf16 v[108:111], v[132:135], v[172:175], v[108:111]
	v_mfma_f32_16x16x32_bf16 v[108:111], v[144:147], v[176:179], v[108:111]
	v_mfma_f32_16x16x32_bf16 v[136:139], v[144:147], v[168:171], v[136:139]
	v_mfma_f32_16x16x32_bf16 v[136:139], v[132:135], v[164:167], v[136:139]
	v_mfma_f32_16x16x32_bf16 v[120:123], v[148:151], v[164:167], v[120:123]
	v_mfma_f32_16x16x32_bf16 v[120:123], v[152:155], v[168:171], v[120:123]
	v_mfma_f32_16x16x32_bf16 v[104:107], v[152:155], v[176:179], v[104:107]
	v_mfma_f32_16x16x32_bf16 v[104:107], v[148:151], v[172:175], v[104:107]
	v_mfma_f32_16x16x32_bf16 v[88:91], v[148:151], v[180:183], v[88:91]
	v_mfma_f32_16x16x32_bf16 v[88:91], v[152:155], v[184:187], v[88:91]
	v_mfma_f32_16x16x32_bf16 v[72:75], v[152:155], v[214:217], v[72:75]
	v_mfma_f32_16x16x32_bf16 v[72:75], v[148:151], v[188:191], v[72:75]
	v_mfma_f32_16x16x32_bf16 v[68:71], v[156:159], v[188:191], v[68:71]
	v_mfma_f32_16x16x32_bf16 v[68:71], v[160:163], v[214:217], v[68:71]
	v_mfma_f32_16x16x32_bf16 v[84:87], v[160:163], v[184:187], v[84:87]
	v_mfma_f32_16x16x32_bf16 v[84:87], v[156:159], v[180:183], v[84:87]
	v_mfma_f32_16x16x32_bf16 v[100:103], v[156:159], v[172:175], v[100:103]
	v_mfma_f32_16x16x32_bf16 v[100:103], v[160:163], v[176:179], v[100:103]
	v_mfma_f32_16x16x32_bf16 v[116:119], v[160:163], v[168:171], v[116:119]
	v_mfma_f32_16x16x32_bf16 v[116:119], v[156:159], v[164:167], v[116:119]
	s_setprio 0
	s_barrier
	s_add_i32 s22, s56, s41
	v_lshl_add_u64 v[218:219], v[218:219], 0, s[84:85]
	s_mov_b32 m0, s22
	ds_read_b128 v[164:167], v242 offset:49152
	ds_read_b128 v[168:171], v242 offset:50176
	ds_read_b128 v[172:175], v242 offset:51200
	ds_read_b128 v[176:179], v242 offset:52224
	ds_read_b128 v[180:183], v242 offset:53248
	ds_read_b128 v[184:187], v242 offset:54272
	ds_read_b128 v[188:191], v242 offset:55296
	ds_read_b128 v[214:217], v242 offset:56320
	global_load_lds_dwordx4 v[218:219], off
	s_add_i32 m0, s22, 0x2000
	s_add_u32 s22, s26, 0x2b0080
	v_lshl_add_u64 v[218:219], v[220:221], 0, s[84:85]
	s_addc_u32 s23, s27, 0
	s_add_i32 s26, s57, s41
	global_load_lds_dwordx4 v[218:219], off
	v_lshl_add_u64 v[218:219], s[22:23], 0, v[2:3]
	s_mov_b32 m0, s26
	s_nop 0
	global_load_lds_dwordx4 v[218:219], off
	v_lshl_add_u64 v[218:219], s[22:23], 0, v[204:205]
	s_add_i32 m0, s26, 0x2000
	s_nop 0
	global_load_lds_dwordx4 v[218:219], off
	s_cmpk_eq_i32 s55, 0xa8
	s_cbranch_scc0 .Ldefer_1700_body
	v_lshl_add_u64 v[218:219], v[222:223], 0, s[84:85]
	s_mov_b32 m0, s46
	s_nop 0
	global_load_lds_dwordx4 v[218:219], off
	v_lshl_add_u64 v[218:219], v[224:225], 0, s[84:85]
	s_mov_b32 m0, s47
	s_nop 0
	global_load_lds_dwordx4 v[218:219], off

; #define PG8_STAGE(bufoff, gbase, voff) do { _Pragma("unroll") for (int _i = 0; _i < 2; ++_i) \
;         __builtin_amdgcn_global_load_lds((const unsigned*)((const char*)(gbase) + (voff)[_i]), (PG8_LAS unsigned*)(lds + (bufoff) + ldsw + _i * 8192), 16, 0, 0); } while (0)
; #define PG8_LDA(dst, b, h) do { _Pragma("unroll") for (int m = 0; m < 4; ++m) _Pragma("unroll") for (int k = 0; k < 2; ++k) dst[m][k] = *(const PG8_LAS bf16x8*)(lds + PG8_SA(b, h) + aoff + m * 2048 + k * 1024); } while (0)
; #define PG8_LDB(dst, b, h) do { _Pragma("unroll") for (int n = 0; n < 2; ++n) _Pragma("unroll") for (int k = 0; k < 2; ++k) dst[n][k] = *(const PG8_LAS bf16x8*)(lds + PG8_SB(b, h) + boff + n * 2048 + k * 1024); } while (0)
; #define PG8_WAIT_V(n) asm volatile("s_waitcnt vmcnt(" #n ")" ::: "memory")
; #define PG8_WAIT_L(n) asm volatile("s_waitcnt lgkmcnt(" #n ")" ::: "memory")
; #define PG8_BAR __builtin_amdgcn_s_barrier()
; #define PG8_SCHED __builtin_amdgcn_sched_barrier(0)
; template <class Epi, class Sched, bool ALIGN_EPI = false, bool SP2 = false, bool I8 = false>
; __device__ __forceinline__ void gemm_phase(PG8_LAS unsigned char* lds, const Gemm g, const Sched& S, const Epi& E) {
;     ...
;     for (;;) {
;         const bool has_next = S.next(ui + 1, nxt);
;         const char* nA = has_next ? (const char*)g.A + (size_t)nxt.pm * tstep : cA; const char* nB = has_next ? (const char*)g.Bt + (size_t)nxt.pn * tstep : cB;
;         for (int t = 0; t < nt; t += 2) {
;             const bool last = (t == nt - 2);
;             const char* a1 = cA + (size_t)(t + 1) * kstep;
;             const char* a2 = last ? nA : cA + (size_t)(t + 2) * kstep; const char* b2 = last ? nB : cB + (size_t)(t + 2) * kstep;
;             const char* a3 = a2 + kstep; const char* b3 = b2 + kstep;
;             if (last && has_next) S.a_ready(nxt);
;             if constexpr (SP2) {
;             PG8_LDB(B0, 0, 0); PG8_LDB(B1, 0, 1); PG8_SCHED; PG8_LDA(At, 0, 0); PG8_STAGE(PG8_SA(1, 1), a1 + hstep, voffA);
;             PG8_WAIT_V(8); PG8_WAIT_L(0); PG8_BAR; PG8_MMA(0, 0, At, B0); PG8_MMA(0, 1, At, B1); PG8_BAR; PG8_SCHED;
;             PG8_LDA(At, 0, 1); PG8_STAGE(PG8_SB(0, 0), b2, voffB); PG8_STAGE(PG8_SB(0, 1), b2 + hstep, voffB); PG8_STAGE(PG8_SA(0, 0), a2, voffA);
.LBB0_1842:
	s_ashr_i32 s45, s44, 31
	s_lshl_b64 s[34:35], s[44:45], 20
	s_add_u32 s50, s47, s34
	s_addc_u32 s51, s52, s35
	s_and_b64 s[34:35], s[8:9], exec
	s_cselect_b32 s11, s51, s55
	s_cselect_b32 s13, s50, s54
	s_ashr_i32 s49, s48, 31
	s_lshl_b64 s[34:35], s[48:49], 20
	s_add_u32 s56, s53, s34
	s_addc_u32 s57, s64, s35
	s_and_b64 s[34:35], s[8:9], exec
	s_cselect_b32 s34, s57, s59
	s_cselect_b32 s35, s56, s58
	s_add_u32 s54, s54, 0x80080
	s_addc_u32 s55, s55, 0
	s_add_u32 s45, s58, 0x100
	s_addc_u32 s49, s59, 0
	s_mov_b32 s86, -2
	s_waitcnt lgkmcnt(0)
	s_add_u32 s58, s54, 0xfff80080
	s_addc_u32 s59, s55, -1
	s_add_i32 s87, 0, 0x10000
	s_cmp_eq_u32 s86, 28
	s_cselect_b32 s61, s11, s59
	s_cselect_b32 s60, s13, s58
	s_cselect_b32 s59, s34, s49
	s_cselect_b32 s58, s35, s45
	s_add_i32 vcc_lo, 0, 0x14000
	v_add_u32_e32 v40, s87, v217
	v_add_u32_e32 v160, vcc_lo, v217
	ds_read_b128 v[28:31], v40
	ds_read_b128 v[32:35], v40 offset:1024
	ds_read_b128 v[36:39], v40 offset:2048
	ds_read_b128 v[40:43], v40 offset:3072
	ds_read_b128 v[140:143], v160
	ds_read_b128 v[144:147], v160 offset:1024
	ds_read_b128 v[156:159], v160 offset:2048
	ds_read_b128 v[160:163], v160 offset:3072
	v_lshl_add_u64 v[190:191], s[54:55], 0, v[186:187]
	s_add_i32 m0, s65, 0xc000
	ds_read_b128 v[164:167], v219
	ds_read_b128 v[168:171], v219 offset:1024
	ds_read_b128 v[172:175], v219 offset:2048
	ds_read_b128 v[176:179], v219 offset:3072
	ds_read_b128 v[204:207], v219 offset:4096
	ds_read_b128 v[208:211], v219 offset:5120
	ds_read_b128 v[212:215], v219 offset:6144
	ds_read_b128 v[220:223], v219 offset:7168
	global_load_lds_dwordx4 v[190:191], off
	v_lshl_add_u64 v[190:191], s[54:55], 0, v[188:189]
	s_add_i32 m0, s65, 0xe000
	s_nop 0
	global_load_lds_dwordx4 v[190:191], off
	s_waitcnt vmcnt(8)
	s_waitcnt lgkmcnt(0)
	s_barrier
	s_setprio 1
	s_waitcnt lgkmcnt(0)
	v_mfma_i32_16x16x64_i8 v[152:155], v[28:31], v[164:167], 0
	v_mfma_i32_16x16x64_i8 v[152:155], v[32:35], v[168:171], v[152:155]
	v_mfma_i32_16x16x64_i8 v[128:131], v[32:35], v[176:179], 0
	v_mfma_i32_16x16x64_i8 v[128:131], v[28:31], v[172:175], v[128:131]
	v_mfma_i32_16x16x64_i8 v[112:115], v[28:31], v[204:207], 0
	v_mfma_i32_16x16x64_i8 v[112:115], v[32:35], v[208:211], v[112:115]
	v_mfma_i32_16x16x64_i8 v[96:99], v[32:35], v[220:223], 0
	v_mfma_i32_16x16x64_i8 v[96:99], v[28:31], v[212:215], v[96:99]
	v_mfma_i32_16x16x64_i8 v[92:95], v[36:39], v[212:215], 0
	v_mfma_i32_16x16x64_i8 v[92:95], v[40:43], v[220:223], v[92:95]
	v_mfma_i32_16x16x64_i8 v[108:111], v[40:43], v[208:211], 0
	v_mfma_i32_16x16x64_i8 v[108:111], v[36:39], v[204:207], v[108:111]
	v_mfma_i32_16x16x64_i8 v[124:127], v[36:39], v[172:175], 0
	v_mfma_i32_16x16x64_i8 v[124:127], v[40:43], v[176:179], v[124:127]
	v_mfma_i32_16x16x64_i8 v[148:151], v[40:43], v[168:171], 0
	v_mfma_i32_16x16x64_i8 v[148:151], v[36:39], v[164:167], v[148:151]
	v_mfma_i32_16x16x64_i8 v[136:139], v[140:143], v[164:167], 0
	v_mfma_i32_16x16x64_i8 v[136:139], v[144:147], v[168:171], v[136:139]
	v_mfma_i32_16x16x64_i8 v[120:123], v[144:147], v[176:179], 0
	v_mfma_i32_16x16x64_i8 v[120:123], v[140:143], v[172:175], v[120:123]
	v_mfma_i32_16x16x64_i8 v[104:107], v[140:143], v[204:207], 0
	v_mfma_i32_16x16x64_i8 v[104:107], v[144:147], v[208:211], v[104:107]
	v_mfma_i32_16x16x64_i8 v[88:91], v[144:147], v[220:223], 0
	v_mfma_i32_16x16x64_i8 v[88:91], v[140:143], v[212:215], v[88:91]
	v_mfma_i32_16x16x64_i8 v[84:87], v[156:159], v[212:215], 0
	v_mfma_i32_16x16x64_i8 v[84:87], v[160:163], v[220:223], v[84:87]
	v_mfma_i32_16x16x64_i8 v[100:103], v[160:163], v[208:211], 0
	v_mfma_i32_16x16x64_i8 v[100:103], v[156:159], v[204:207], v[100:103]
	v_mfma_i32_16x16x64_i8 v[116:119], v[156:159], v[172:175], 0
	v_mfma_i32_16x16x64_i8 v[116:119], v[160:163], v[176:179], v[116:119]
	v_mfma_i32_16x16x64_i8 v[132:135], v[160:163], v[168:171], 0
	v_mfma_i32_16x16x64_i8 v[132:135], v[156:159], v[164:167], v[132:135]
	s_setprio 0
	s_barrier
	s_add_i32 s87, s87, s46
	v_lshl_add_u64 v[190:191], s[58:59], 0, v[2:3]
	s_mov_b32 m0, s87
	ds_read_b128 v[164:167], v219 offset:16384
	ds_read_b128 v[168:171], v219 offset:17408
	ds_read_b128 v[172:175], v219 offset:18432
	ds_read_b128 v[176:179], v219 offset:19456
	ds_read_b128 v[204:207], v219 offset:20480
	ds_read_b128 v[208:211], v219 offset:21504
	ds_read_b128 v[212:215], v219 offset:22528
	ds_read_b128 v[220:223], v219 offset:23552
	global_load_lds_dwordx4 v[190:191], off
	s_add_i32 m0, s87, 0x2000
	s_add_u32 s96, s58, 0x80000
	v_lshl_add_u64 v[224:225], s[58:59], 0, v[184:185]
	s_addc_u32 s97, s59, 0
	s_add_i32 s87, vcc_lo, s46
	global_load_lds_dwordx4 v[224:225], off
	v_lshl_add_u64 v[226:227], s[96:97], 0, v[2:3]
	s_mov_b32 m0, s87
	v_lshl_add_u64 v[228:229], s[60:61], 0, v[182:183]
	global_load_lds_dwordx4 v[226:227], off
	v_lshl_add_u64 v[226:227], s[96:97], 0, v[184:185]
	s_add_i32 m0, s87, 0x2000
	s_nop 0
	global_load_lds_dwordx4 v[226:227], off
	v_lshl_add_u64 v[226:227], s[60:61], 0, v[180:181]
	s_waitcnt vmcnt(6)
	s_waitcnt lgkmcnt(0)
	s_barrier
; #define PG8_STAGE(bufoff, gbase, voff) do { _Pragma("unroll") for (int _i = 0; _i < 2; ++_i) \
;         __builtin_amdgcn_global_load_lds((const unsigned*)((const char*)(gbase) + (voff)[_i]), (PG8_LAS unsigned*)(lds + (bufoff) + ldsw + _i * 8192), 16, 0, 0); } while (0)
; #define PG8_LDA(dst, b, h) do { _Pragma("unroll") for (int m = 0; m < 4; ++m) _Pragma("unroll") for (int k = 0; k < 2; ++k) dst[m][k] = *(const PG8_LAS bf16x8*)(lds + PG8_SA(b, h) + aoff + m * 2048 + k * 1024); } while (0)
; #define PG8_LDB(dst, b, h) do { _Pragma("unroll") for (int n = 0; n < 2; ++n) _Pragma("unroll") for (int k = 0; k < 2; ++k) dst[n][k] = *(const PG8_LAS bf16x8*)(lds + PG8_SB(b, h) + boff + n * 2048 + k * 1024); } while (0)
; #define PG8_WAIT_V(n) asm volatile("s_waitcnt vmcnt(" #n ")" ::: "memory")
; #define PG8_WAIT_L(n) asm volatile("s_waitcnt lgkmcnt(" #n ")" ::: "memory")
; #define PG8_BAR __builtin_amdgcn_s_barrier()
; #define PG8_SCHED __builtin_amdgcn_sched_barrier(0)
; template <class Epi, class Sched, bool ALIGN_EPI = false, bool SP2 = false, bool I8 = false>
; __device__ __forceinline__ void gemm_phase(PG8_LAS unsigned char* lds, const Gemm g, const Sched& S, const Epi& E) {
;     ...
;             PG8_WAIT_V(8); PG8_WAIT_L(0); PG8_BAR; PG8_MMA(1, 0, At, B0); PG8_MMA(1, 1, At, B1); PG8_BAR; PG8_SCHED;
;             PG8_LDB(B0, 1, 0); PG8_LDB(B1, 1, 1); PG8_SCHED; PG8_LDA(At, 1, 0); PG8_STAGE(PG8_SA(0, 1), a2 + hstep, voffA);
;             PG8_WAIT_V(8); PG8_WAIT_L(0); PG8_BAR; PG8_MMA(0, 0, At, B0); PG8_MMA(0, 1, At, B1); PG8_BAR; PG8_SCHED;
;             PG8_LDA(At, 1, 1); PG8_STAGE(PG8_SB(1, 0), b3, voffB); PG8_STAGE(PG8_SB(1, 1), b3 + hstep, voffB); PG8_STAGE(PG8_SA(1, 0), a3, voffA);
	s_setprio 1
	s_waitcnt lgkmcnt(0)
	v_mfma_i32_16x16x64_i8 v[80:83], v[28:31], v[164:167], 0
	v_mfma_i32_16x16x64_i8 v[80:83], v[32:35], v[168:171], v[80:83]
	v_mfma_i32_16x16x64_i8 v[64:67], v[32:35], v[176:179], 0
	v_mfma_i32_16x16x64_i8 v[64:67], v[28:31], v[172:175], v[64:67]
	v_mfma_i32_16x16x64_i8 v[48:51], v[28:31], v[204:207], 0
	v_mfma_i32_16x16x64_i8 v[48:51], v[32:35], v[208:211], v[48:51]
	v_mfma_i32_16x16x64_i8 v[16:19], v[32:35], v[220:223], 0
	v_mfma_i32_16x16x64_i8 v[16:19], v[28:31], v[212:215], v[16:19]
	v_mfma_i32_16x16x64_i8 v[12:15], v[36:39], v[212:215], 0
	v_mfma_i32_16x16x64_i8 v[12:15], v[40:43], v[220:223], v[12:15]
	v_mfma_i32_16x16x64_i8 v[44:47], v[40:43], v[208:211], 0
	v_mfma_i32_16x16x64_i8 v[44:47], v[36:39], v[204:207], v[44:47]
	v_mfma_i32_16x16x64_i8 v[60:63], v[36:39], v[172:175], 0
	v_mfma_i32_16x16x64_i8 v[60:63], v[40:43], v[176:179], v[60:63]
	v_mfma_i32_16x16x64_i8 v[76:79], v[40:43], v[168:171], 0
	v_mfma_i32_16x16x64_i8 v[76:79], v[36:39], v[164:167], v[76:79]
	v_mfma_i32_16x16x64_i8 v[28:31], v[140:143], v[164:167], 0
	v_mfma_i32_16x16x64_i8 v[28:31], v[144:147], v[168:171], v[28:31]
	v_mfma_i32_16x16x64_i8 v[36:39], v[144:147], v[176:179], 0
	v_mfma_i32_16x16x64_i8 v[36:39], v[140:143], v[172:175], v[36:39]
	v_mfma_i32_16x16x64_i8 v[24:27], v[140:143], v[204:207], 0
	v_mfma_i32_16x16x64_i8 v[24:27], v[144:147], v[208:211], v[24:27]
	v_mfma_i32_16x16x64_i8 v[8:11], v[144:147], v[220:223], 0
	v_mfma_i32_16x16x64_i8 v[8:11], v[140:143], v[212:215], v[8:11]
	v_mfma_i32_16x16x64_i8 v[4:7], v[156:159], v[212:215], 0
	v_mfma_i32_16x16x64_i8 v[4:7], v[160:163], v[220:223], v[4:7]
	v_mfma_i32_16x16x64_i8 v[20:23], v[160:163], v[208:211], 0
	v_mfma_i32_16x16x64_i8 v[20:23], v[156:159], v[204:207], v[20:23]
	v_mfma_i32_16x16x64_i8 v[40:43], v[156:159], v[172:175], 0
	v_mfma_i32_16x16x64_i8 v[40:43], v[160:163], v[176:179], v[40:43]
	v_mfma_i32_16x16x64_i8 v[32:35], v[160:163], v[168:171], 0
	v_mfma_i32_16x16x64_i8 v[32:35], v[156:159], v[164:167], v[32:35]
	s_setprio 0
	s_barrier
	s_add_i32 s87, 0, 0x18000
	s_add_i32 s96, 0, 0x1c000
	v_add_u32_e32 v72, s87, v217
	v_add_u32_e32 v160, s96, v217
	ds_read_b128 v[52:55], v72
	ds_read_b128 v[56:59], v72 offset:1024
	ds_read_b128 v[68:71], v72 offset:2048
	ds_read_b128 v[72:75], v72 offset:3072
	ds_read_b128 v[140:143], v160
	ds_read_b128 v[144:147], v160 offset:1024
	ds_read_b128 v[156:159], v160 offset:2048
	ds_read_b128 v[160:163], v160 offset:3072
	s_add_u32 s60, s60, 0x80000
	s_addc_u32 s61, s61, 0
	s_mov_b32 m0, s72
	v_lshl_add_u64 v[240:241], s[60:61], 0, v[180:181]
	ds_read_b128 v[164:167], v219 offset:32768
	ds_read_b128 v[168:171], v219 offset:33792
	ds_read_b128 v[172:175], v219 offset:34816
	ds_read_b128 v[176:179], v219 offset:35840
	ds_read_b128 v[204:207], v219 offset:36864
	ds_read_b128 v[208:211], v219 offset:37888
	ds_read_b128 v[212:215], v219 offset:38912
	ds_read_b128 v[220:223], v219 offset:39936
	s_mov_b32 m0, s65
	s_nop 0
	global_load_lds_dwordx4 v[226:227], off
	s_mov_b32 m0, s67
	s_nop 0
	global_load_lds_dwordx4 v[228:229], off
	s_mov_b32 m0, s72
	s_nop 0
	global_load_lds_dwordx4 v[240:241], off
	v_lshl_add_u64 v[240:241], s[60:61], 0, v[182:183]
	s_mov_b32 m0, s73
	s_nop 0
	global_load_lds_dwordx4 v[240:241], off
	s_waitcnt vmcnt(8)
	s_waitcnt lgkmcnt(0)
	s_barrier
	s_setprio 1
	s_waitcnt lgkmcnt(0)
	v_mfma_i32_16x16x64_i8 v[152:155], v[52:55], v[164:167], v[152:155]
	v_mfma_i32_16x16x64_i8 v[152:155], v[56:59], v[168:171], v[152:155]
	v_mfma_i32_16x16x64_i8 v[128:131], v[56:59], v[176:179], v[128:131]
	v_mfma_i32_16x16x64_i8 v[128:131], v[52:55], v[172:175], v[128:131]
	v_mfma_i32_16x16x64_i8 v[112:115], v[52:55], v[204:207], v[112:115]
	v_mfma_i32_16x16x64_i8 v[112:115], v[56:59], v[208:211], v[112:115]
	v_mfma_i32_16x16x64_i8 v[96:99], v[56:59], v[220:223], v[96:99]
	v_mfma_i32_16x16x64_i8 v[96:99], v[52:55], v[212:215], v[96:99]
	v_mfma_i32_16x16x64_i8 v[92:95], v[68:71], v[212:215], v[92:95]
	v_mfma_i32_16x16x64_i8 v[92:95], v[72:75], v[220:223], v[92:95]
	v_mfma_i32_16x16x64_i8 v[108:111], v[72:75], v[208:211], v[108:111]
	v_mfma_i32_16x16x64_i8 v[108:111], v[68:71], v[204:207], v[108:111]
	v_mfma_i32_16x16x64_i8 v[124:127], v[68:71], v[172:175], v[124:127]
	v_mfma_i32_16x16x64_i8 v[124:127], v[72:75], v[176:179], v[124:127]
	v_mfma_i32_16x16x64_i8 v[148:151], v[72:75], v[168:171], v[148:151]
	v_mfma_i32_16x16x64_i8 v[148:151], v[68:71], v[164:167], v[148:151]
	v_mfma_i32_16x16x64_i8 v[136:139], v[140:143], v[164:167], v[136:139]
	v_mfma_i32_16x16x64_i8 v[136:139], v[144:147], v[168:171], v[136:139]
	v_mfma_i32_16x16x64_i8 v[120:123], v[144:147], v[176:179], v[120:123]
	v_mfma_i32_16x16x64_i8 v[120:123], v[140:143], v[172:175], v[120:123]
	v_mfma_i32_16x16x64_i8 v[104:107], v[140:143], v[204:207], v[104:107]
	v_mfma_i32_16x16x64_i8 v[104:107], v[144:147], v[208:211], v[104:107]
	v_mfma_i32_16x16x64_i8 v[88:91], v[144:147], v[220:223], v[88:91]
	v_mfma_i32_16x16x64_i8 v[88:91], v[140:143], v[212:215], v[88:91]
	v_mfma_i32_16x16x64_i8 v[84:87], v[156:159], v[212:215], v[84:87]
	v_mfma_i32_16x16x64_i8 v[84:87], v[160:163], v[220:223], v[84:87]
	v_mfma_i32_16x16x64_i8 v[100:103], v[160:163], v[208:211], v[100:103]
	v_mfma_i32_16x16x64_i8 v[100:103], v[156:159], v[204:207], v[100:103]
	v_mfma_i32_16x16x64_i8 v[116:119], v[156:159], v[172:175], v[116:119]
	v_mfma_i32_16x16x64_i8 v[116:119], v[160:163], v[176:179], v[116:119]
	v_mfma_i32_16x16x64_i8 v[132:135], v[160:163], v[168:171], v[132:135]
	v_mfma_i32_16x16x64_i8 v[132:135], v[156:159], v[164:167], v[132:135]
	s_setprio 0
	s_barrier
	s_add_i32 s60, s87, s46
	v_lshl_add_u64 v[190:191], v[190:191], 0, s[84:85]
	s_mov_b32 m0, s60
	ds_read_b128 v[164:167], v219 offset:49152
	ds_read_b128 v[168:171], v219 offset:50176
	ds_read_b128 v[172:175], v219 offset:51200
	ds_read_b128 v[176:179], v219 offset:52224
	ds_read_b128 v[204:207], v219 offset:53248
	ds_read_b128 v[208:211], v219 offset:54272
	ds_read_b128 v[212:215], v219 offset:55296
	ds_read_b128 v[220:223], v219 offset:56320
	global_load_lds_dwordx4 v[190:191], off
	s_add_i32 m0, s60, 0x2000
	s_add_u32 s58, s58, 0x80080
	v_lshl_add_u64 v[190:191], v[224:225], 0, s[84:85]
	s_addc_u32 s59, s59, 0
	s_add_i32 s60, s96, s46
	global_load_lds_dwordx4 v[190:191], off
	v_lshl_add_u64 v[190:191], s[58:59], 0, v[2:3]
	s_mov_b32 m0, s60
	s_nop 0
	global_load_lds_dwordx4 v[190:191], off
	v_lshl_add_u64 v[190:191], s[58:59], 0, v[184:185]
	s_add_i32 m0, s60, 0x2000
	s_nop 0
	global_load_lds_dwordx4 v[190:191], off
	s_cmp_eq_u32 s86, 28
	s_cbranch_scc0 .Ldefer_1843_peel
	v_lshl_add_u64 v[190:191], v[226:227], 0, s[84:85]
	s_mov_b32 m0, s28
	s_nop 0
	global_load_lds_dwordx4 v[190:191], off
	v_lshl_add_u64 v[190:191], v[228:229], 0, s[84:85]
	s_mov_b32 m0, s77
	s_nop 0
	global_load_lds_dwordx4 v[190:191], off

; #define PG8_STAGE(bufoff, gbase, voff) do { _Pragma("unroll") for (int _i = 0; _i < 2; ++_i) \
;         __builtin_amdgcn_global_load_lds((const unsigned*)((const char*)(gbase) + (voff)[_i]), (PG8_LAS unsigned*)(lds + (bufoff) + ldsw + _i * 8192), 16, 0, 0); } while (0)
; #define PG8_LDA(dst, b, h) do { _Pragma("unroll") for (int m = 0; m < 4; ++m) _Pragma("unroll") for (int k = 0; k < 2; ++k) dst[m][k] = *(const PG8_LAS bf16x8*)(lds + PG8_SA(b, h) + aoff + m * 2048 + k * 1024); } while (0)
; #define PG8_LDB(dst, b, h) do { _Pragma("unroll") for (int n = 0; n < 2; ++n) _Pragma("unroll") for (int k = 0; k < 2; ++k) dst[n][k] = *(const PG8_LAS bf16x8*)(lds + PG8_SB(b, h) + boff + n * 2048 + k * 1024); } while (0)
; #define PG8_WAIT_V(n) asm volatile("s_waitcnt vmcnt(" #n ")" ::: "memory")
; #define PG8_WAIT_L(n) asm volatile("s_waitcnt lgkmcnt(" #n ")" ::: "memory")
; #define PG8_BAR __builtin_amdgcn_s_barrier()
; #define PG8_SCHED __builtin_amdgcn_sched_barrier(0)
; template <class Epi, class Sched, bool ALIGN_EPI = false, bool SP2 = false, bool I8 = false>
; __device__ __forceinline__ void gemm_phase(PG8_LAS unsigned char* lds, const Gemm g, const Sched& S, const Epi& E) {
;     ...
;         for (int t = 0; t < nt; t += 2) {
;             const bool last = (t == nt - 2);
;             const char* a1 = cA + (size_t)(t + 1) * kstep;
;             const char* a2 = last ? nA : cA + (size_t)(t + 2) * kstep; const char* b2 = last ? nB : cB + (size_t)(t + 2) * kstep;
;             const char* a3 = a2 + kstep; const char* b3 = b2 + kstep;
;             if (last && has_next) S.a_ready(nxt);
;             if constexpr (SP2) {
;             PG8_LDB(B0, 0, 0); PG8_LDB(B1, 0, 1); PG8_SCHED; PG8_LDA(At, 0, 0); PG8_STAGE(PG8_SA(1, 1), a1 + hstep, voffA);
;             PG8_WAIT_V(8); PG8_WAIT_L(0); PG8_BAR; PG8_MMA(0, 0, At, B0); PG8_MMA(0, 1, At, B1); PG8_BAR; PG8_SCHED;
;             PG8_LDA(At, 0, 1); PG8_STAGE(PG8_SB(0, 0), b2, voffB); PG8_STAGE(PG8_SB(0, 1), b2 + hstep, voffB); PG8_STAGE(PG8_SA(0, 0), a2, voffA);
.LBB0_1843:
	s_add_u32 s58, s54, 0xfff80080
	s_addc_u32 s59, s55, -1
	s_add_i32 s87, 0, 0x10000
	s_cmp_eq_u32 s86, 28
	s_cselect_b32 s61, s11, s59
	s_cselect_b32 s60, s13, s58
	s_cselect_b32 s59, s34, s49
	s_cselect_b32 s58, s35, s45
	s_add_i32 vcc_lo, 0, 0x14000
	v_add_u32_e32 v40, s87, v217
	v_add_u32_e32 v160, vcc_lo, v217
	ds_read_b128 v[28:31], v40
	ds_read_b128 v[32:35], v40 offset:1024
	ds_read_b128 v[36:39], v40 offset:2048
	ds_read_b128 v[40:43], v40 offset:3072
	ds_read_b128 v[140:143], v160
	ds_read_b128 v[144:147], v160 offset:1024
	ds_read_b128 v[156:159], v160 offset:2048
	ds_read_b128 v[160:163], v160 offset:3072
	ds_read_b128 v[164:167], v219
	ds_read_b128 v[168:171], v219 offset:1024
	ds_read_b128 v[172:175], v219 offset:2048
	ds_read_b128 v[176:179], v219 offset:3072
	ds_read_b128 v[204:207], v219 offset:4096
	ds_read_b128 v[208:211], v219 offset:5120
	ds_read_b128 v[212:215], v219 offset:6144
	ds_read_b128 v[220:223], v219 offset:7168
	v_lshl_add_u64 v[190:191], v[226:227], 0, s[84:85]
	s_mov_b32 m0, s28
	s_nop 0
	global_load_lds_dwordx4 v[190:191], off
	v_lshl_add_u64 v[190:191], v[228:229], 0, s[84:85]
	s_mov_b32 m0, s77
	s_nop 0
	global_load_lds_dwordx4 v[190:191], off
	v_lshl_add_u64 v[190:191], s[54:55], 0, v[186:187]
	s_add_i32 m0, s65, 0xc000
	s_nop 0
	global_load_lds_dwordx4 v[190:191], off
	v_lshl_add_u64 v[190:191], s[54:55], 0, v[188:189]
	s_add_i32 m0, s65, 0xe000
	s_nop 0
	global_load_lds_dwordx4 v[190:191], off
	s_waitcnt vmcnt(8)
	s_waitcnt lgkmcnt(0)
	s_barrier
	s_setprio 1
	s_waitcnt lgkmcnt(0)
	v_mfma_i32_16x16x64_i8 v[152:155], v[28:31], v[164:167], v[152:155]
	v_mfma_i32_16x16x64_i8 v[152:155], v[32:35], v[168:171], v[152:155]
	v_mfma_i32_16x16x64_i8 v[128:131], v[32:35], v[176:179], v[128:131]
	v_mfma_i32_16x16x64_i8 v[128:131], v[28:31], v[172:175], v[128:131]
	v_mfma_i32_16x16x64_i8 v[112:115], v[28:31], v[204:207], v[112:115]
	v_mfma_i32_16x16x64_i8 v[112:115], v[32:35], v[208:211], v[112:115]
	v_mfma_i32_16x16x64_i8 v[96:99], v[32:35], v[220:223], v[96:99]
	v_mfma_i32_16x16x64_i8 v[96:99], v[28:31], v[212:215], v[96:99]
	v_mfma_i32_16x16x64_i8 v[92:95], v[36:39], v[212:215], v[92:95]
	v_mfma_i32_16x16x64_i8 v[92:95], v[40:43], v[220:223], v[92:95]
	v_mfma_i32_16x16x64_i8 v[108:111], v[40:43], v[208:211], v[108:111]
	v_mfma_i32_16x16x64_i8 v[108:111], v[36:39], v[204:207], v[108:111]
	v_mfma_i32_16x16x64_i8 v[124:127], v[36:39], v[172:175], v[124:127]
	v_mfma_i32_16x16x64_i8 v[124:127], v[40:43], v[176:179], v[124:127]
	v_mfma_i32_16x16x64_i8 v[148:151], v[40:43], v[168:171], v[148:151]
	v_mfma_i32_16x16x64_i8 v[148:151], v[36:39], v[164:167], v[148:151]
	v_mfma_i32_16x16x64_i8 v[136:139], v[140:143], v[164:167], v[136:139]
	v_mfma_i32_16x16x64_i8 v[136:139], v[144:147], v[168:171], v[136:139]
	v_mfma_i32_16x16x64_i8 v[120:123], v[144:147], v[176:179], v[120:123]
	v_mfma_i32_16x16x64_i8 v[120:123], v[140:143], v[172:175], v[120:123]
	v_mfma_i32_16x16x64_i8 v[104:107], v[140:143], v[204:207], v[104:107]
	v_mfma_i32_16x16x64_i8 v[104:107], v[144:147], v[208:211], v[104:107]
	v_mfma_i32_16x16x64_i8 v[88:91], v[144:147], v[220:223], v[88:91]
	v_mfma_i32_16x16x64_i8 v[88:91], v[140:143], v[212:215], v[88:91]
	v_mfma_i32_16x16x64_i8 v[84:87], v[156:159], v[212:215], v[84:87]
	v_mfma_i32_16x16x64_i8 v[84:87], v[160:163], v[220:223], v[84:87]
	v_mfma_i32_16x16x64_i8 v[100:103], v[160:163], v[208:211], v[100:103]
	v_mfma_i32_16x16x64_i8 v[100:103], v[156:159], v[204:207], v[100:103]
	v_mfma_i32_16x16x64_i8 v[116:119], v[156:159], v[172:175], v[116:119]
	v_mfma_i32_16x16x64_i8 v[116:119], v[160:163], v[176:179], v[116:119]
	v_mfma_i32_16x16x64_i8 v[132:135], v[160:163], v[168:171], v[132:135]
	v_mfma_i32_16x16x64_i8 v[132:135], v[156:159], v[164:167], v[132:135]
	s_setprio 0
	s_barrier
	s_add_i32 s87, s87, s46
	v_lshl_add_u64 v[190:191], s[58:59], 0, v[2:3]
	s_mov_b32 m0, s87
	ds_read_b128 v[164:167], v219 offset:16384
	ds_read_b128 v[168:171], v219 offset:17408
	ds_read_b128 v[172:175], v219 offset:18432
	ds_read_b128 v[176:179], v219 offset:19456
	ds_read_b128 v[204:207], v219 offset:20480
	ds_read_b128 v[208:211], v219 offset:21504
	ds_read_b128 v[212:215], v219 offset:22528
	ds_read_b128 v[220:223], v219 offset:23552
	global_load_lds_dwordx4 v[190:191], off
	s_add_i32 m0, s87, 0x2000
	s_add_u32 s96, s58, 0x80000
	v_lshl_add_u64 v[224:225], s[58:59], 0, v[184:185]
	s_addc_u32 s97, s59, 0
	s_add_i32 s87, vcc_lo, s46
	global_load_lds_dwordx4 v[224:225], off
	v_lshl_add_u64 v[226:227], s[96:97], 0, v[2:3]
	s_mov_b32 m0, s87
	v_lshl_add_u64 v[228:229], s[60:61], 0, v[182:183]
	global_load_lds_dwordx4 v[226:227], off
	v_lshl_add_u64 v[226:227], s[96:97], 0, v[184:185]
	s_add_i32 m0, s87, 0x2000
	s_nop 0
	global_load_lds_dwordx4 v[226:227], off
	v_lshl_add_u64 v[226:227], s[60:61], 0, v[180:181]
	s_waitcnt vmcnt(6)
	s_waitcnt lgkmcnt(0)
	s_barrier
; #define PG8_STAGE(bufoff, gbase, voff) do { _Pragma("unroll") for (int _i = 0; _i < 2; ++_i) \
;         __builtin_amdgcn_global_load_lds((const unsigned*)((const char*)(gbase) + (voff)[_i]), (PG8_LAS unsigned*)(lds + (bufoff) + ldsw + _i * 8192), 16, 0, 0); } while (0)
; #define PG8_LDA(dst, b, h) do { _Pragma("unroll") for (int m = 0; m < 4; ++m) _Pragma("unroll") for (int k = 0; k < 2; ++k) dst[m][k] = *(const PG8_LAS bf16x8*)(lds + PG8_SA(b, h) + aoff + m * 2048 + k * 1024); } while (0)
; #define PG8_LDB(dst, b, h) do { _Pragma("unroll") for (int n = 0; n < 2; ++n) _Pragma("unroll") for (int k = 0; k < 2; ++k) dst[n][k] = *(const PG8_LAS bf16x8*)(lds + PG8_SB(b, h) + boff + n * 2048 + k * 1024); } while (0)
; #define PG8_WAIT_V(n) asm volatile("s_waitcnt vmcnt(" #n ")" ::: "memory")
; #define PG8_WAIT_L(n) asm volatile("s_waitcnt lgkmcnt(" #n ")" ::: "memory")
; #define PG8_BAR __builtin_amdgcn_s_barrier()
; #define PG8_SCHED __builtin_amdgcn_sched_barrier(0)
; template <class Epi, class Sched, bool ALIGN_EPI = false, bool SP2 = false, bool I8 = false>
; __device__ __forceinline__ void gemm_phase(PG8_LAS unsigned char* lds, const Gemm g, const Sched& S, const Epi& E) {
;     ...
;             PG8_WAIT_V(8); PG8_WAIT_L(0); PG8_BAR; PG8_MMA(1, 0, At, B0); PG8_MMA(1, 1, At, B1); PG8_BAR; PG8_SCHED;
;             PG8_LDB(B0, 1, 0); PG8_LDB(B1, 1, 1); PG8_SCHED; PG8_LDA(At, 1, 0); PG8_STAGE(PG8_SA(0, 1), a2 + hstep, voffA);
;             PG8_WAIT_V(8); PG8_WAIT_L(0); PG8_BAR; PG8_MMA(0, 0, At, B0); PG8_MMA(0, 1, At, B1); PG8_BAR; PG8_SCHED;
;             PG8_LDA(At, 1, 1); PG8_STAGE(PG8_SB(1, 0), b3, voffB); PG8_STAGE(PG8_SB(1, 1), b3 + hstep, voffB); PG8_STAGE(PG8_SA(1, 0), a3, voffA);
	s_setprio 1
	s_waitcnt lgkmcnt(0)
	v_mfma_i32_16x16x64_i8 v[80:83], v[28:31], v[164:167], v[80:83]
	v_mfma_i32_16x16x64_i8 v[80:83], v[32:35], v[168:171], v[80:83]
	v_mfma_i32_16x16x64_i8 v[64:67], v[32:35], v[176:179], v[64:67]
	v_mfma_i32_16x16x64_i8 v[64:67], v[28:31], v[172:175], v[64:67]
	v_mfma_i32_16x16x64_i8 v[48:51], v[28:31], v[204:207], v[48:51]
	v_mfma_i32_16x16x64_i8 v[48:51], v[32:35], v[208:211], v[48:51]
	v_mfma_i32_16x16x64_i8 v[16:19], v[32:35], v[220:223], v[16:19]
	v_mfma_i32_16x16x64_i8 v[16:19], v[28:31], v[212:215], v[16:19]
	v_mfma_i32_16x16x64_i8 v[12:15], v[36:39], v[212:215], v[12:15]
	v_mfma_i32_16x16x64_i8 v[12:15], v[40:43], v[220:223], v[12:15]
	v_mfma_i32_16x16x64_i8 v[44:47], v[40:43], v[208:211], v[44:47]
	v_mfma_i32_16x16x64_i8 v[44:47], v[36:39], v[204:207], v[44:47]
	v_mfma_i32_16x16x64_i8 v[60:63], v[36:39], v[172:175], v[60:63]
	v_mfma_i32_16x16x64_i8 v[60:63], v[40:43], v[176:179], v[60:63]
	v_mfma_i32_16x16x64_i8 v[76:79], v[40:43], v[168:171], v[76:79]
	v_mfma_i32_16x16x64_i8 v[76:79], v[36:39], v[164:167], v[76:79]
	v_mfma_i32_16x16x64_i8 v[28:31], v[140:143], v[164:167], v[72:75]
	v_mfma_i32_16x16x64_i8 v[28:31], v[144:147], v[168:171], v[28:31]
	v_mfma_i32_16x16x64_i8 v[36:39], v[144:147], v[176:179], v[56:59]
	v_mfma_i32_16x16x64_i8 v[36:39], v[140:143], v[172:175], v[36:39]
	v_mfma_i32_16x16x64_i8 v[24:27], v[140:143], v[204:207], v[24:27]
	v_mfma_i32_16x16x64_i8 v[24:27], v[144:147], v[208:211], v[24:27]
	v_mfma_i32_16x16x64_i8 v[8:11], v[144:147], v[220:223], v[8:11]
	v_mfma_i32_16x16x64_i8 v[8:11], v[140:143], v[212:215], v[8:11]
	v_mfma_i32_16x16x64_i8 v[4:7], v[156:159], v[212:215], v[4:7]
	v_mfma_i32_16x16x64_i8 v[4:7], v[160:163], v[220:223], v[4:7]
	v_mfma_i32_16x16x64_i8 v[20:23], v[160:163], v[208:211], v[20:23]
	v_mfma_i32_16x16x64_i8 v[20:23], v[156:159], v[204:207], v[20:23]
	v_mfma_i32_16x16x64_i8 v[40:43], v[156:159], v[172:175], v[52:55]
	v_mfma_i32_16x16x64_i8 v[40:43], v[160:163], v[176:179], v[40:43]
	v_mfma_i32_16x16x64_i8 v[32:35], v[160:163], v[168:171], v[68:71]
	v_mfma_i32_16x16x64_i8 v[32:35], v[156:159], v[164:167], v[32:35]
	s_setprio 0
	s_barrier
	s_add_i32 s87, 0, 0x18000
	s_add_i32 s96, 0, 0x1c000
	v_add_u32_e32 v72, s87, v217
	v_add_u32_e32 v160, s96, v217
	ds_read_b128 v[52:55], v72
	ds_read_b128 v[56:59], v72 offset:1024
	ds_read_b128 v[68:71], v72 offset:2048
	ds_read_b128 v[72:75], v72 offset:3072
	ds_read_b128 v[140:143], v160
	ds_read_b128 v[144:147], v160 offset:1024
	ds_read_b128 v[156:159], v160 offset:2048
	ds_read_b128 v[160:163], v160 offset:3072
	s_add_u32 s60, s60, 0x80000
	s_addc_u32 s61, s61, 0
	s_mov_b32 m0, s72
	v_lshl_add_u64 v[240:241], s[60:61], 0, v[180:181]
	ds_read_b128 v[164:167], v219 offset:32768
	ds_read_b128 v[168:171], v219 offset:33792
	ds_read_b128 v[172:175], v219 offset:34816
	ds_read_b128 v[176:179], v219 offset:35840
	ds_read_b128 v[204:207], v219 offset:36864
	ds_read_b128 v[208:211], v219 offset:37888
	ds_read_b128 v[212:215], v219 offset:38912
	ds_read_b128 v[220:223], v219 offset:39936
	s_mov_b32 m0, s65
	s_nop 0
	global_load_lds_dwordx4 v[226:227], off
	s_mov_b32 m0, s67
	s_nop 0
	global_load_lds_dwordx4 v[228:229], off
	s_mov_b32 m0, s72
	s_nop 0
	global_load_lds_dwordx4 v[240:241], off
	v_lshl_add_u64 v[240:241], s[60:61], 0, v[182:183]
	s_mov_b32 m0, s73
	s_nop 0
	global_load_lds_dwordx4 v[240:241], off
	s_waitcnt vmcnt(8)
	s_waitcnt lgkmcnt(0)
	s_barrier
	s_setprio 1
	s_waitcnt lgkmcnt(0)
	v_mfma_i32_16x16x64_i8 v[152:155], v[52:55], v[164:167], v[152:155]
	v_mfma_i32_16x16x64_i8 v[152:155], v[56:59], v[168:171], v[152:155]
	v_mfma_i32_16x16x64_i8 v[128:131], v[56:59], v[176:179], v[128:131]
	v_mfma_i32_16x16x64_i8 v[128:131], v[52:55], v[172:175], v[128:131]
	v_mfma_i32_16x16x64_i8 v[112:115], v[52:55], v[204:207], v[112:115]
	v_mfma_i32_16x16x64_i8 v[112:115], v[56:59], v[208:211], v[112:115]
	v_mfma_i32_16x16x64_i8 v[96:99], v[56:59], v[220:223], v[96:99]
	v_mfma_i32_16x16x64_i8 v[96:99], v[52:55], v[212:215], v[96:99]
	v_mfma_i32_16x16x64_i8 v[92:95], v[68:71], v[212:215], v[92:95]
	v_mfma_i32_16x16x64_i8 v[92:95], v[72:75], v[220:223], v[92:95]
	v_mfma_i32_16x16x64_i8 v[108:111], v[72:75], v[208:211], v[108:111]
	v_mfma_i32_16x16x64_i8 v[108:111], v[68:71], v[204:207], v[108:111]
	v_mfma_i32_16x16x64_i8 v[124:127], v[68:71], v[172:175], v[124:127]
	v_mfma_i32_16x16x64_i8 v[124:127], v[72:75], v[176:179], v[124:127]
	v_mfma_i32_16x16x64_i8 v[148:151], v[72:75], v[168:171], v[148:151]
	v_mfma_i32_16x16x64_i8 v[148:151], v[68:71], v[164:167], v[148:151]
	v_mfma_i32_16x16x64_i8 v[136:139], v[140:143], v[164:167], v[136:139]
	v_mfma_i32_16x16x64_i8 v[136:139], v[144:147], v[168:171], v[136:139]
	v_mfma_i32_16x16x64_i8 v[120:123], v[144:147], v[176:179], v[120:123]
	v_mfma_i32_16x16x64_i8 v[120:123], v[140:143], v[172:175], v[120:123]
	v_mfma_i32_16x16x64_i8 v[104:107], v[140:143], v[204:207], v[104:107]
	v_mfma_i32_16x16x64_i8 v[104:107], v[144:147], v[208:211], v[104:107]
	v_mfma_i32_16x16x64_i8 v[88:91], v[144:147], v[220:223], v[88:91]
	v_mfma_i32_16x16x64_i8 v[88:91], v[140:143], v[212:215], v[88:91]
	v_mfma_i32_16x16x64_i8 v[84:87], v[156:159], v[212:215], v[84:87]
	v_mfma_i32_16x16x64_i8 v[84:87], v[160:163], v[220:223], v[84:87]
	v_mfma_i32_16x16x64_i8 v[100:103], v[160:163], v[208:211], v[100:103]
	v_mfma_i32_16x16x64_i8 v[100:103], v[156:159], v[204:207], v[100:103]
	v_mfma_i32_16x16x64_i8 v[116:119], v[156:159], v[172:175], v[116:119]
	v_mfma_i32_16x16x64_i8 v[116:119], v[160:163], v[176:179], v[116:119]
	v_mfma_i32_16x16x64_i8 v[132:135], v[160:163], v[168:171], v[132:135]
	v_mfma_i32_16x16x64_i8 v[132:135], v[156:159], v[164:167], v[132:135]
	s_setprio 0
	s_barrier
	s_add_i32 s60, s87, s46
	v_lshl_add_u64 v[190:191], v[190:191], 0, s[84:85]
	s_mov_b32 m0, s60
	ds_read_b128 v[164:167], v219 offset:49152
	ds_read_b128 v[168:171], v219 offset:50176
	ds_read_b128 v[172:175], v219 offset:51200
	ds_read_b128 v[176:179], v219 offset:52224
	ds_read_b128 v[204:207], v219 offset:53248
	ds_read_b128 v[208:211], v219 offset:54272
	ds_read_b128 v[212:215], v219 offset:55296
	ds_read_b128 v[220:223], v219 offset:56320
	global_load_lds_dwordx4 v[190:191], off
	s_add_i32 m0, s60, 0x2000
	s_add_u32 s58, s58, 0x80080
	v_lshl_add_u64 v[190:191], v[224:225], 0, s[84:85]
	s_addc_u32 s59, s59, 0
	s_add_i32 s60, s96, s46
	global_load_lds_dwordx4 v[190:191], off
	v_lshl_add_u64 v[190:191], s[58:59], 0, v[2:3]
	s_mov_b32 m0, s60
	s_nop 0
	global_load_lds_dwordx4 v[190:191], off
	v_lshl_add_u64 v[190:191], s[58:59], 0, v[184:185]
	s_add_i32 m0, s60, 0x2000
	s_nop 0
	global_load_lds_dwordx4 v[190:191], off
	s_cmp_eq_u32 s86, 28
	s_cbranch_scc0 .Ldefer_1843_body
	v_lshl_add_u64 v[190:191], v[226:227], 0, s[84:85]
	s_mov_b32 m0, s28
	s_nop 0
	global_load_lds_dwordx4 v[190:191], off
	v_lshl_add_u64 v[190:191], v[228:229], 0, s[84:85]
	s_mov_b32 m0, s77
	s_nop 0
	global_load_lds_dwordx4 v[190:191], off
